# v30 + GEMM K-loops: the two waits that close each load segment (vmcnt(8), lgkmcnt(0)) merged into one s_waitcnt
# baseline (speedup 1.0000x reference)
.LBB0_161:
	s_ashr_i32 s23, s22, 31
	s_lshl_b64 s[8:9], s[22:23], 20
	v_readlane_b32 s20, v254, 38
	v_readlane_b32 s21, v254, 39
	s_add_u32 s8, s20, s8
	s_addc_u32 s9, s21, s9
	s_and_b64 s[20:21], s[40:41], exec
	s_cselect_b32 s13, s9, s43
	s_cselect_b32 s20, s8, s42
	s_ashr_i32 s19, s18, 31
	s_lshl_b64 s[28:29], s[18:19], 20
	v_readlane_b32 s30, v254, 22
	v_readlane_b32 s31, v254, 23
	s_add_u32 s28, s30, s28
	s_addc_u32 s29, s31, s29
	s_and_b64 s[30:31], s[40:41], exec
	s_cselect_b32 s19, s29, s45
	s_cselect_b32 s21, s28, s44
	s_add_u32 s42, s42, 0x80080
	s_addc_u32 s43, s43, 0
	s_add_u32 s23, s44, 0x100
	s_addc_u32 s25, s45, 0
	s_mov_b32 s30, -2
	v_readlane_b32 s52, v255, 20
	v_readlane_b32 s53, v255, 21
	v_readlane_b32 s72, v255, 22
	v_readlane_b32 s73, v255, 23
	s_mov_b64 s[74:75], 0x80
	s_add_u32 s31, s42, 0xfff80080
	s_addc_u32 s44, s43, -1
	s_add_i32 s47, 0, 0x10000
	s_cmp_eq_u32 s30, 28
	s_cselect_b32 s49, s13, s44
	s_cselect_b32 s48, s20, s31
	ds_read_b128 v[144:147], v1
	ds_read_b128 v[148:151], v141
	s_cselect_b32 s45, s19, s25
	s_cselect_b32 s44, s21, s23
	s_add_i32 s31, 0, 0x14000
	ds_read_b128 v[152:155], v1 offset:2048
	ds_read_b128 v[156:159], v141 offset:2048
	ds_read_b128 v[160:163], v1 offset:16384
	ds_read_b128 v[164:167], v141 offset:16384
	ds_read_b128 v[168:171], v1 offset:18432
	ds_read_b128 v[172:175], v141 offset:18432
	s_add_i32 m0, s34, 0xc000
	ds_read_b128 v[176:179], v142
	ds_read_b128 v[184:187], v142 offset:2048
	ds_read_b128 v[188:191], v143
	ds_read_b128 v[192:195], v143 offset:2048
	ds_read_b128 v[196:199], v142 offset:4096
	ds_read_b128 v[200:203], v142 offset:6144
	ds_read_b128 v[204:207], v143 offset:4096
	ds_read_b128 v[208:211], v143 offset:6144
	global_load_lds_dwordx4 v138, s[42:43]
	s_add_i32 m0, s34, 0xe000
	s_nop 0
	global_load_lds_dwordx4 v134, s[42:43]
	s_waitcnt vmcnt(8) lgkmcnt(0)
	s_barrier
	s_setprio 1
	v_mfma_f32_16x16x32_bf16 v[128:131], v[144:147], v[176:179], 0
	v_mfma_f32_16x16x32_bf16 v[124:127], v[152:155], v[176:179], 0
	v_mfma_f32_16x16x32_bf16 v[112:115], v[144:147], v[184:187], 0
	v_mfma_f32_16x16x32_bf16 v[108:111], v[152:155], v[184:187], 0
	v_mfma_f32_16x16x32_bf16 v[96:99], v[144:147], v[196:199], 0
	v_mfma_f32_16x16x32_bf16 v[92:95], v[152:155], v[196:199], 0
	v_mfma_f32_16x16x32_bf16 v[80:83], v[144:147], v[200:203], 0
	v_mfma_f32_16x16x32_bf16 v[76:79], v[152:155], v[200:203], 0
	v_mfma_f32_16x16x32_bf16 v[128:131], v[148:151], v[188:191], v[128:131]
	v_mfma_f32_16x16x32_bf16 v[124:127], v[156:159], v[188:191], v[124:127]
	v_mfma_f32_16x16x32_bf16 v[112:115], v[148:151], v[192:195], v[112:115]
	v_mfma_f32_16x16x32_bf16 v[108:111], v[156:159], v[192:195], v[108:111]
	v_mfma_f32_16x16x32_bf16 v[96:99], v[148:151], v[204:207], v[96:99]
	v_mfma_f32_16x16x32_bf16 v[92:95], v[156:159], v[204:207], v[92:95]
	v_mfma_f32_16x16x32_bf16 v[80:83], v[148:151], v[208:211], v[80:83]
	v_mfma_f32_16x16x32_bf16 v[76:79], v[156:159], v[208:211], v[76:79]
	s_setprio 0
	s_setprio 1
	v_mfma_f32_16x16x32_bf16 v[120:123], v[160:163], v[176:179], 0
	v_mfma_f32_16x16x32_bf16 v[116:119], v[168:171], v[176:179], 0
	v_mfma_f32_16x16x32_bf16 v[104:107], v[160:163], v[184:187], 0
	v_mfma_f32_16x16x32_bf16 v[100:103], v[168:171], v[184:187], 0
	v_mfma_f32_16x16x32_bf16 v[88:91], v[160:163], v[196:199], 0
	v_mfma_f32_16x16x32_bf16 v[84:87], v[168:171], v[196:199], 0
	v_mfma_f32_16x16x32_bf16 v[72:75], v[160:163], v[200:203], 0
	v_mfma_f32_16x16x32_bf16 v[68:71], v[168:171], v[200:203], 0
	v_mfma_f32_16x16x32_bf16 v[120:123], v[164:167], v[188:191], v[120:123]
	v_mfma_f32_16x16x32_bf16 v[116:119], v[172:175], v[188:191], v[116:119]
	v_mfma_f32_16x16x32_bf16 v[104:107], v[164:167], v[192:195], v[104:107]
	v_mfma_f32_16x16x32_bf16 v[100:103], v[172:175], v[192:195], v[100:103]
	v_mfma_f32_16x16x32_bf16 v[88:91], v[164:167], v[204:207], v[88:91]
	v_mfma_f32_16x16x32_bf16 v[84:87], v[172:175], v[204:207], v[84:87]
	v_mfma_f32_16x16x32_bf16 v[72:75], v[164:167], v[208:211], v[72:75]
	v_mfma_f32_16x16x32_bf16 v[68:71], v[172:175], v[208:211], v[68:71]
	s_setprio 0
	s_barrier
	s_add_i32 s47, s47, s33
	s_mov_b32 m0, s47
	ds_read_b128 v[176:179], v142 offset:16384
	ds_read_b128 v[184:187], v142 offset:18432
	ds_read_b128 v[188:191], v143 offset:16384
	ds_read_b128 v[192:195], v143 offset:18432
	ds_read_b128 v[196:199], v142 offset:20480
	ds_read_b128 v[200:203], v142 offset:22528
	ds_read_b128 v[204:207], v143 offset:20480
	ds_read_b128 v[208:211], v143 offset:22528
	global_load_lds_dwordx4 v136, s[44:45]
	s_add_i32 m0, s47, 0x2000
	s_add_u32 s50, s44, 0x80000
	s_addc_u32 s51, s45, 0
	s_add_i32 s31, s31, s33
	global_load_lds_dwordx4 v132, s[44:45]
	s_mov_b32 m0, s31
	s_nop 0
	global_load_lds_dwordx4 v136, s[50:51]
	s_add_i32 m0, s31, 0x2000
	s_nop 0
	global_load_lds_dwordx4 v132, s[50:51]
	s_mov_b32 m0, s34
	s_nop 0
	global_load_lds_dwordx4 v138, s[48:49]
	s_mov_b32 m0, s35
	s_nop 0
	global_load_lds_dwordx4 v134, s[48:49]
	s_waitcnt vmcnt(8) lgkmcnt(0)
	s_barrier
	s_setprio 1
	v_mfma_f32_16x16x32_bf16 v[64:67], v[144:147], v[176:179], 0
	v_mfma_f32_16x16x32_bf16 v[60:63], v[152:155], v[176:179], 0
	v_mfma_f32_16x16x32_bf16 v[48:51], v[144:147], v[184:187], 0
	v_mfma_f32_16x16x32_bf16 v[44:47], v[152:155], v[184:187], 0
	v_mfma_f32_16x16x32_bf16 v[30:33], v[144:147], v[196:199], 0
	v_mfma_f32_16x16x32_bf16 v[26:29], v[152:155], v[196:199], 0
	v_mfma_f32_16x16x32_bf16 v[14:17], v[144:147], v[200:203], 0
	v_mfma_f32_16x16x32_bf16 v[10:13], v[152:155], v[200:203], 0
	v_mfma_f32_16x16x32_bf16 v[64:67], v[148:151], v[188:191], v[64:67]
	v_mfma_f32_16x16x32_bf16 v[60:63], v[156:159], v[188:191], v[60:63]
	v_mfma_f32_16x16x32_bf16 v[48:51], v[148:151], v[192:195], v[48:51]
	v_mfma_f32_16x16x32_bf16 v[44:47], v[156:159], v[192:195], v[44:47]
	v_mfma_f32_16x16x32_bf16 v[30:33], v[148:151], v[204:207], v[30:33]
	v_mfma_f32_16x16x32_bf16 v[26:29], v[156:159], v[204:207], v[26:29]
	v_mfma_f32_16x16x32_bf16 v[14:17], v[148:151], v[208:211], v[14:17]
	v_mfma_f32_16x16x32_bf16 v[10:13], v[156:159], v[208:211], v[10:13]
	s_setprio 0
	s_setprio 1
	v_mfma_f32_16x16x32_bf16 v[56:59], v[160:163], v[176:179], 0
	v_mfma_f32_16x16x32_bf16 v[52:55], v[168:171], v[176:179], 0
	v_mfma_f32_16x16x32_bf16 v[40:43], v[160:163], v[184:187], 0
	v_mfma_f32_16x16x32_bf16 v[36:39], v[168:171], v[184:187], 0
	v_mfma_f32_16x16x32_bf16 v[22:25], v[160:163], v[196:199], 0
	v_mfma_f32_16x16x32_bf16 v[18:21], v[168:171], v[196:199], 0
	v_mfma_f32_16x16x32_bf16 v[6:9], v[160:163], v[200:203], 0
	v_mfma_f32_16x16x32_bf16 v[2:5], v[168:171], v[200:203], 0
	v_mfma_f32_16x16x32_bf16 v[56:59], v[164:167], v[188:191], v[56:59]
	v_mfma_f32_16x16x32_bf16 v[52:55], v[172:175], v[188:191], v[52:55]
	v_mfma_f32_16x16x32_bf16 v[40:43], v[164:167], v[192:195], v[40:43]
	v_mfma_f32_16x16x32_bf16 v[36:39], v[172:175], v[192:195], v[36:39]
	v_mfma_f32_16x16x32_bf16 v[22:25], v[164:167], v[204:207], v[22:25]
	v_mfma_f32_16x16x32_bf16 v[18:21], v[172:175], v[204:207], v[18:21]
	v_mfma_f32_16x16x32_bf16 v[6:9], v[164:167], v[208:211], v[6:9]
	v_mfma_f32_16x16x32_bf16 v[2:5], v[172:175], v[208:211], v[2:5]
	s_setprio 0
	s_barrier
	s_add_i32 s31, 0, 0x18000
	ds_read_b128 v[144:147], v1 offset:32768
	ds_read_b128 v[148:151], v141 offset:32768
	s_add_i32 s47, 0, 0x1c000
	ds_read_b128 v[152:155], v1 offset:34816
	ds_read_b128 v[156:159], v141 offset:34816
	ds_read_b128 v[160:163], v1 offset:49152
	ds_read_b128 v[164:167], v141 offset:49152
	ds_read_b128 v[168:171], v1 offset:51200
	ds_read_b128 v[172:175], v141 offset:51200
	s_mov_b64 s[100:101], s[48:49]
	s_add_u32 s48, s48, 0x80000
	s_addc_u32 s49, s49, 0
	s_mov_b32 m0, s54
	ds_read_b128 v[176:179], v142 offset:32768
	ds_read_b128 v[184:187], v142 offset:34816
	ds_read_b128 v[188:191], v143 offset:32768
	ds_read_b128 v[192:195], v143 offset:34816
	ds_read_b128 v[196:199], v142 offset:36864
	ds_read_b128 v[200:203], v142 offset:38912
	ds_read_b128 v[204:207], v143 offset:36864
	ds_read_b128 v[208:211], v143 offset:38912
	global_load_lds_dwordx4 v138, s[48:49]
	s_mov_b32 m0, s55
	s_nop 0
	global_load_lds_dwordx4 v134, s[48:49]
	s_waitcnt vmcnt(8) lgkmcnt(0)
	s_barrier
	s_setprio 1
	v_mfma_f32_16x16x32_bf16 v[128:131], v[144:147], v[176:179], v[128:131]
	v_mfma_f32_16x16x32_bf16 v[124:127], v[152:155], v[176:179], v[124:127]
	v_mfma_f32_16x16x32_bf16 v[112:115], v[144:147], v[184:187], v[112:115]
	v_mfma_f32_16x16x32_bf16 v[108:111], v[152:155], v[184:187], v[108:111]
	v_mfma_f32_16x16x32_bf16 v[96:99], v[144:147], v[196:199], v[96:99]
	v_mfma_f32_16x16x32_bf16 v[92:95], v[152:155], v[196:199], v[92:95]
	v_mfma_f32_16x16x32_bf16 v[80:83], v[144:147], v[200:203], v[80:83]
	v_mfma_f32_16x16x32_bf16 v[76:79], v[152:155], v[200:203], v[76:79]
	v_mfma_f32_16x16x32_bf16 v[128:131], v[148:151], v[188:191], v[128:131]
	v_mfma_f32_16x16x32_bf16 v[124:127], v[156:159], v[188:191], v[124:127]
	v_mfma_f32_16x16x32_bf16 v[112:115], v[148:151], v[192:195], v[112:115]
	v_mfma_f32_16x16x32_bf16 v[108:111], v[156:159], v[192:195], v[108:111]
	v_mfma_f32_16x16x32_bf16 v[96:99], v[148:151], v[204:207], v[96:99]
	v_mfma_f32_16x16x32_bf16 v[92:95], v[156:159], v[204:207], v[92:95]
	v_mfma_f32_16x16x32_bf16 v[80:83], v[148:151], v[208:211], v[80:83]
	v_mfma_f32_16x16x32_bf16 v[76:79], v[156:159], v[208:211], v[76:79]
	s_setprio 0
	s_setprio 1
	v_mfma_f32_16x16x32_bf16 v[120:123], v[160:163], v[176:179], v[120:123]
	v_mfma_f32_16x16x32_bf16 v[116:119], v[168:171], v[176:179], v[116:119]
	v_mfma_f32_16x16x32_bf16 v[104:107], v[160:163], v[184:187], v[104:107]
	v_mfma_f32_16x16x32_bf16 v[100:103], v[168:171], v[184:187], v[100:103]
	v_mfma_f32_16x16x32_bf16 v[88:91], v[160:163], v[196:199], v[88:91]
	v_mfma_f32_16x16x32_bf16 v[84:87], v[168:171], v[196:199], v[84:87]
	v_mfma_f32_16x16x32_bf16 v[72:75], v[160:163], v[200:203], v[72:75]
	v_mfma_f32_16x16x32_bf16 v[68:71], v[168:171], v[200:203], v[68:71]
	v_mfma_f32_16x16x32_bf16 v[120:123], v[164:167], v[188:191], v[120:123]
	v_mfma_f32_16x16x32_bf16 v[116:119], v[172:175], v[188:191], v[116:119]
	v_mfma_f32_16x16x32_bf16 v[104:107], v[164:167], v[192:195], v[104:107]
	v_mfma_f32_16x16x32_bf16 v[100:103], v[172:175], v[192:195], v[100:103]
	v_mfma_f32_16x16x32_bf16 v[88:91], v[164:167], v[204:207], v[88:91]
	v_mfma_f32_16x16x32_bf16 v[84:87], v[172:175], v[204:207], v[84:87]
	v_mfma_f32_16x16x32_bf16 v[72:75], v[164:167], v[208:211], v[72:75]
	v_mfma_f32_16x16x32_bf16 v[68:71], v[172:175], v[208:211], v[68:71]
	s_setprio 0
	s_barrier
	s_add_i32 s31, s31, s33
	s_add_i32 m0, s31, 0xffffff80
	ds_read_b128 v[176:179], v142 offset:49152
	ds_read_b128 v[184:187], v142 offset:51200
	ds_read_b128 v[188:191], v143 offset:49152
	ds_read_b128 v[192:195], v143 offset:51200
	ds_read_b128 v[196:199], v142 offset:53248
	ds_read_b128 v[200:203], v142 offset:55296
	ds_read_b128 v[204:207], v143 offset:53248
	ds_read_b128 v[208:211], v143 offset:55296
	global_load_lds_dwordx4 v136, s[44:45] offset:128
	s_add_i32 m0, s31, 0x1f80
	s_mov_b64 s[98:99], s[44:45]
	s_add_u32 s44, s44, 0x80080
	s_addc_u32 s45, s45, 0
	s_add_i32 s31, s47, s33
	global_load_lds_dwordx4 v132, s[98:99] offset:128
	s_mov_b32 m0, s31
	s_nop 0
	global_load_lds_dwordx4 v136, s[44:45]
	s_add_i32 m0, s31, 0x2000
	s_nop 0
	global_load_lds_dwordx4 v132, s[44:45]
	s_add_i32 m0, s56, 0xffffff80
	s_nop 0
	global_load_lds_dwordx4 v138, s[100:101] offset:128
	s_add_i32 m0, s57, 0xffffff80
	s_nop 0
	global_load_lds_dwordx4 v134, s[100:101] offset:128
	s_waitcnt vmcnt(8) lgkmcnt(0)
	s_barrier
	s_setprio 1
	v_mfma_f32_16x16x32_bf16 v[64:67], v[144:147], v[176:179], v[64:67]
	v_mfma_f32_16x16x32_bf16 v[60:63], v[152:155], v[176:179], v[60:63]
	v_mfma_f32_16x16x32_bf16 v[48:51], v[144:147], v[184:187], v[48:51]
	v_mfma_f32_16x16x32_bf16 v[44:47], v[152:155], v[184:187], v[44:47]
	v_mfma_f32_16x16x32_bf16 v[30:33], v[144:147], v[196:199], v[30:33]
	v_mfma_f32_16x16x32_bf16 v[26:29], v[152:155], v[196:199], v[26:29]
	v_mfma_f32_16x16x32_bf16 v[14:17], v[144:147], v[200:203], v[14:17]
	v_mfma_f32_16x16x32_bf16 v[10:13], v[152:155], v[200:203], v[10:13]
	v_mfma_f32_16x16x32_bf16 v[64:67], v[148:151], v[188:191], v[64:67]
	v_mfma_f32_16x16x32_bf16 v[60:63], v[156:159], v[188:191], v[60:63]
	v_mfma_f32_16x16x32_bf16 v[48:51], v[148:151], v[192:195], v[48:51]
	v_mfma_f32_16x16x32_bf16 v[44:47], v[156:159], v[192:195], v[44:47]
	v_mfma_f32_16x16x32_bf16 v[30:33], v[148:151], v[204:207], v[30:33]
	v_mfma_f32_16x16x32_bf16 v[26:29], v[156:159], v[204:207], v[26:29]
	v_mfma_f32_16x16x32_bf16 v[14:17], v[148:151], v[208:211], v[14:17]
	v_mfma_f32_16x16x32_bf16 v[10:13], v[156:159], v[208:211], v[10:13]
	s_setprio 0
	s_setprio 1
	v_mfma_f32_16x16x32_bf16 v[56:59], v[160:163], v[176:179], v[56:59]
	v_mfma_f32_16x16x32_bf16 v[52:55], v[168:171], v[176:179], v[52:55]
	v_mfma_f32_16x16x32_bf16 v[40:43], v[160:163], v[184:187], v[40:43]
	v_mfma_f32_16x16x32_bf16 v[36:39], v[168:171], v[184:187], v[36:39]
	v_mfma_f32_16x16x32_bf16 v[22:25], v[160:163], v[196:199], v[22:25]
	v_mfma_f32_16x16x32_bf16 v[18:21], v[168:171], v[196:199], v[18:21]
	v_mfma_f32_16x16x32_bf16 v[6:9], v[160:163], v[200:203], v[6:9]
	v_mfma_f32_16x16x32_bf16 v[2:5], v[168:171], v[200:203], v[2:5]
	v_mfma_f32_16x16x32_bf16 v[56:59], v[164:167], v[188:191], v[56:59]
	v_mfma_f32_16x16x32_bf16 v[52:55], v[172:175], v[188:191], v[52:55]
	v_mfma_f32_16x16x32_bf16 v[40:43], v[164:167], v[192:195], v[40:43]
	v_mfma_f32_16x16x32_bf16 v[36:39], v[172:175], v[192:195], v[36:39]
	v_mfma_f32_16x16x32_bf16 v[22:25], v[164:167], v[204:207], v[22:25]
	v_mfma_f32_16x16x32_bf16 v[18:21], v[172:175], v[204:207], v[18:21]
	v_mfma_f32_16x16x32_bf16 v[6:9], v[164:167], v[208:211], v[6:9]
	v_mfma_f32_16x16x32_bf16 v[2:5], v[172:175], v[208:211], v[2:5]
	s_setprio 0
	s_barrier
	s_add_i32 s30, s30, 2
	s_add_u32 s42, s42, 0x100
	s_addc_u32 s43, s43, 0
	s_add_u32 s23, s23, 0x100
	s_addc_u32 s25, s25, 0
	s_cmp_gt_u32 s30, 29
	s_cbranch_scc1 .Lpeel_done_P1
.LBB0_162:
	s_add_u32 s31, s42, 0xfff80080
	s_addc_u32 s44, s43, -1
	s_add_i32 s47, 0, 0x10000
	s_cmp_eq_u32 s30, 28
	s_cselect_b32 s49, s13, s44
	s_cselect_b32 s48, s20, s31
	ds_read_b128 v[144:147], v1
	ds_read_b128 v[148:151], v141
	s_cselect_b32 s45, s19, s25
	s_cselect_b32 s44, s21, s23
	s_add_i32 s31, 0, 0x14000
	ds_read_b128 v[152:155], v1 offset:2048
	ds_read_b128 v[156:159], v141 offset:2048
	ds_read_b128 v[160:163], v1 offset:16384
	ds_read_b128 v[164:167], v141 offset:16384
	ds_read_b128 v[168:171], v1 offset:18432
	ds_read_b128 v[172:175], v141 offset:18432
	s_add_i32 m0, s34, 0xc000
	ds_read_b128 v[176:179], v142
	ds_read_b128 v[184:187], v142 offset:2048
	ds_read_b128 v[188:191], v143
	ds_read_b128 v[192:195], v143 offset:2048
	ds_read_b128 v[196:199], v142 offset:4096
	ds_read_b128 v[200:203], v142 offset:6144
	ds_read_b128 v[204:207], v143 offset:4096
	ds_read_b128 v[208:211], v143 offset:6144
	global_load_lds_dwordx4 v138, s[42:43]
	s_add_i32 m0, s34, 0xe000
	s_nop 0
	global_load_lds_dwordx4 v134, s[42:43]
	s_waitcnt vmcnt(8) lgkmcnt(0)
	s_barrier
	s_setprio 1
	v_mfma_f32_16x16x32_bf16 v[128:131], v[144:147], v[176:179], v[128:131]
	v_mfma_f32_16x16x32_bf16 v[124:127], v[152:155], v[176:179], v[124:127]
	v_mfma_f32_16x16x32_bf16 v[112:115], v[144:147], v[184:187], v[112:115]
	v_mfma_f32_16x16x32_bf16 v[108:111], v[152:155], v[184:187], v[108:111]
	v_mfma_f32_16x16x32_bf16 v[96:99], v[144:147], v[196:199], v[96:99]
	v_mfma_f32_16x16x32_bf16 v[92:95], v[152:155], v[196:199], v[92:95]
	v_mfma_f32_16x16x32_bf16 v[80:83], v[144:147], v[200:203], v[80:83]
	v_mfma_f32_16x16x32_bf16 v[76:79], v[152:155], v[200:203], v[76:79]
	v_mfma_f32_16x16x32_bf16 v[128:131], v[148:151], v[188:191], v[128:131]
	v_mfma_f32_16x16x32_bf16 v[124:127], v[156:159], v[188:191], v[124:127]
	v_mfma_f32_16x16x32_bf16 v[112:115], v[148:151], v[192:195], v[112:115]
	v_mfma_f32_16x16x32_bf16 v[108:111], v[156:159], v[192:195], v[108:111]
	v_mfma_f32_16x16x32_bf16 v[96:99], v[148:151], v[204:207], v[96:99]
	v_mfma_f32_16x16x32_bf16 v[92:95], v[156:159], v[204:207], v[92:95]
	v_mfma_f32_16x16x32_bf16 v[80:83], v[148:151], v[208:211], v[80:83]
	v_mfma_f32_16x16x32_bf16 v[76:79], v[156:159], v[208:211], v[76:79]
	s_setprio 0
	s_setprio 1
	v_mfma_f32_16x16x32_bf16 v[120:123], v[160:163], v[176:179], v[120:123]
	v_mfma_f32_16x16x32_bf16 v[116:119], v[168:171], v[176:179], v[116:119]
	v_mfma_f32_16x16x32_bf16 v[104:107], v[160:163], v[184:187], v[104:107]
	v_mfma_f32_16x16x32_bf16 v[100:103], v[168:171], v[184:187], v[100:103]
	v_mfma_f32_16x16x32_bf16 v[88:91], v[160:163], v[196:199], v[88:91]
	v_mfma_f32_16x16x32_bf16 v[84:87], v[168:171], v[196:199], v[84:87]
	v_mfma_f32_16x16x32_bf16 v[72:75], v[160:163], v[200:203], v[72:75]
	v_mfma_f32_16x16x32_bf16 v[68:71], v[168:171], v[200:203], v[68:71]
	v_mfma_f32_16x16x32_bf16 v[120:123], v[164:167], v[188:191], v[120:123]
	v_mfma_f32_16x16x32_bf16 v[116:119], v[172:175], v[188:191], v[116:119]
	v_mfma_f32_16x16x32_bf16 v[104:107], v[164:167], v[192:195], v[104:107]
	v_mfma_f32_16x16x32_bf16 v[100:103], v[172:175], v[192:195], v[100:103]
	v_mfma_f32_16x16x32_bf16 v[88:91], v[164:167], v[204:207], v[88:91]
	v_mfma_f32_16x16x32_bf16 v[84:87], v[172:175], v[204:207], v[84:87]
	v_mfma_f32_16x16x32_bf16 v[72:75], v[164:167], v[208:211], v[72:75]
	v_mfma_f32_16x16x32_bf16 v[68:71], v[172:175], v[208:211], v[68:71]
	s_setprio 0
	s_barrier
	s_add_i32 s47, s47, s33
	s_mov_b32 m0, s47
	ds_read_b128 v[176:179], v142 offset:16384
	ds_read_b128 v[184:187], v142 offset:18432
	ds_read_b128 v[188:191], v143 offset:16384
	ds_read_b128 v[192:195], v143 offset:18432
	ds_read_b128 v[196:199], v142 offset:20480
	ds_read_b128 v[200:203], v142 offset:22528
	ds_read_b128 v[204:207], v143 offset:20480
	ds_read_b128 v[208:211], v143 offset:22528
	global_load_lds_dwordx4 v136, s[44:45]
	s_add_i32 m0, s47, 0x2000
	s_add_u32 s50, s44, 0x80000
	s_addc_u32 s51, s45, 0
	s_add_i32 s31, s31, s33
	global_load_lds_dwordx4 v132, s[44:45]
	s_mov_b32 m0, s31
	s_nop 0
	global_load_lds_dwordx4 v136, s[50:51]
	s_add_i32 m0, s31, 0x2000
	s_nop 0
	global_load_lds_dwordx4 v132, s[50:51]
	s_mov_b32 m0, s34
	s_nop 0
	global_load_lds_dwordx4 v138, s[48:49]
	s_mov_b32 m0, s35
	s_nop 0
	global_load_lds_dwordx4 v134, s[48:49]
	s_waitcnt vmcnt(8) lgkmcnt(0)
	s_barrier
	s_setprio 1
	v_mfma_f32_16x16x32_bf16 v[64:67], v[144:147], v[176:179], v[64:67]
	v_mfma_f32_16x16x32_bf16 v[60:63], v[152:155], v[176:179], v[60:63]
	v_mfma_f32_16x16x32_bf16 v[48:51], v[144:147], v[184:187], v[48:51]
	v_mfma_f32_16x16x32_bf16 v[44:47], v[152:155], v[184:187], v[44:47]
	v_mfma_f32_16x16x32_bf16 v[30:33], v[144:147], v[196:199], v[30:33]
	v_mfma_f32_16x16x32_bf16 v[26:29], v[152:155], v[196:199], v[26:29]
	v_mfma_f32_16x16x32_bf16 v[14:17], v[144:147], v[200:203], v[14:17]
	v_mfma_f32_16x16x32_bf16 v[10:13], v[152:155], v[200:203], v[10:13]
	v_mfma_f32_16x16x32_bf16 v[64:67], v[148:151], v[188:191], v[64:67]
	v_mfma_f32_16x16x32_bf16 v[60:63], v[156:159], v[188:191], v[60:63]
	v_mfma_f32_16x16x32_bf16 v[48:51], v[148:151], v[192:195], v[48:51]
	v_mfma_f32_16x16x32_bf16 v[44:47], v[156:159], v[192:195], v[44:47]
	v_mfma_f32_16x16x32_bf16 v[30:33], v[148:151], v[204:207], v[30:33]
	v_mfma_f32_16x16x32_bf16 v[26:29], v[156:159], v[204:207], v[26:29]
	v_mfma_f32_16x16x32_bf16 v[14:17], v[148:151], v[208:211], v[14:17]
	v_mfma_f32_16x16x32_bf16 v[10:13], v[156:159], v[208:211], v[10:13]
	s_setprio 0
	s_setprio 1
	v_mfma_f32_16x16x32_bf16 v[56:59], v[160:163], v[176:179], v[56:59]
	v_mfma_f32_16x16x32_bf16 v[52:55], v[168:171], v[176:179], v[52:55]
	v_mfma_f32_16x16x32_bf16 v[40:43], v[160:163], v[184:187], v[40:43]
	v_mfma_f32_16x16x32_bf16 v[36:39], v[168:171], v[184:187], v[36:39]
	v_mfma_f32_16x16x32_bf16 v[22:25], v[160:163], v[196:199], v[22:25]
	v_mfma_f32_16x16x32_bf16 v[18:21], v[168:171], v[196:199], v[18:21]
	v_mfma_f32_16x16x32_bf16 v[6:9], v[160:163], v[200:203], v[6:9]
	v_mfma_f32_16x16x32_bf16 v[2:5], v[168:171], v[200:203], v[2:5]
	v_mfma_f32_16x16x32_bf16 v[56:59], v[164:167], v[188:191], v[56:59]
	v_mfma_f32_16x16x32_bf16 v[52:55], v[172:175], v[188:191], v[52:55]
	v_mfma_f32_16x16x32_bf16 v[40:43], v[164:167], v[192:195], v[40:43]
	v_mfma_f32_16x16x32_bf16 v[36:39], v[172:175], v[192:195], v[36:39]
	v_mfma_f32_16x16x32_bf16 v[22:25], v[164:167], v[204:207], v[22:25]
	v_mfma_f32_16x16x32_bf16 v[18:21], v[172:175], v[204:207], v[18:21]
	v_mfma_f32_16x16x32_bf16 v[6:9], v[164:167], v[208:211], v[6:9]
	v_mfma_f32_16x16x32_bf16 v[2:5], v[172:175], v[208:211], v[2:5]
	s_setprio 0
	s_barrier
	s_add_i32 s31, 0, 0x18000
	ds_read_b128 v[144:147], v1 offset:32768
	ds_read_b128 v[148:151], v141 offset:32768
	s_add_i32 s47, 0, 0x1c000
	ds_read_b128 v[152:155], v1 offset:34816
	ds_read_b128 v[156:159], v141 offset:34816
	ds_read_b128 v[160:163], v1 offset:49152
	ds_read_b128 v[164:167], v141 offset:49152
	ds_read_b128 v[168:171], v1 offset:51200
	ds_read_b128 v[172:175], v141 offset:51200
	s_mov_b64 s[100:101], s[48:49]
	s_add_u32 s48, s48, 0x80000
	s_addc_u32 s49, s49, 0
	s_mov_b32 m0, s54
	ds_read_b128 v[176:179], v142 offset:32768
	ds_read_b128 v[184:187], v142 offset:34816
	ds_read_b128 v[188:191], v143 offset:32768
	ds_read_b128 v[192:195], v143 offset:34816
	ds_read_b128 v[196:199], v142 offset:36864
	ds_read_b128 v[200:203], v142 offset:38912
	ds_read_b128 v[204:207], v143 offset:36864
	ds_read_b128 v[208:211], v143 offset:38912
	global_load_lds_dwordx4 v138, s[48:49]
	s_mov_b32 m0, s55
	s_nop 0
	global_load_lds_dwordx4 v134, s[48:49]
	s_waitcnt vmcnt(8) lgkmcnt(0)
	s_barrier
	s_setprio 1
	v_mfma_f32_16x16x32_bf16 v[128:131], v[144:147], v[176:179], v[128:131]
	v_mfma_f32_16x16x32_bf16 v[124:127], v[152:155], v[176:179], v[124:127]
	v_mfma_f32_16x16x32_bf16 v[112:115], v[144:147], v[184:187], v[112:115]
	v_mfma_f32_16x16x32_bf16 v[108:111], v[152:155], v[184:187], v[108:111]
	v_mfma_f32_16x16x32_bf16 v[96:99], v[144:147], v[196:199], v[96:99]
	v_mfma_f32_16x16x32_bf16 v[92:95], v[152:155], v[196:199], v[92:95]
	v_mfma_f32_16x16x32_bf16 v[80:83], v[144:147], v[200:203], v[80:83]
	v_mfma_f32_16x16x32_bf16 v[76:79], v[152:155], v[200:203], v[76:79]
	v_mfma_f32_16x16x32_bf16 v[128:131], v[148:151], v[188:191], v[128:131]
	v_mfma_f32_16x16x32_bf16 v[124:127], v[156:159], v[188:191], v[124:127]
	v_mfma_f32_16x16x32_bf16 v[112:115], v[148:151], v[192:195], v[112:115]
	v_mfma_f32_16x16x32_bf16 v[108:111], v[156:159], v[192:195], v[108:111]
	v_mfma_f32_16x16x32_bf16 v[96:99], v[148:151], v[204:207], v[96:99]
	v_mfma_f32_16x16x32_bf16 v[92:95], v[156:159], v[204:207], v[92:95]
	v_mfma_f32_16x16x32_bf16 v[80:83], v[148:151], v[208:211], v[80:83]
	v_mfma_f32_16x16x32_bf16 v[76:79], v[156:159], v[208:211], v[76:79]
	s_setprio 0
	s_setprio 1
	v_mfma_f32_16x16x32_bf16 v[120:123], v[160:163], v[176:179], v[120:123]
	v_mfma_f32_16x16x32_bf16 v[116:119], v[168:171], v[176:179], v[116:119]
	v_mfma_f32_16x16x32_bf16 v[104:107], v[160:163], v[184:187], v[104:107]
	v_mfma_f32_16x16x32_bf16 v[100:103], v[168:171], v[184:187], v[100:103]
	v_mfma_f32_16x16x32_bf16 v[88:91], v[160:163], v[196:199], v[88:91]
	v_mfma_f32_16x16x32_bf16 v[84:87], v[168:171], v[196:199], v[84:87]
	v_mfma_f32_16x16x32_bf16 v[72:75], v[160:163], v[200:203], v[72:75]
	v_mfma_f32_16x16x32_bf16 v[68:71], v[168:171], v[200:203], v[68:71]
	v_mfma_f32_16x16x32_bf16 v[120:123], v[164:167], v[188:191], v[120:123]
	v_mfma_f32_16x16x32_bf16 v[116:119], v[172:175], v[188:191], v[116:119]
	v_mfma_f32_16x16x32_bf16 v[104:107], v[164:167], v[192:195], v[104:107]
	v_mfma_f32_16x16x32_bf16 v[100:103], v[172:175], v[192:195], v[100:103]
	v_mfma_f32_16x16x32_bf16 v[88:91], v[164:167], v[204:207], v[88:91]
	v_mfma_f32_16x16x32_bf16 v[84:87], v[172:175], v[204:207], v[84:87]
	v_mfma_f32_16x16x32_bf16 v[72:75], v[164:167], v[208:211], v[72:75]
	v_mfma_f32_16x16x32_bf16 v[68:71], v[172:175], v[208:211], v[68:71]
	s_setprio 0
	s_barrier
	s_add_i32 s31, s31, s33
	s_add_i32 m0, s31, 0xffffff80
	ds_read_b128 v[176:179], v142 offset:49152
	ds_read_b128 v[184:187], v142 offset:51200
	ds_read_b128 v[188:191], v143 offset:49152
	ds_read_b128 v[192:195], v143 offset:51200
	ds_read_b128 v[196:199], v142 offset:53248
	ds_read_b128 v[200:203], v142 offset:55296
	ds_read_b128 v[204:207], v143 offset:53248
	ds_read_b128 v[208:211], v143 offset:55296
	global_load_lds_dwordx4 v136, s[44:45] offset:128
	s_add_i32 m0, s31, 0x1f80
	s_mov_b64 s[98:99], s[44:45]
	s_add_u32 s44, s44, 0x80080
	s_addc_u32 s45, s45, 0
	s_add_i32 s31, s47, s33
	global_load_lds_dwordx4 v132, s[98:99] offset:128
	s_mov_b32 m0, s31
	s_nop 0
	global_load_lds_dwordx4 v136, s[44:45]
	s_add_i32 m0, s31, 0x2000
	s_nop 0
	global_load_lds_dwordx4 v132, s[44:45]
	s_add_i32 m0, s56, 0xffffff80
	s_nop 0
	global_load_lds_dwordx4 v138, s[100:101] offset:128
	s_add_i32 m0, s57, 0xffffff80
	s_nop 0
	global_load_lds_dwordx4 v134, s[100:101] offset:128
	s_waitcnt vmcnt(8) lgkmcnt(0)
	s_barrier
	s_setprio 1
	v_mfma_f32_16x16x32_bf16 v[64:67], v[144:147], v[176:179], v[64:67]
	v_mfma_f32_16x16x32_bf16 v[60:63], v[152:155], v[176:179], v[60:63]
	v_mfma_f32_16x16x32_bf16 v[48:51], v[144:147], v[184:187], v[48:51]
	v_mfma_f32_16x16x32_bf16 v[44:47], v[152:155], v[184:187], v[44:47]
	v_mfma_f32_16x16x32_bf16 v[30:33], v[144:147], v[196:199], v[30:33]
	v_mfma_f32_16x16x32_bf16 v[26:29], v[152:155], v[196:199], v[26:29]
	v_mfma_f32_16x16x32_bf16 v[14:17], v[144:147], v[200:203], v[14:17]
	v_mfma_f32_16x16x32_bf16 v[10:13], v[152:155], v[200:203], v[10:13]
	v_mfma_f32_16x16x32_bf16 v[64:67], v[148:151], v[188:191], v[64:67]
	v_mfma_f32_16x16x32_bf16 v[60:63], v[156:159], v[188:191], v[60:63]
	v_mfma_f32_16x16x32_bf16 v[48:51], v[148:151], v[192:195], v[48:51]
	v_mfma_f32_16x16x32_bf16 v[44:47], v[156:159], v[192:195], v[44:47]
	v_mfma_f32_16x16x32_bf16 v[30:33], v[148:151], v[204:207], v[30:33]
	v_mfma_f32_16x16x32_bf16 v[26:29], v[156:159], v[204:207], v[26:29]
	v_mfma_f32_16x16x32_bf16 v[14:17], v[148:151], v[208:211], v[14:17]
	v_mfma_f32_16x16x32_bf16 v[10:13], v[156:159], v[208:211], v[10:13]
	s_setprio 0
	s_setprio 1
	v_mfma_f32_16x16x32_bf16 v[56:59], v[160:163], v[176:179], v[56:59]
	v_mfma_f32_16x16x32_bf16 v[52:55], v[168:171], v[176:179], v[52:55]
	v_mfma_f32_16x16x32_bf16 v[40:43], v[160:163], v[184:187], v[40:43]
	v_mfma_f32_16x16x32_bf16 v[36:39], v[168:171], v[184:187], v[36:39]
	v_mfma_f32_16x16x32_bf16 v[22:25], v[160:163], v[196:199], v[22:25]
	v_mfma_f32_16x16x32_bf16 v[18:21], v[168:171], v[196:199], v[18:21]
	v_mfma_f32_16x16x32_bf16 v[6:9], v[160:163], v[200:203], v[6:9]
	v_mfma_f32_16x16x32_bf16 v[2:5], v[168:171], v[200:203], v[2:5]
	v_mfma_f32_16x16x32_bf16 v[56:59], v[164:167], v[188:191], v[56:59]
	v_mfma_f32_16x16x32_bf16 v[52:55], v[172:175], v[188:191], v[52:55]
	v_mfma_f32_16x16x32_bf16 v[40:43], v[164:167], v[192:195], v[40:43]
	v_mfma_f32_16x16x32_bf16 v[36:39], v[172:175], v[192:195], v[36:39]
	v_mfma_f32_16x16x32_bf16 v[22:25], v[164:167], v[204:207], v[22:25]
	v_mfma_f32_16x16x32_bf16 v[18:21], v[172:175], v[204:207], v[18:21]
	v_mfma_f32_16x16x32_bf16 v[6:9], v[164:167], v[208:211], v[6:9]
	v_mfma_f32_16x16x32_bf16 v[2:5], v[172:175], v[208:211], v[2:5]
	s_setprio 0
	s_barrier
	s_add_i32 s30, s30, 2
	s_add_u32 s42, s42, 0x100
	s_addc_u32 s43, s43, 0
	s_add_u32 s23, s23, 0x100
	s_addc_u32 s25, s25, 0
	s_cmp_gt_u32 s30, 29
	s_cbranch_scc0 .LBB0_162

.LBB0_907:
	s_and_b32 s9, 1, s12
	s_cmp_gt_i32 s12, 1
	s_cselect_b32 s24, 10, 12
	s_cmp_eq_u32 s9, 1
	s_cselect_b64 s[18:19], -1, 0
	s_and_b64 s[20:21], s[18:19], exec
	s_cselect_b32 s9, s24, 32
	s_add_i32 s20, s9, -2
	s_add_u32 s22, s22, 0x80080
	s_addc_u32 s23, s23, 0
	s_add_u32 s21, s28, 0x100
	s_addc_u32 s24, s29, 0
	s_mov_b32 s25, 0
	s_waitcnt vmcnt(0)
	v_readlane_b32 s43, v255, 20
	v_readlane_b32 s45, v255, 21
	v_readlane_b32 s66, v255, 22
	v_readlane_b32 s67, v255, 23
	s_mov_b64 s[68:69], 0x80
	s_add_i32 s30, s25, 2
	s_add_u32 s28, s22, 0xfff80080
	s_addc_u32 s29, s23, -1
	s_add_i32 s31, 0, 0x10000
	s_cmp_eq_u32 s20, s25
	s_cselect_b32 s41, s47, s29
	s_cselect_b32 s40, s46, s28
	s_cselect_b32 s29, s49, s24
	s_cselect_b32 s28, s48, s21
	s_add_i32 s25, 0, 0x14000
	ds_read_b128 v[132:135], v1
	ds_read_b128 v[136:139], v204
	ds_read_b128 v[140:143], v1 offset:2048
	ds_read_b128 v[144:147], v204 offset:2048
	ds_read_b128 v[148:151], v1 offset:16384
	ds_read_b128 v[152:155], v204 offset:16384
	ds_read_b128 v[156:159], v1 offset:18432
	ds_read_b128 v[160:163], v204 offset:18432
	s_add_i32 m0, s50, 0xc000
	ds_read_b128 v[164:167], v205
	ds_read_b128 v[168:171], v205 offset:2048
	ds_read_b128 v[172:175], v206
	ds_read_b128 v[176:179], v206 offset:2048
	ds_read_b128 v[190:193], v205 offset:4096
	ds_read_b128 v[194:197], v205 offset:6144
	ds_read_b128 v[198:201], v206 offset:4096
	ds_read_b128 v[232:235], v206 offset:6144
	global_load_lds_dwordx4 v188, s[22:23]
	s_add_i32 m0, s50, 0xe000
	s_nop 0
	global_load_lds_dwordx4 v186, s[22:23]
	s_waitcnt vmcnt(8) lgkmcnt(0)
	s_barrier
	s_setprio 1
	v_mfma_f32_16x16x32_bf16 v[68:71], v[132:135], v[164:167], 0
	v_mfma_f32_16x16x32_bf16 v[72:75], v[140:143], v[164:167], 0
	v_mfma_f32_16x16x32_bf16 v[84:87], v[132:135], v[168:171], 0
	v_mfma_f32_16x16x32_bf16 v[88:91], v[140:143], v[168:171], 0
	v_mfma_f32_16x16x32_bf16 v[100:103], v[132:135], v[190:193], 0
	v_mfma_f32_16x16x32_bf16 v[104:107], v[140:143], v[190:193], 0
	v_mfma_f32_16x16x32_bf16 v[116:119], v[132:135], v[194:197], 0
	v_mfma_f32_16x16x32_bf16 v[120:123], v[140:143], v[194:197], 0
	v_mfma_f32_16x16x32_bf16 v[68:71], v[136:139], v[172:175], v[68:71]
	v_mfma_f32_16x16x32_bf16 v[72:75], v[144:147], v[172:175], v[72:75]
	v_mfma_f32_16x16x32_bf16 v[84:87], v[136:139], v[176:179], v[84:87]
	v_mfma_f32_16x16x32_bf16 v[88:91], v[144:147], v[176:179], v[88:91]
	v_mfma_f32_16x16x32_bf16 v[100:103], v[136:139], v[198:201], v[100:103]
	v_mfma_f32_16x16x32_bf16 v[104:107], v[144:147], v[198:201], v[104:107]
	v_mfma_f32_16x16x32_bf16 v[116:119], v[136:139], v[232:235], v[116:119]
	v_mfma_f32_16x16x32_bf16 v[120:123], v[144:147], v[232:235], v[120:123]
	s_setprio 0
	s_setprio 1
	v_mfma_f32_16x16x32_bf16 v[76:79], v[148:151], v[164:167], 0
	v_mfma_f32_16x16x32_bf16 v[80:83], v[156:159], v[164:167], 0
	v_mfma_f32_16x16x32_bf16 v[92:95], v[148:151], v[168:171], 0
	v_mfma_f32_16x16x32_bf16 v[96:99], v[156:159], v[168:171], 0
	v_mfma_f32_16x16x32_bf16 v[108:111], v[148:151], v[190:193], 0
	v_mfma_f32_16x16x32_bf16 v[112:115], v[156:159], v[190:193], 0
	v_mfma_f32_16x16x32_bf16 v[124:127], v[148:151], v[194:197], 0
	v_mfma_f32_16x16x32_bf16 v[128:131], v[156:159], v[194:197], 0
	v_mfma_f32_16x16x32_bf16 v[76:79], v[152:155], v[172:175], v[76:79]
	v_mfma_f32_16x16x32_bf16 v[80:83], v[160:163], v[172:175], v[80:83]
	v_mfma_f32_16x16x32_bf16 v[92:95], v[152:155], v[176:179], v[92:95]
	v_mfma_f32_16x16x32_bf16 v[96:99], v[160:163], v[176:179], v[96:99]
	v_mfma_f32_16x16x32_bf16 v[108:111], v[152:155], v[198:201], v[108:111]
	v_mfma_f32_16x16x32_bf16 v[112:115], v[160:163], v[198:201], v[112:115]
	v_mfma_f32_16x16x32_bf16 v[124:127], v[152:155], v[232:235], v[124:127]
	v_mfma_f32_16x16x32_bf16 v[128:131], v[160:163], v[232:235], v[128:131]
	s_setprio 0
	s_barrier
	s_add_i32 s31, s31, s33
	s_mov_b32 m0, s31
	ds_read_b128 v[164:167], v205 offset:16384
	ds_read_b128 v[168:171], v205 offset:18432
	ds_read_b128 v[172:175], v206 offset:16384
	ds_read_b128 v[176:179], v206 offset:18432
	ds_read_b128 v[190:193], v205 offset:20480
	ds_read_b128 v[194:197], v205 offset:22528
	ds_read_b128 v[198:201], v206 offset:20480
	ds_read_b128 v[232:235], v206 offset:22528
	global_load_lds_dwordx4 v34, s[28:29]
	s_add_i32 m0, s31, 0x2000
	s_add_u32 s34, s28, 0x80000
	s_addc_u32 s35, s29, 0
	s_add_i32 s25, s25, s33
	global_load_lds_dwordx4 v184, s[28:29]
	s_mov_b32 m0, s25
	s_nop 0
	global_load_lds_dwordx4 v34, s[34:35]
	s_add_i32 m0, s25, 0x2000
	s_nop 0
	global_load_lds_dwordx4 v184, s[34:35]
	s_mov_b32 m0, s50
	s_nop 0
	global_load_lds_dwordx4 v188, s[40:41]
	s_mov_b32 m0, s51
	s_nop 0
	global_load_lds_dwordx4 v186, s[40:41]
	s_waitcnt vmcnt(8) lgkmcnt(0)
	s_barrier
	s_setprio 1
	v_mfma_f32_16x16x32_bf16 v[2:5], v[132:135], v[164:167], 0
	v_mfma_f32_16x16x32_bf16 v[6:9], v[140:143], v[164:167], 0
	v_mfma_f32_16x16x32_bf16 v[18:21], v[132:135], v[168:171], 0
	v_mfma_f32_16x16x32_bf16 v[22:25], v[140:143], v[168:171], 0
	v_mfma_f32_16x16x32_bf16 v[36:39], v[132:135], v[190:193], 0
	v_mfma_f32_16x16x32_bf16 v[40:43], v[140:143], v[190:193], 0
	v_mfma_f32_16x16x32_bf16 v[52:55], v[132:135], v[194:197], 0
	v_mfma_f32_16x16x32_bf16 v[56:59], v[140:143], v[194:197], 0
	v_mfma_f32_16x16x32_bf16 v[2:5], v[136:139], v[172:175], v[2:5]
	v_mfma_f32_16x16x32_bf16 v[6:9], v[144:147], v[172:175], v[6:9]
	v_mfma_f32_16x16x32_bf16 v[18:21], v[136:139], v[176:179], v[18:21]
	v_mfma_f32_16x16x32_bf16 v[22:25], v[144:147], v[176:179], v[22:25]
	v_mfma_f32_16x16x32_bf16 v[36:39], v[136:139], v[198:201], v[36:39]
	v_mfma_f32_16x16x32_bf16 v[40:43], v[144:147], v[198:201], v[40:43]
	v_mfma_f32_16x16x32_bf16 v[52:55], v[136:139], v[232:235], v[52:55]
	v_mfma_f32_16x16x32_bf16 v[56:59], v[144:147], v[232:235], v[56:59]
	s_setprio 0
	s_setprio 1
	v_mfma_f32_16x16x32_bf16 v[10:13], v[148:151], v[164:167], 0
	v_mfma_f32_16x16x32_bf16 v[14:17], v[156:159], v[164:167], 0
	v_mfma_f32_16x16x32_bf16 v[26:29], v[148:151], v[168:171], 0
	v_mfma_f32_16x16x32_bf16 v[30:33], v[156:159], v[168:171], 0
	v_mfma_f32_16x16x32_bf16 v[44:47], v[148:151], v[190:193], 0
	v_mfma_f32_16x16x32_bf16 v[48:51], v[156:159], v[190:193], 0
	v_mfma_f32_16x16x32_bf16 v[60:63], v[148:151], v[194:197], 0
	v_mfma_f32_16x16x32_bf16 v[64:67], v[156:159], v[194:197], 0
	v_mfma_f32_16x16x32_bf16 v[10:13], v[152:155], v[172:175], v[10:13]
	v_mfma_f32_16x16x32_bf16 v[14:17], v[160:163], v[172:175], v[14:17]
	v_mfma_f32_16x16x32_bf16 v[26:29], v[152:155], v[176:179], v[26:29]
	v_mfma_f32_16x16x32_bf16 v[30:33], v[160:163], v[176:179], v[30:33]
	v_mfma_f32_16x16x32_bf16 v[44:47], v[152:155], v[198:201], v[44:47]
	v_mfma_f32_16x16x32_bf16 v[48:51], v[160:163], v[198:201], v[48:51]
	v_mfma_f32_16x16x32_bf16 v[60:63], v[152:155], v[232:235], v[60:63]
	v_mfma_f32_16x16x32_bf16 v[64:67], v[160:163], v[232:235], v[64:67]
	s_setprio 0
	s_barrier
	s_add_i32 s25, 0, 0x18000
	s_add_i32 s31, 0, 0x1c000
	ds_read_b128 v[132:135], v1 offset:32768
	ds_read_b128 v[136:139], v204 offset:32768
	ds_read_b128 v[140:143], v1 offset:34816
	ds_read_b128 v[144:147], v204 offset:34816
	ds_read_b128 v[148:151], v1 offset:49152
	ds_read_b128 v[152:155], v204 offset:49152
	ds_read_b128 v[156:159], v1 offset:51200
	ds_read_b128 v[160:163], v204 offset:51200
	s_add_u32 s34, s40, 0x80000
	s_addc_u32 s35, s41, 0
	s_mov_b32 m0, s52
	ds_read_b128 v[164:167], v205 offset:32768
	ds_read_b128 v[168:171], v205 offset:34816
	ds_read_b128 v[172:175], v206 offset:32768
	ds_read_b128 v[176:179], v206 offset:34816
	ds_read_b128 v[190:193], v205 offset:36864
	ds_read_b128 v[194:197], v205 offset:38912
	ds_read_b128 v[198:201], v206 offset:36864
	ds_read_b128 v[232:235], v206 offset:38912
	global_load_lds_dwordx4 v188, s[34:35]
	s_mov_b32 m0, s53
	s_nop 0
	global_load_lds_dwordx4 v186, s[34:35]
	s_waitcnt vmcnt(8) lgkmcnt(0)
	s_barrier
	s_setprio 1
	v_mfma_f32_16x16x32_bf16 v[68:71], v[132:135], v[164:167], v[68:71]
	v_mfma_f32_16x16x32_bf16 v[72:75], v[140:143], v[164:167], v[72:75]
	v_mfma_f32_16x16x32_bf16 v[84:87], v[132:135], v[168:171], v[84:87]
	v_mfma_f32_16x16x32_bf16 v[88:91], v[140:143], v[168:171], v[88:91]
	v_mfma_f32_16x16x32_bf16 v[100:103], v[132:135], v[190:193], v[100:103]
	v_mfma_f32_16x16x32_bf16 v[104:107], v[140:143], v[190:193], v[104:107]
	v_mfma_f32_16x16x32_bf16 v[116:119], v[132:135], v[194:197], v[116:119]
	v_mfma_f32_16x16x32_bf16 v[120:123], v[140:143], v[194:197], v[120:123]
	v_mfma_f32_16x16x32_bf16 v[68:71], v[136:139], v[172:175], v[68:71]
	v_mfma_f32_16x16x32_bf16 v[72:75], v[144:147], v[172:175], v[72:75]
	v_mfma_f32_16x16x32_bf16 v[84:87], v[136:139], v[176:179], v[84:87]
	v_mfma_f32_16x16x32_bf16 v[88:91], v[144:147], v[176:179], v[88:91]
	v_mfma_f32_16x16x32_bf16 v[100:103], v[136:139], v[198:201], v[100:103]
	v_mfma_f32_16x16x32_bf16 v[104:107], v[144:147], v[198:201], v[104:107]
	v_mfma_f32_16x16x32_bf16 v[116:119], v[136:139], v[232:235], v[116:119]
	v_mfma_f32_16x16x32_bf16 v[120:123], v[144:147], v[232:235], v[120:123]
	s_setprio 0
	s_setprio 1
	v_mfma_f32_16x16x32_bf16 v[76:79], v[148:151], v[164:167], v[76:79]
	v_mfma_f32_16x16x32_bf16 v[80:83], v[156:159], v[164:167], v[80:83]
	v_mfma_f32_16x16x32_bf16 v[92:95], v[148:151], v[168:171], v[92:95]
	v_mfma_f32_16x16x32_bf16 v[96:99], v[156:159], v[168:171], v[96:99]
	v_mfma_f32_16x16x32_bf16 v[108:111], v[148:151], v[190:193], v[108:111]
	v_mfma_f32_16x16x32_bf16 v[112:115], v[156:159], v[190:193], v[112:115]
	v_mfma_f32_16x16x32_bf16 v[124:127], v[148:151], v[194:197], v[124:127]
	v_mfma_f32_16x16x32_bf16 v[128:131], v[156:159], v[194:197], v[128:131]
	v_mfma_f32_16x16x32_bf16 v[76:79], v[152:155], v[172:175], v[76:79]
	v_mfma_f32_16x16x32_bf16 v[80:83], v[160:163], v[172:175], v[80:83]
	v_mfma_f32_16x16x32_bf16 v[92:95], v[152:155], v[176:179], v[92:95]
	v_mfma_f32_16x16x32_bf16 v[96:99], v[160:163], v[176:179], v[96:99]
	v_mfma_f32_16x16x32_bf16 v[108:111], v[152:155], v[198:201], v[108:111]
	v_mfma_f32_16x16x32_bf16 v[112:115], v[160:163], v[198:201], v[112:115]
	v_mfma_f32_16x16x32_bf16 v[124:127], v[152:155], v[232:235], v[124:127]
	v_mfma_f32_16x16x32_bf16 v[128:131], v[160:163], v[232:235], v[128:131]
	s_setprio 0
	s_barrier
	s_add_i32 s25, s25, s33
	s_add_i32 m0, s25, 0xffffff80
	ds_read_b128 v[164:167], v205 offset:49152
	ds_read_b128 v[168:171], v205 offset:51200
	ds_read_b128 v[172:175], v206 offset:49152
	ds_read_b128 v[176:179], v206 offset:51200
	ds_read_b128 v[190:193], v205 offset:53248
	ds_read_b128 v[194:197], v205 offset:55296
	ds_read_b128 v[198:201], v206 offset:53248
	ds_read_b128 v[232:235], v206 offset:55296
	global_load_lds_dwordx4 v34, s[28:29] offset:128
	s_add_i32 m0, s25, 0x1f80
	s_mov_b64 s[98:99], s[28:29]
	s_add_u32 s28, s28, 0x80080
	s_addc_u32 s29, s29, 0
	s_add_i32 s25, s31, s33
	global_load_lds_dwordx4 v184, s[98:99] offset:128
	s_mov_b32 m0, s25
	s_nop 0
	global_load_lds_dwordx4 v34, s[28:29]
	s_add_i32 m0, s25, 0x2000
	s_nop 0
	global_load_lds_dwordx4 v184, s[28:29]
	s_add_i32 m0, s54, 0xffffff80
	s_nop 0
	global_load_lds_dwordx4 v188, s[40:41] offset:128
	s_add_i32 m0, s55, 0xffffff80
	s_nop 0
	global_load_lds_dwordx4 v186, s[40:41] offset:128
	s_waitcnt vmcnt(8) lgkmcnt(0)
	s_barrier
	s_setprio 1
	v_mfma_f32_16x16x32_bf16 v[2:5], v[132:135], v[164:167], v[2:5]
	v_mfma_f32_16x16x32_bf16 v[6:9], v[140:143], v[164:167], v[6:9]
	v_mfma_f32_16x16x32_bf16 v[18:21], v[132:135], v[168:171], v[18:21]
	v_mfma_f32_16x16x32_bf16 v[22:25], v[140:143], v[168:171], v[22:25]
	v_mfma_f32_16x16x32_bf16 v[36:39], v[132:135], v[190:193], v[36:39]
	v_mfma_f32_16x16x32_bf16 v[40:43], v[140:143], v[190:193], v[40:43]
	v_mfma_f32_16x16x32_bf16 v[52:55], v[132:135], v[194:197], v[52:55]
	v_mfma_f32_16x16x32_bf16 v[56:59], v[140:143], v[194:197], v[56:59]
	v_mfma_f32_16x16x32_bf16 v[2:5], v[136:139], v[172:175], v[2:5]
	v_mfma_f32_16x16x32_bf16 v[6:9], v[144:147], v[172:175], v[6:9]
	v_mfma_f32_16x16x32_bf16 v[18:21], v[136:139], v[176:179], v[18:21]
	v_mfma_f32_16x16x32_bf16 v[22:25], v[144:147], v[176:179], v[22:25]
	v_mfma_f32_16x16x32_bf16 v[36:39], v[136:139], v[198:201], v[36:39]
	v_mfma_f32_16x16x32_bf16 v[40:43], v[144:147], v[198:201], v[40:43]
	v_mfma_f32_16x16x32_bf16 v[52:55], v[136:139], v[232:235], v[52:55]
	v_mfma_f32_16x16x32_bf16 v[56:59], v[144:147], v[232:235], v[56:59]
	s_setprio 0
	s_setprio 1
	v_mfma_f32_16x16x32_bf16 v[10:13], v[148:151], v[164:167], v[10:13]
	v_mfma_f32_16x16x32_bf16 v[14:17], v[156:159], v[164:167], v[14:17]
	v_mfma_f32_16x16x32_bf16 v[26:29], v[148:151], v[168:171], v[26:29]
	v_mfma_f32_16x16x32_bf16 v[30:33], v[156:159], v[168:171], v[30:33]
	v_mfma_f32_16x16x32_bf16 v[44:47], v[148:151], v[190:193], v[44:47]
	v_mfma_f32_16x16x32_bf16 v[48:51], v[156:159], v[190:193], v[48:51]
	v_mfma_f32_16x16x32_bf16 v[60:63], v[148:151], v[194:197], v[60:63]
	v_mfma_f32_16x16x32_bf16 v[64:67], v[156:159], v[194:197], v[64:67]
	v_mfma_f32_16x16x32_bf16 v[10:13], v[152:155], v[172:175], v[10:13]
	v_mfma_f32_16x16x32_bf16 v[14:17], v[160:163], v[172:175], v[14:17]
	v_mfma_f32_16x16x32_bf16 v[26:29], v[152:155], v[176:179], v[26:29]
	v_mfma_f32_16x16x32_bf16 v[30:33], v[160:163], v[176:179], v[30:33]
	v_mfma_f32_16x16x32_bf16 v[44:47], v[152:155], v[198:201], v[44:47]
	v_mfma_f32_16x16x32_bf16 v[48:51], v[160:163], v[198:201], v[48:51]
	v_mfma_f32_16x16x32_bf16 v[60:63], v[152:155], v[232:235], v[60:63]
	v_mfma_f32_16x16x32_bf16 v[64:67], v[160:163], v[232:235], v[64:67]
	s_setprio 0
	s_barrier
	s_add_u32 s22, s22, 0x100
	s_addc_u32 s23, s23, 0
	s_add_u32 s21, s21, 0x100
	s_addc_u32 s24, s24, 0
	s_cmp_ge_u32 s30, s9
	s_mov_b32 s25, s30
	s_cbranch_scc1 .Lpeel_done_P3
.LBB0_908:
	s_add_i32 s30, s25, 2
	s_add_u32 s28, s22, 0xfff80080
	s_addc_u32 s29, s23, -1
	s_add_i32 s31, 0, 0x10000
	s_cmp_eq_u32 s20, s25
	s_cselect_b32 s41, s47, s29
	s_cselect_b32 s40, s46, s28
	s_cselect_b32 s29, s49, s24
	s_cselect_b32 s28, s48, s21
	s_add_i32 s25, 0, 0x14000
	ds_read_b128 v[132:135], v1
	ds_read_b128 v[136:139], v204
	ds_read_b128 v[140:143], v1 offset:2048
	ds_read_b128 v[144:147], v204 offset:2048
	ds_read_b128 v[148:151], v1 offset:16384
	ds_read_b128 v[152:155], v204 offset:16384
	ds_read_b128 v[156:159], v1 offset:18432
	ds_read_b128 v[160:163], v204 offset:18432
	s_add_i32 m0, s50, 0xc000
	ds_read_b128 v[164:167], v205
	ds_read_b128 v[168:171], v205 offset:2048
	ds_read_b128 v[172:175], v206
	ds_read_b128 v[176:179], v206 offset:2048
	ds_read_b128 v[190:193], v205 offset:4096
	ds_read_b128 v[194:197], v205 offset:6144
	ds_read_b128 v[198:201], v206 offset:4096
	ds_read_b128 v[232:235], v206 offset:6144
	global_load_lds_dwordx4 v188, s[22:23]
	s_add_i32 m0, s50, 0xe000
	s_nop 0
	global_load_lds_dwordx4 v186, s[22:23]
	s_waitcnt vmcnt(8) lgkmcnt(0)
	s_barrier
	s_setprio 1
	v_mfma_f32_16x16x32_bf16 v[68:71], v[132:135], v[164:167], v[68:71]
	v_mfma_f32_16x16x32_bf16 v[72:75], v[140:143], v[164:167], v[72:75]
	v_mfma_f32_16x16x32_bf16 v[84:87], v[132:135], v[168:171], v[84:87]
	v_mfma_f32_16x16x32_bf16 v[88:91], v[140:143], v[168:171], v[88:91]
	v_mfma_f32_16x16x32_bf16 v[100:103], v[132:135], v[190:193], v[100:103]
	v_mfma_f32_16x16x32_bf16 v[104:107], v[140:143], v[190:193], v[104:107]
	v_mfma_f32_16x16x32_bf16 v[116:119], v[132:135], v[194:197], v[116:119]
	v_mfma_f32_16x16x32_bf16 v[120:123], v[140:143], v[194:197], v[120:123]
	v_mfma_f32_16x16x32_bf16 v[68:71], v[136:139], v[172:175], v[68:71]
	v_mfma_f32_16x16x32_bf16 v[72:75], v[144:147], v[172:175], v[72:75]
	v_mfma_f32_16x16x32_bf16 v[84:87], v[136:139], v[176:179], v[84:87]
	v_mfma_f32_16x16x32_bf16 v[88:91], v[144:147], v[176:179], v[88:91]
	v_mfma_f32_16x16x32_bf16 v[100:103], v[136:139], v[198:201], v[100:103]
	v_mfma_f32_16x16x32_bf16 v[104:107], v[144:147], v[198:201], v[104:107]
	v_mfma_f32_16x16x32_bf16 v[116:119], v[136:139], v[232:235], v[116:119]
	v_mfma_f32_16x16x32_bf16 v[120:123], v[144:147], v[232:235], v[120:123]
	s_setprio 0
	s_setprio 1
	v_mfma_f32_16x16x32_bf16 v[76:79], v[148:151], v[164:167], v[76:79]
	v_mfma_f32_16x16x32_bf16 v[80:83], v[156:159], v[164:167], v[80:83]
	v_mfma_f32_16x16x32_bf16 v[92:95], v[148:151], v[168:171], v[92:95]
	v_mfma_f32_16x16x32_bf16 v[96:99], v[156:159], v[168:171], v[96:99]
	v_mfma_f32_16x16x32_bf16 v[108:111], v[148:151], v[190:193], v[108:111]
	v_mfma_f32_16x16x32_bf16 v[112:115], v[156:159], v[190:193], v[112:115]
	v_mfma_f32_16x16x32_bf16 v[124:127], v[148:151], v[194:197], v[124:127]
	v_mfma_f32_16x16x32_bf16 v[128:131], v[156:159], v[194:197], v[128:131]
	v_mfma_f32_16x16x32_bf16 v[76:79], v[152:155], v[172:175], v[76:79]
	v_mfma_f32_16x16x32_bf16 v[80:83], v[160:163], v[172:175], v[80:83]
	v_mfma_f32_16x16x32_bf16 v[92:95], v[152:155], v[176:179], v[92:95]
	v_mfma_f32_16x16x32_bf16 v[96:99], v[160:163], v[176:179], v[96:99]
	v_mfma_f32_16x16x32_bf16 v[108:111], v[152:155], v[198:201], v[108:111]
	v_mfma_f32_16x16x32_bf16 v[112:115], v[160:163], v[198:201], v[112:115]
	v_mfma_f32_16x16x32_bf16 v[124:127], v[152:155], v[232:235], v[124:127]
	v_mfma_f32_16x16x32_bf16 v[128:131], v[160:163], v[232:235], v[128:131]
	s_setprio 0
	s_barrier
	s_add_i32 s31, s31, s33
	s_mov_b32 m0, s31
	ds_read_b128 v[164:167], v205 offset:16384
	ds_read_b128 v[168:171], v205 offset:18432
	ds_read_b128 v[172:175], v206 offset:16384
	ds_read_b128 v[176:179], v206 offset:18432
	ds_read_b128 v[190:193], v205 offset:20480
	ds_read_b128 v[194:197], v205 offset:22528
	ds_read_b128 v[198:201], v206 offset:20480
	ds_read_b128 v[232:235], v206 offset:22528
	global_load_lds_dwordx4 v34, s[28:29]
	s_add_i32 m0, s31, 0x2000
	s_add_u32 s34, s28, 0x80000
	s_addc_u32 s35, s29, 0
	s_add_i32 s25, s25, s33
	global_load_lds_dwordx4 v184, s[28:29]
	s_mov_b32 m0, s25
	s_nop 0
	global_load_lds_dwordx4 v34, s[34:35]
	s_add_i32 m0, s25, 0x2000
	s_nop 0
	global_load_lds_dwordx4 v184, s[34:35]
	s_mov_b32 m0, s50
	s_nop 0
	global_load_lds_dwordx4 v188, s[40:41]
	s_mov_b32 m0, s51
	s_nop 0
	global_load_lds_dwordx4 v186, s[40:41]
	s_waitcnt vmcnt(8) lgkmcnt(0)
	s_barrier
	s_setprio 1
	v_mfma_f32_16x16x32_bf16 v[2:5], v[132:135], v[164:167], v[2:5]
	v_mfma_f32_16x16x32_bf16 v[6:9], v[140:143], v[164:167], v[6:9]
	v_mfma_f32_16x16x32_bf16 v[18:21], v[132:135], v[168:171], v[18:21]
	v_mfma_f32_16x16x32_bf16 v[22:25], v[140:143], v[168:171], v[22:25]
	v_mfma_f32_16x16x32_bf16 v[36:39], v[132:135], v[190:193], v[36:39]
	v_mfma_f32_16x16x32_bf16 v[40:43], v[140:143], v[190:193], v[40:43]
	v_mfma_f32_16x16x32_bf16 v[52:55], v[132:135], v[194:197], v[52:55]
	v_mfma_f32_16x16x32_bf16 v[56:59], v[140:143], v[194:197], v[56:59]
	v_mfma_f32_16x16x32_bf16 v[2:5], v[136:139], v[172:175], v[2:5]
	v_mfma_f32_16x16x32_bf16 v[6:9], v[144:147], v[172:175], v[6:9]
	v_mfma_f32_16x16x32_bf16 v[18:21], v[136:139], v[176:179], v[18:21]
	v_mfma_f32_16x16x32_bf16 v[22:25], v[144:147], v[176:179], v[22:25]
	v_mfma_f32_16x16x32_bf16 v[36:39], v[136:139], v[198:201], v[36:39]
	v_mfma_f32_16x16x32_bf16 v[40:43], v[144:147], v[198:201], v[40:43]
	v_mfma_f32_16x16x32_bf16 v[52:55], v[136:139], v[232:235], v[52:55]
	v_mfma_f32_16x16x32_bf16 v[56:59], v[144:147], v[232:235], v[56:59]
	s_setprio 0
	s_setprio 1
	v_mfma_f32_16x16x32_bf16 v[10:13], v[148:151], v[164:167], v[10:13]
	v_mfma_f32_16x16x32_bf16 v[14:17], v[156:159], v[164:167], v[14:17]
	v_mfma_f32_16x16x32_bf16 v[26:29], v[148:151], v[168:171], v[26:29]
	v_mfma_f32_16x16x32_bf16 v[30:33], v[156:159], v[168:171], v[30:33]
	v_mfma_f32_16x16x32_bf16 v[44:47], v[148:151], v[190:193], v[44:47]
	v_mfma_f32_16x16x32_bf16 v[48:51], v[156:159], v[190:193], v[48:51]
	v_mfma_f32_16x16x32_bf16 v[60:63], v[148:151], v[194:197], v[60:63]
	v_mfma_f32_16x16x32_bf16 v[64:67], v[156:159], v[194:197], v[64:67]
	v_mfma_f32_16x16x32_bf16 v[10:13], v[152:155], v[172:175], v[10:13]
	v_mfma_f32_16x16x32_bf16 v[14:17], v[160:163], v[172:175], v[14:17]
	v_mfma_f32_16x16x32_bf16 v[26:29], v[152:155], v[176:179], v[26:29]
	v_mfma_f32_16x16x32_bf16 v[30:33], v[160:163], v[176:179], v[30:33]
	v_mfma_f32_16x16x32_bf16 v[44:47], v[152:155], v[198:201], v[44:47]
	v_mfma_f32_16x16x32_bf16 v[48:51], v[160:163], v[198:201], v[48:51]
	v_mfma_f32_16x16x32_bf16 v[60:63], v[152:155], v[232:235], v[60:63]
	v_mfma_f32_16x16x32_bf16 v[64:67], v[160:163], v[232:235], v[64:67]
	s_setprio 0
	s_barrier
	s_add_i32 s25, 0, 0x18000
	s_add_i32 s31, 0, 0x1c000
	ds_read_b128 v[132:135], v1 offset:32768
	ds_read_b128 v[136:139], v204 offset:32768
	ds_read_b128 v[140:143], v1 offset:34816
	ds_read_b128 v[144:147], v204 offset:34816
	ds_read_b128 v[148:151], v1 offset:49152
	ds_read_b128 v[152:155], v204 offset:49152
	ds_read_b128 v[156:159], v1 offset:51200
	ds_read_b128 v[160:163], v204 offset:51200
	s_add_u32 s34, s40, 0x80000
	s_addc_u32 s35, s41, 0
	s_mov_b32 m0, s52
	ds_read_b128 v[164:167], v205 offset:32768
	ds_read_b128 v[168:171], v205 offset:34816
	ds_read_b128 v[172:175], v206 offset:32768
	ds_read_b128 v[176:179], v206 offset:34816
	ds_read_b128 v[190:193], v205 offset:36864
	ds_read_b128 v[194:197], v205 offset:38912
	ds_read_b128 v[198:201], v206 offset:36864
	ds_read_b128 v[232:235], v206 offset:38912
	global_load_lds_dwordx4 v188, s[34:35]
	s_mov_b32 m0, s53
	s_nop 0
	global_load_lds_dwordx4 v186, s[34:35]
	s_waitcnt vmcnt(8) lgkmcnt(0)
	s_barrier
	s_setprio 1
	v_mfma_f32_16x16x32_bf16 v[68:71], v[132:135], v[164:167], v[68:71]
	v_mfma_f32_16x16x32_bf16 v[72:75], v[140:143], v[164:167], v[72:75]
	v_mfma_f32_16x16x32_bf16 v[84:87], v[132:135], v[168:171], v[84:87]
	v_mfma_f32_16x16x32_bf16 v[88:91], v[140:143], v[168:171], v[88:91]
	v_mfma_f32_16x16x32_bf16 v[100:103], v[132:135], v[190:193], v[100:103]
	v_mfma_f32_16x16x32_bf16 v[104:107], v[140:143], v[190:193], v[104:107]
	v_mfma_f32_16x16x32_bf16 v[116:119], v[132:135], v[194:197], v[116:119]
	v_mfma_f32_16x16x32_bf16 v[120:123], v[140:143], v[194:197], v[120:123]
	v_mfma_f32_16x16x32_bf16 v[68:71], v[136:139], v[172:175], v[68:71]
	v_mfma_f32_16x16x32_bf16 v[72:75], v[144:147], v[172:175], v[72:75]
	v_mfma_f32_16x16x32_bf16 v[84:87], v[136:139], v[176:179], v[84:87]
	v_mfma_f32_16x16x32_bf16 v[88:91], v[144:147], v[176:179], v[88:91]
	v_mfma_f32_16x16x32_bf16 v[100:103], v[136:139], v[198:201], v[100:103]
	v_mfma_f32_16x16x32_bf16 v[104:107], v[144:147], v[198:201], v[104:107]
	v_mfma_f32_16x16x32_bf16 v[116:119], v[136:139], v[232:235], v[116:119]
	v_mfma_f32_16x16x32_bf16 v[120:123], v[144:147], v[232:235], v[120:123]
	s_setprio 0
	s_setprio 1
	v_mfma_f32_16x16x32_bf16 v[76:79], v[148:151], v[164:167], v[76:79]
	v_mfma_f32_16x16x32_bf16 v[80:83], v[156:159], v[164:167], v[80:83]
	v_mfma_f32_16x16x32_bf16 v[92:95], v[148:151], v[168:171], v[92:95]
	v_mfma_f32_16x16x32_bf16 v[96:99], v[156:159], v[168:171], v[96:99]
	v_mfma_f32_16x16x32_bf16 v[108:111], v[148:151], v[190:193], v[108:111]
	v_mfma_f32_16x16x32_bf16 v[112:115], v[156:159], v[190:193], v[112:115]
	v_mfma_f32_16x16x32_bf16 v[124:127], v[148:151], v[194:197], v[124:127]
	v_mfma_f32_16x16x32_bf16 v[128:131], v[156:159], v[194:197], v[128:131]
	v_mfma_f32_16x16x32_bf16 v[76:79], v[152:155], v[172:175], v[76:79]
	v_mfma_f32_16x16x32_bf16 v[80:83], v[160:163], v[172:175], v[80:83]
	v_mfma_f32_16x16x32_bf16 v[92:95], v[152:155], v[176:179], v[92:95]
	v_mfma_f32_16x16x32_bf16 v[96:99], v[160:163], v[176:179], v[96:99]
	v_mfma_f32_16x16x32_bf16 v[108:111], v[152:155], v[198:201], v[108:111]
	v_mfma_f32_16x16x32_bf16 v[112:115], v[160:163], v[198:201], v[112:115]
	v_mfma_f32_16x16x32_bf16 v[124:127], v[152:155], v[232:235], v[124:127]
	v_mfma_f32_16x16x32_bf16 v[128:131], v[160:163], v[232:235], v[128:131]
	s_setprio 0
	s_barrier
	s_add_i32 s25, s25, s33
	s_add_i32 m0, s25, 0xffffff80
	ds_read_b128 v[164:167], v205 offset:49152
	ds_read_b128 v[168:171], v205 offset:51200
	ds_read_b128 v[172:175], v206 offset:49152
	ds_read_b128 v[176:179], v206 offset:51200
	ds_read_b128 v[190:193], v205 offset:53248
	ds_read_b128 v[194:197], v205 offset:55296
	ds_read_b128 v[198:201], v206 offset:53248
	ds_read_b128 v[232:235], v206 offset:55296
	global_load_lds_dwordx4 v34, s[28:29] offset:128
	s_add_i32 m0, s25, 0x1f80
	s_mov_b64 s[98:99], s[28:29]
	s_add_u32 s28, s28, 0x80080
	s_addc_u32 s29, s29, 0
	s_add_i32 s25, s31, s33
	global_load_lds_dwordx4 v184, s[98:99] offset:128
	s_mov_b32 m0, s25
	s_nop 0
	global_load_lds_dwordx4 v34, s[28:29]
	s_add_i32 m0, s25, 0x2000
	s_nop 0
	global_load_lds_dwordx4 v184, s[28:29]
	s_add_i32 m0, s54, 0xffffff80
	s_nop 0
	global_load_lds_dwordx4 v188, s[40:41] offset:128
	s_add_i32 m0, s55, 0xffffff80
	s_nop 0
	global_load_lds_dwordx4 v186, s[40:41] offset:128
	s_waitcnt vmcnt(8) lgkmcnt(0)
	s_barrier
	s_setprio 1
	v_mfma_f32_16x16x32_bf16 v[2:5], v[132:135], v[164:167], v[2:5]
	v_mfma_f32_16x16x32_bf16 v[6:9], v[140:143], v[164:167], v[6:9]
	v_mfma_f32_16x16x32_bf16 v[18:21], v[132:135], v[168:171], v[18:21]
	v_mfma_f32_16x16x32_bf16 v[22:25], v[140:143], v[168:171], v[22:25]
	v_mfma_f32_16x16x32_bf16 v[36:39], v[132:135], v[190:193], v[36:39]
	v_mfma_f32_16x16x32_bf16 v[40:43], v[140:143], v[190:193], v[40:43]
	v_mfma_f32_16x16x32_bf16 v[52:55], v[132:135], v[194:197], v[52:55]
	v_mfma_f32_16x16x32_bf16 v[56:59], v[140:143], v[194:197], v[56:59]
	v_mfma_f32_16x16x32_bf16 v[2:5], v[136:139], v[172:175], v[2:5]
	v_mfma_f32_16x16x32_bf16 v[6:9], v[144:147], v[172:175], v[6:9]
	v_mfma_f32_16x16x32_bf16 v[18:21], v[136:139], v[176:179], v[18:21]
	v_mfma_f32_16x16x32_bf16 v[22:25], v[144:147], v[176:179], v[22:25]
	v_mfma_f32_16x16x32_bf16 v[36:39], v[136:139], v[198:201], v[36:39]
	v_mfma_f32_16x16x32_bf16 v[40:43], v[144:147], v[198:201], v[40:43]
	v_mfma_f32_16x16x32_bf16 v[52:55], v[136:139], v[232:235], v[52:55]
	v_mfma_f32_16x16x32_bf16 v[56:59], v[144:147], v[232:235], v[56:59]
	s_setprio 0
	s_setprio 1
	v_mfma_f32_16x16x32_bf16 v[10:13], v[148:151], v[164:167], v[10:13]
	v_mfma_f32_16x16x32_bf16 v[14:17], v[156:159], v[164:167], v[14:17]
	v_mfma_f32_16x16x32_bf16 v[26:29], v[148:151], v[168:171], v[26:29]
	v_mfma_f32_16x16x32_bf16 v[30:33], v[156:159], v[168:171], v[30:33]
	v_mfma_f32_16x16x32_bf16 v[44:47], v[148:151], v[190:193], v[44:47]
	v_mfma_f32_16x16x32_bf16 v[48:51], v[156:159], v[190:193], v[48:51]
	v_mfma_f32_16x16x32_bf16 v[60:63], v[148:151], v[194:197], v[60:63]
	v_mfma_f32_16x16x32_bf16 v[64:67], v[156:159], v[194:197], v[64:67]
	v_mfma_f32_16x16x32_bf16 v[10:13], v[152:155], v[172:175], v[10:13]
	v_mfma_f32_16x16x32_bf16 v[14:17], v[160:163], v[172:175], v[14:17]
	v_mfma_f32_16x16x32_bf16 v[26:29], v[152:155], v[176:179], v[26:29]
	v_mfma_f32_16x16x32_bf16 v[30:33], v[160:163], v[176:179], v[30:33]
	v_mfma_f32_16x16x32_bf16 v[44:47], v[152:155], v[198:201], v[44:47]
	v_mfma_f32_16x16x32_bf16 v[48:51], v[160:163], v[198:201], v[48:51]
	v_mfma_f32_16x16x32_bf16 v[60:63], v[152:155], v[232:235], v[60:63]
	v_mfma_f32_16x16x32_bf16 v[64:67], v[160:163], v[232:235], v[64:67]
	s_setprio 0
	s_barrier
	s_add_u32 s22, s22, 0x100
	s_addc_u32 s23, s23, 0
	s_add_u32 s21, s21, 0x100
	s_addc_u32 s24, s24, 0
	s_cmp_ge_u32 s30, s9
	s_mov_b32 s25, s30
	s_cbranch_scc0 .LBB0_908

.LBB0_1022:
	s_ashr_i32 s23, s22, 31
	s_lshl_b64 s[12:13], s[22:23], 20
	v_readlane_b32 s20, v254, 52
	v_readlane_b32 s21, v254, 53
	s_add_u32 s40, s20, s12
	s_addc_u32 s41, s21, s13
	s_and_b64 s[12:13], s[38:39], exec
	s_cselect_b32 s12, s41, s9
	s_cselect_b32 s13, s40, s8
	s_ashr_i32 s19, s18, 31
	s_lshl_b64 s[20:21], s[18:19], 20
	v_readlane_b32 s24, v254, 48
	v_readlane_b32 s25, v254, 49
	s_add_u32 s42, s24, s20
	s_addc_u32 s43, s25, s21
	s_and_b64 s[20:21], s[38:39], exec
	s_cselect_b32 s19, s43, s29
	s_cselect_b32 s20, s42, s28
	s_add_u32 s8, s8, 0x80080
	s_addc_u32 s9, s9, 0
	s_add_u32 s21, s28, 0x100
	s_addc_u32 s23, s29, 0
	s_mov_b32 s24, -2
	v_readlane_b32 s35, v255, 20
	v_readlane_b32 s57, v255, 21
	v_readlane_b32 s58, v255, 22
	v_readlane_b32 s59, v255, 23
	s_mov_b64 s[60:61], 0x80
	s_add_u32 s25, s8, 0xfff80080
	s_addc_u32 s28, s9, -1
	s_add_i32 s30, 0, 0x10000
	s_cmp_eq_u32 s24, 28
	s_cselect_b32 s45, s12, s28
	s_cselect_b32 s44, s13, s25
	s_cselect_b32 s29, s19, s23
	s_cselect_b32 s28, s20, s21
	s_add_i32 s25, 0, 0x14000
	ds_read_b128 v[138:141], v1
	ds_read_b128 v[142:145], v150
	ds_read_b128 v[146:149], v1 offset:2048
	ds_read_b128 v[154:157], v150 offset:2048
	ds_read_b128 v[158:161], v1 offset:16384
	ds_read_b128 v[162:165], v150 offset:16384
	ds_read_b128 v[166:169], v1 offset:18432
	ds_read_b128 v[170:173], v150 offset:18432
	s_add_i32 m0, s46, 0xc000
	ds_read_b128 v[174:177], v151
	ds_read_b128 v[184:187], v151 offset:2048
	ds_read_b128 v[188:191], v152
	ds_read_b128 v[192:195], v152 offset:2048
	ds_read_b128 v[196:199], v151 offset:4096
	ds_read_b128 v[200:203], v151 offset:6144
	ds_read_b128 v[204:207], v152 offset:4096
	ds_read_b128 v[208:211], v152 offset:6144
	global_load_lds_dwordx4 v136, s[8:9]
	s_add_i32 m0, s46, 0xe000
	s_nop 0
	global_load_lds_dwordx4 v134, s[8:9]
	s_waitcnt vmcnt(8) lgkmcnt(0)
	s_barrier
	s_setprio 1
	v_mfma_f32_16x16x32_bf16 v[128:131], v[138:141], v[174:177], 0
	v_mfma_f32_16x16x32_bf16 v[124:127], v[146:149], v[174:177], 0
	v_mfma_f32_16x16x32_bf16 v[112:115], v[138:141], v[184:187], 0
	v_mfma_f32_16x16x32_bf16 v[108:111], v[146:149], v[184:187], 0
	v_mfma_f32_16x16x32_bf16 v[96:99], v[138:141], v[196:199], 0
	v_mfma_f32_16x16x32_bf16 v[92:95], v[146:149], v[196:199], 0
	v_mfma_f32_16x16x32_bf16 v[80:83], v[138:141], v[200:203], 0
	v_mfma_f32_16x16x32_bf16 v[76:79], v[146:149], v[200:203], 0
	v_mfma_f32_16x16x32_bf16 v[128:131], v[142:145], v[188:191], v[128:131]
	v_mfma_f32_16x16x32_bf16 v[124:127], v[154:157], v[188:191], v[124:127]
	v_mfma_f32_16x16x32_bf16 v[112:115], v[142:145], v[192:195], v[112:115]
	v_mfma_f32_16x16x32_bf16 v[108:111], v[154:157], v[192:195], v[108:111]
	v_mfma_f32_16x16x32_bf16 v[96:99], v[142:145], v[204:207], v[96:99]
	v_mfma_f32_16x16x32_bf16 v[92:95], v[154:157], v[204:207], v[92:95]
	v_mfma_f32_16x16x32_bf16 v[80:83], v[142:145], v[208:211], v[80:83]
	v_mfma_f32_16x16x32_bf16 v[76:79], v[154:157], v[208:211], v[76:79]
	s_setprio 0
	s_setprio 1
	v_mfma_f32_16x16x32_bf16 v[120:123], v[158:161], v[174:177], 0
	v_mfma_f32_16x16x32_bf16 v[116:119], v[166:169], v[174:177], 0
	v_mfma_f32_16x16x32_bf16 v[104:107], v[158:161], v[184:187], 0
	v_mfma_f32_16x16x32_bf16 v[100:103], v[166:169], v[184:187], 0
	v_mfma_f32_16x16x32_bf16 v[88:91], v[158:161], v[196:199], 0
	v_mfma_f32_16x16x32_bf16 v[84:87], v[166:169], v[196:199], 0
	v_mfma_f32_16x16x32_bf16 v[72:75], v[158:161], v[200:203], 0
	v_mfma_f32_16x16x32_bf16 v[68:71], v[166:169], v[200:203], 0
	v_mfma_f32_16x16x32_bf16 v[120:123], v[162:165], v[188:191], v[120:123]
	v_mfma_f32_16x16x32_bf16 v[116:119], v[170:173], v[188:191], v[116:119]
	v_mfma_f32_16x16x32_bf16 v[104:107], v[162:165], v[192:195], v[104:107]
	v_mfma_f32_16x16x32_bf16 v[100:103], v[170:173], v[192:195], v[100:103]
	v_mfma_f32_16x16x32_bf16 v[88:91], v[162:165], v[204:207], v[88:91]
	v_mfma_f32_16x16x32_bf16 v[84:87], v[170:173], v[204:207], v[84:87]
	v_mfma_f32_16x16x32_bf16 v[72:75], v[162:165], v[208:211], v[72:75]
	v_mfma_f32_16x16x32_bf16 v[68:71], v[170:173], v[208:211], v[68:71]
	s_setprio 0
	s_barrier
	s_add_i32 s30, s30, s33
	s_mov_b32 m0, s30
	ds_read_b128 v[174:177], v151 offset:16384
	ds_read_b128 v[184:187], v151 offset:18432
	ds_read_b128 v[188:191], v152 offset:16384
	ds_read_b128 v[192:195], v152 offset:18432
	ds_read_b128 v[196:199], v151 offset:20480
	ds_read_b128 v[200:203], v151 offset:22528
	ds_read_b128 v[204:207], v152 offset:20480
	ds_read_b128 v[208:211], v152 offset:22528
	global_load_lds_dwordx4 v34, s[28:29]
	s_add_i32 m0, s30, 0x2000
	s_add_u32 s30, s28, 0x80000
	s_addc_u32 s31, s29, 0
	s_add_i32 s25, s25, s33
	global_load_lds_dwordx4 v132, s[28:29]
	s_mov_b32 m0, s25
	s_nop 0
	global_load_lds_dwordx4 v34, s[30:31]
	s_add_i32 m0, s25, 0x2000
	s_nop 0
	global_load_lds_dwordx4 v132, s[30:31]
	s_mov_b32 m0, s46
	s_nop 0
	global_load_lds_dwordx4 v136, s[44:45]
	s_mov_b32 m0, s47
	s_nop 0
	global_load_lds_dwordx4 v134, s[44:45]
	s_waitcnt vmcnt(8) lgkmcnt(0)
	s_barrier
	s_setprio 1
	v_mfma_f32_16x16x32_bf16 v[64:67], v[138:141], v[174:177], 0
	v_mfma_f32_16x16x32_bf16 v[60:63], v[146:149], v[174:177], 0
	v_mfma_f32_16x16x32_bf16 v[48:51], v[138:141], v[184:187], 0
	v_mfma_f32_16x16x32_bf16 v[44:47], v[146:149], v[184:187], 0
	v_mfma_f32_16x16x32_bf16 v[30:33], v[138:141], v[196:199], 0
	v_mfma_f32_16x16x32_bf16 v[26:29], v[146:149], v[196:199], 0
	v_mfma_f32_16x16x32_bf16 v[14:17], v[138:141], v[200:203], 0
	v_mfma_f32_16x16x32_bf16 v[10:13], v[146:149], v[200:203], 0
	v_mfma_f32_16x16x32_bf16 v[64:67], v[142:145], v[188:191], v[64:67]
	v_mfma_f32_16x16x32_bf16 v[60:63], v[154:157], v[188:191], v[60:63]
	v_mfma_f32_16x16x32_bf16 v[48:51], v[142:145], v[192:195], v[48:51]
	v_mfma_f32_16x16x32_bf16 v[44:47], v[154:157], v[192:195], v[44:47]
	v_mfma_f32_16x16x32_bf16 v[30:33], v[142:145], v[204:207], v[30:33]
	v_mfma_f32_16x16x32_bf16 v[26:29], v[154:157], v[204:207], v[26:29]
	v_mfma_f32_16x16x32_bf16 v[14:17], v[142:145], v[208:211], v[14:17]
	v_mfma_f32_16x16x32_bf16 v[10:13], v[154:157], v[208:211], v[10:13]
	s_setprio 0
	s_setprio 1
	v_mfma_f32_16x16x32_bf16 v[56:59], v[158:161], v[174:177], 0
	v_mfma_f32_16x16x32_bf16 v[52:55], v[166:169], v[174:177], 0
	v_mfma_f32_16x16x32_bf16 v[40:43], v[158:161], v[184:187], 0
	v_mfma_f32_16x16x32_bf16 v[36:39], v[166:169], v[184:187], 0
	v_mfma_f32_16x16x32_bf16 v[22:25], v[158:161], v[196:199], 0
	v_mfma_f32_16x16x32_bf16 v[18:21], v[166:169], v[196:199], 0
	v_mfma_f32_16x16x32_bf16 v[6:9], v[158:161], v[200:203], 0
	v_mfma_f32_16x16x32_bf16 v[2:5], v[166:169], v[200:203], 0
	v_mfma_f32_16x16x32_bf16 v[56:59], v[162:165], v[188:191], v[56:59]
	v_mfma_f32_16x16x32_bf16 v[52:55], v[170:173], v[188:191], v[52:55]
	v_mfma_f32_16x16x32_bf16 v[40:43], v[162:165], v[192:195], v[40:43]
	v_mfma_f32_16x16x32_bf16 v[36:39], v[170:173], v[192:195], v[36:39]
	v_mfma_f32_16x16x32_bf16 v[22:25], v[162:165], v[204:207], v[22:25]
	v_mfma_f32_16x16x32_bf16 v[18:21], v[170:173], v[204:207], v[18:21]
	v_mfma_f32_16x16x32_bf16 v[6:9], v[162:165], v[208:211], v[6:9]
	v_mfma_f32_16x16x32_bf16 v[2:5], v[170:173], v[208:211], v[2:5]
	s_setprio 0
	s_barrier
	s_add_i32 s25, 0, 0x18000
	s_add_i32 s34, 0, 0x1c000
	ds_read_b128 v[138:141], v1 offset:32768
	ds_read_b128 v[142:145], v150 offset:32768
	ds_read_b128 v[146:149], v1 offset:34816
	ds_read_b128 v[154:157], v150 offset:34816
	ds_read_b128 v[158:161], v1 offset:49152
	ds_read_b128 v[162:165], v150 offset:49152
	ds_read_b128 v[166:169], v1 offset:51200
	ds_read_b128 v[170:173], v150 offset:51200
	s_add_u32 s30, s44, 0x80000
	s_addc_u32 s31, s45, 0
	s_mov_b32 m0, s48
	ds_read_b128 v[174:177], v151 offset:32768
	ds_read_b128 v[184:187], v151 offset:34816
	ds_read_b128 v[188:191], v152 offset:32768
	ds_read_b128 v[192:195], v152 offset:34816
	ds_read_b128 v[196:199], v151 offset:36864
	ds_read_b128 v[200:203], v151 offset:38912
	ds_read_b128 v[204:207], v152 offset:36864
	ds_read_b128 v[208:211], v152 offset:38912
	global_load_lds_dwordx4 v136, s[30:31]
	s_mov_b32 m0, s49
	s_nop 0
	global_load_lds_dwordx4 v134, s[30:31]
	s_waitcnt vmcnt(8) lgkmcnt(0)
	s_barrier
	s_setprio 1
	v_mfma_f32_16x16x32_bf16 v[128:131], v[138:141], v[174:177], v[128:131]
	v_mfma_f32_16x16x32_bf16 v[124:127], v[146:149], v[174:177], v[124:127]
	v_mfma_f32_16x16x32_bf16 v[112:115], v[138:141], v[184:187], v[112:115]
	v_mfma_f32_16x16x32_bf16 v[108:111], v[146:149], v[184:187], v[108:111]
	v_mfma_f32_16x16x32_bf16 v[96:99], v[138:141], v[196:199], v[96:99]
	v_mfma_f32_16x16x32_bf16 v[92:95], v[146:149], v[196:199], v[92:95]
	v_mfma_f32_16x16x32_bf16 v[80:83], v[138:141], v[200:203], v[80:83]
	v_mfma_f32_16x16x32_bf16 v[76:79], v[146:149], v[200:203], v[76:79]
	v_mfma_f32_16x16x32_bf16 v[128:131], v[142:145], v[188:191], v[128:131]
	v_mfma_f32_16x16x32_bf16 v[124:127], v[154:157], v[188:191], v[124:127]
	v_mfma_f32_16x16x32_bf16 v[112:115], v[142:145], v[192:195], v[112:115]
	v_mfma_f32_16x16x32_bf16 v[108:111], v[154:157], v[192:195], v[108:111]
	v_mfma_f32_16x16x32_bf16 v[96:99], v[142:145], v[204:207], v[96:99]
	v_mfma_f32_16x16x32_bf16 v[92:95], v[154:157], v[204:207], v[92:95]
	v_mfma_f32_16x16x32_bf16 v[80:83], v[142:145], v[208:211], v[80:83]
	v_mfma_f32_16x16x32_bf16 v[76:79], v[154:157], v[208:211], v[76:79]
	s_setprio 0
	s_setprio 1
	v_mfma_f32_16x16x32_bf16 v[120:123], v[158:161], v[174:177], v[120:123]
	v_mfma_f32_16x16x32_bf16 v[116:119], v[166:169], v[174:177], v[116:119]
	v_mfma_f32_16x16x32_bf16 v[104:107], v[158:161], v[184:187], v[104:107]
	v_mfma_f32_16x16x32_bf16 v[100:103], v[166:169], v[184:187], v[100:103]
	v_mfma_f32_16x16x32_bf16 v[88:91], v[158:161], v[196:199], v[88:91]
	v_mfma_f32_16x16x32_bf16 v[84:87], v[166:169], v[196:199], v[84:87]
	v_mfma_f32_16x16x32_bf16 v[72:75], v[158:161], v[200:203], v[72:75]
	v_mfma_f32_16x16x32_bf16 v[68:71], v[166:169], v[200:203], v[68:71]
	v_mfma_f32_16x16x32_bf16 v[120:123], v[162:165], v[188:191], v[120:123]
	v_mfma_f32_16x16x32_bf16 v[116:119], v[170:173], v[188:191], v[116:119]
	v_mfma_f32_16x16x32_bf16 v[104:107], v[162:165], v[192:195], v[104:107]
	v_mfma_f32_16x16x32_bf16 v[100:103], v[170:173], v[192:195], v[100:103]
	v_mfma_f32_16x16x32_bf16 v[88:91], v[162:165], v[204:207], v[88:91]
	v_mfma_f32_16x16x32_bf16 v[84:87], v[170:173], v[204:207], v[84:87]
	v_mfma_f32_16x16x32_bf16 v[72:75], v[162:165], v[208:211], v[72:75]
	v_mfma_f32_16x16x32_bf16 v[68:71], v[170:173], v[208:211], v[68:71]
	s_setprio 0
	s_barrier
	s_add_i32 s25, s25, s33
	s_add_i32 m0, s25, 0xffffff80
	ds_read_b128 v[174:177], v151 offset:49152
	ds_read_b128 v[184:187], v151 offset:51200
	ds_read_b128 v[188:191], v152 offset:49152
	ds_read_b128 v[192:195], v152 offset:51200
	ds_read_b128 v[196:199], v151 offset:53248
	ds_read_b128 v[200:203], v151 offset:55296
	ds_read_b128 v[204:207], v152 offset:53248
	ds_read_b128 v[208:211], v152 offset:55296
	global_load_lds_dwordx4 v34, s[28:29] offset:128
	s_add_i32 m0, s25, 0x1f80
	s_mov_b64 s[98:99], s[28:29]
	s_add_u32 s28, s28, 0x80080
	s_addc_u32 s29, s29, 0
	s_add_i32 s25, s34, s33
	global_load_lds_dwordx4 v132, s[98:99] offset:128
	s_mov_b32 m0, s25
	s_nop 0
	global_load_lds_dwordx4 v34, s[28:29]
	s_add_i32 m0, s25, 0x2000
	s_nop 0
	global_load_lds_dwordx4 v132, s[28:29]
	s_add_i32 m0, s52, 0xffffff80
	s_nop 0
	global_load_lds_dwordx4 v136, s[44:45] offset:128
	s_add_i32 m0, s53, 0xffffff80
	s_nop 0
	global_load_lds_dwordx4 v134, s[44:45] offset:128
	s_waitcnt vmcnt(8) lgkmcnt(0)
	s_barrier
	s_setprio 1
	v_mfma_f32_16x16x32_bf16 v[64:67], v[138:141], v[174:177], v[64:67]
	v_mfma_f32_16x16x32_bf16 v[60:63], v[146:149], v[174:177], v[60:63]
	v_mfma_f32_16x16x32_bf16 v[48:51], v[138:141], v[184:187], v[48:51]
	v_mfma_f32_16x16x32_bf16 v[44:47], v[146:149], v[184:187], v[44:47]
	v_mfma_f32_16x16x32_bf16 v[30:33], v[138:141], v[196:199], v[30:33]
	v_mfma_f32_16x16x32_bf16 v[26:29], v[146:149], v[196:199], v[26:29]
	v_mfma_f32_16x16x32_bf16 v[14:17], v[138:141], v[200:203], v[14:17]
	v_mfma_f32_16x16x32_bf16 v[10:13], v[146:149], v[200:203], v[10:13]
	v_mfma_f32_16x16x32_bf16 v[64:67], v[142:145], v[188:191], v[64:67]
	v_mfma_f32_16x16x32_bf16 v[60:63], v[154:157], v[188:191], v[60:63]
	v_mfma_f32_16x16x32_bf16 v[48:51], v[142:145], v[192:195], v[48:51]
	v_mfma_f32_16x16x32_bf16 v[44:47], v[154:157], v[192:195], v[44:47]
	v_mfma_f32_16x16x32_bf16 v[30:33], v[142:145], v[204:207], v[30:33]
	v_mfma_f32_16x16x32_bf16 v[26:29], v[154:157], v[204:207], v[26:29]
	v_mfma_f32_16x16x32_bf16 v[14:17], v[142:145], v[208:211], v[14:17]
	v_mfma_f32_16x16x32_bf16 v[10:13], v[154:157], v[208:211], v[10:13]
	s_setprio 0
	s_setprio 1
	v_mfma_f32_16x16x32_bf16 v[56:59], v[158:161], v[174:177], v[56:59]
	v_mfma_f32_16x16x32_bf16 v[52:55], v[166:169], v[174:177], v[52:55]
	v_mfma_f32_16x16x32_bf16 v[40:43], v[158:161], v[184:187], v[40:43]
	v_mfma_f32_16x16x32_bf16 v[36:39], v[166:169], v[184:187], v[36:39]
	v_mfma_f32_16x16x32_bf16 v[22:25], v[158:161], v[196:199], v[22:25]
	v_mfma_f32_16x16x32_bf16 v[18:21], v[166:169], v[196:199], v[18:21]
	v_mfma_f32_16x16x32_bf16 v[6:9], v[158:161], v[200:203], v[6:9]
	v_mfma_f32_16x16x32_bf16 v[2:5], v[166:169], v[200:203], v[2:5]
	v_mfma_f32_16x16x32_bf16 v[56:59], v[162:165], v[188:191], v[56:59]
	v_mfma_f32_16x16x32_bf16 v[52:55], v[170:173], v[188:191], v[52:55]
	v_mfma_f32_16x16x32_bf16 v[40:43], v[162:165], v[192:195], v[40:43]
	v_mfma_f32_16x16x32_bf16 v[36:39], v[170:173], v[192:195], v[36:39]
	v_mfma_f32_16x16x32_bf16 v[22:25], v[162:165], v[204:207], v[22:25]
	v_mfma_f32_16x16x32_bf16 v[18:21], v[170:173], v[204:207], v[18:21]
	v_mfma_f32_16x16x32_bf16 v[6:9], v[162:165], v[208:211], v[6:9]
	v_mfma_f32_16x16x32_bf16 v[2:5], v[170:173], v[208:211], v[2:5]
	s_setprio 0
	s_barrier
	s_add_i32 s24, s24, 2
	s_add_u32 s8, s8, 0x100
	s_addc_u32 s9, s9, 0
	s_add_u32 s21, s21, 0x100
	s_addc_u32 s23, s23, 0
	s_cmp_gt_u32 s24, 29
	s_cbranch_scc1 .Lpeel_done_P4
.LBB0_1023:
	s_add_u32 s25, s8, 0xfff80080
	s_addc_u32 s28, s9, -1
	s_add_i32 s30, 0, 0x10000
	s_cmp_eq_u32 s24, 28
	s_cselect_b32 s45, s12, s28
	s_cselect_b32 s44, s13, s25
	s_cselect_b32 s29, s19, s23
	s_cselect_b32 s28, s20, s21
	s_add_i32 s25, 0, 0x14000
	ds_read_b128 v[138:141], v1
	ds_read_b128 v[142:145], v150
	ds_read_b128 v[146:149], v1 offset:2048
	ds_read_b128 v[154:157], v150 offset:2048
	ds_read_b128 v[158:161], v1 offset:16384
	ds_read_b128 v[162:165], v150 offset:16384
	ds_read_b128 v[166:169], v1 offset:18432
	ds_read_b128 v[170:173], v150 offset:18432
	s_add_i32 m0, s46, 0xc000
	ds_read_b128 v[174:177], v151
	ds_read_b128 v[184:187], v151 offset:2048
	ds_read_b128 v[188:191], v152
	ds_read_b128 v[192:195], v152 offset:2048
	ds_read_b128 v[196:199], v151 offset:4096
	ds_read_b128 v[200:203], v151 offset:6144
	ds_read_b128 v[204:207], v152 offset:4096
	ds_read_b128 v[208:211], v152 offset:6144
	global_load_lds_dwordx4 v136, s[8:9]
	s_add_i32 m0, s46, 0xe000
	s_nop 0
	global_load_lds_dwordx4 v134, s[8:9]
	s_waitcnt vmcnt(8) lgkmcnt(0)
	s_barrier
	s_setprio 1
	v_mfma_f32_16x16x32_bf16 v[128:131], v[138:141], v[174:177], v[128:131]
	v_mfma_f32_16x16x32_bf16 v[124:127], v[146:149], v[174:177], v[124:127]
	v_mfma_f32_16x16x32_bf16 v[112:115], v[138:141], v[184:187], v[112:115]
	v_mfma_f32_16x16x32_bf16 v[108:111], v[146:149], v[184:187], v[108:111]
	v_mfma_f32_16x16x32_bf16 v[96:99], v[138:141], v[196:199], v[96:99]
	v_mfma_f32_16x16x32_bf16 v[92:95], v[146:149], v[196:199], v[92:95]
	v_mfma_f32_16x16x32_bf16 v[80:83], v[138:141], v[200:203], v[80:83]
	v_mfma_f32_16x16x32_bf16 v[76:79], v[146:149], v[200:203], v[76:79]
	v_mfma_f32_16x16x32_bf16 v[128:131], v[142:145], v[188:191], v[128:131]
	v_mfma_f32_16x16x32_bf16 v[124:127], v[154:157], v[188:191], v[124:127]
	v_mfma_f32_16x16x32_bf16 v[112:115], v[142:145], v[192:195], v[112:115]
	v_mfma_f32_16x16x32_bf16 v[108:111], v[154:157], v[192:195], v[108:111]
	v_mfma_f32_16x16x32_bf16 v[96:99], v[142:145], v[204:207], v[96:99]
	v_mfma_f32_16x16x32_bf16 v[92:95], v[154:157], v[204:207], v[92:95]
	v_mfma_f32_16x16x32_bf16 v[80:83], v[142:145], v[208:211], v[80:83]
	v_mfma_f32_16x16x32_bf16 v[76:79], v[154:157], v[208:211], v[76:79]
	s_setprio 0
	s_setprio 1
	v_mfma_f32_16x16x32_bf16 v[120:123], v[158:161], v[174:177], v[120:123]
	v_mfma_f32_16x16x32_bf16 v[116:119], v[166:169], v[174:177], v[116:119]
	v_mfma_f32_16x16x32_bf16 v[104:107], v[158:161], v[184:187], v[104:107]
	v_mfma_f32_16x16x32_bf16 v[100:103], v[166:169], v[184:187], v[100:103]
	v_mfma_f32_16x16x32_bf16 v[88:91], v[158:161], v[196:199], v[88:91]
	v_mfma_f32_16x16x32_bf16 v[84:87], v[166:169], v[196:199], v[84:87]
	v_mfma_f32_16x16x32_bf16 v[72:75], v[158:161], v[200:203], v[72:75]
	v_mfma_f32_16x16x32_bf16 v[68:71], v[166:169], v[200:203], v[68:71]
	v_mfma_f32_16x16x32_bf16 v[120:123], v[162:165], v[188:191], v[120:123]
	v_mfma_f32_16x16x32_bf16 v[116:119], v[170:173], v[188:191], v[116:119]
	v_mfma_f32_16x16x32_bf16 v[104:107], v[162:165], v[192:195], v[104:107]
	v_mfma_f32_16x16x32_bf16 v[100:103], v[170:173], v[192:195], v[100:103]
	v_mfma_f32_16x16x32_bf16 v[88:91], v[162:165], v[204:207], v[88:91]
	v_mfma_f32_16x16x32_bf16 v[84:87], v[170:173], v[204:207], v[84:87]
	v_mfma_f32_16x16x32_bf16 v[72:75], v[162:165], v[208:211], v[72:75]
	v_mfma_f32_16x16x32_bf16 v[68:71], v[170:173], v[208:211], v[68:71]
	s_setprio 0
	s_barrier
	s_add_i32 s30, s30, s33
	s_mov_b32 m0, s30
	ds_read_b128 v[174:177], v151 offset:16384
	ds_read_b128 v[184:187], v151 offset:18432
	ds_read_b128 v[188:191], v152 offset:16384
	ds_read_b128 v[192:195], v152 offset:18432
	ds_read_b128 v[196:199], v151 offset:20480
	ds_read_b128 v[200:203], v151 offset:22528
	ds_read_b128 v[204:207], v152 offset:20480
	ds_read_b128 v[208:211], v152 offset:22528
	global_load_lds_dwordx4 v34, s[28:29]
	s_add_i32 m0, s30, 0x2000
	s_add_u32 s30, s28, 0x80000
	s_addc_u32 s31, s29, 0
	s_add_i32 s25, s25, s33
	global_load_lds_dwordx4 v132, s[28:29]
	s_mov_b32 m0, s25
	s_nop 0
	global_load_lds_dwordx4 v34, s[30:31]
	s_add_i32 m0, s25, 0x2000
	s_nop 0
	global_load_lds_dwordx4 v132, s[30:31]
	s_mov_b32 m0, s46
	s_nop 0
	global_load_lds_dwordx4 v136, s[44:45]
	s_mov_b32 m0, s47
	s_nop 0
	global_load_lds_dwordx4 v134, s[44:45]
	s_waitcnt vmcnt(8) lgkmcnt(0)
	s_barrier
	s_setprio 1
	v_mfma_f32_16x16x32_bf16 v[64:67], v[138:141], v[174:177], v[64:67]
	v_mfma_f32_16x16x32_bf16 v[60:63], v[146:149], v[174:177], v[60:63]
	v_mfma_f32_16x16x32_bf16 v[48:51], v[138:141], v[184:187], v[48:51]
	v_mfma_f32_16x16x32_bf16 v[44:47], v[146:149], v[184:187], v[44:47]
	v_mfma_f32_16x16x32_bf16 v[30:33], v[138:141], v[196:199], v[30:33]
	v_mfma_f32_16x16x32_bf16 v[26:29], v[146:149], v[196:199], v[26:29]
	v_mfma_f32_16x16x32_bf16 v[14:17], v[138:141], v[200:203], v[14:17]
	v_mfma_f32_16x16x32_bf16 v[10:13], v[146:149], v[200:203], v[10:13]
	v_mfma_f32_16x16x32_bf16 v[64:67], v[142:145], v[188:191], v[64:67]
	v_mfma_f32_16x16x32_bf16 v[60:63], v[154:157], v[188:191], v[60:63]
	v_mfma_f32_16x16x32_bf16 v[48:51], v[142:145], v[192:195], v[48:51]
	v_mfma_f32_16x16x32_bf16 v[44:47], v[154:157], v[192:195], v[44:47]
	v_mfma_f32_16x16x32_bf16 v[30:33], v[142:145], v[204:207], v[30:33]
	v_mfma_f32_16x16x32_bf16 v[26:29], v[154:157], v[204:207], v[26:29]
	v_mfma_f32_16x16x32_bf16 v[14:17], v[142:145], v[208:211], v[14:17]
	v_mfma_f32_16x16x32_bf16 v[10:13], v[154:157], v[208:211], v[10:13]
	s_setprio 0
	s_setprio 1
	v_mfma_f32_16x16x32_bf16 v[56:59], v[158:161], v[174:177], v[56:59]
	v_mfma_f32_16x16x32_bf16 v[52:55], v[166:169], v[174:177], v[52:55]
	v_mfma_f32_16x16x32_bf16 v[40:43], v[158:161], v[184:187], v[40:43]
	v_mfma_f32_16x16x32_bf16 v[36:39], v[166:169], v[184:187], v[36:39]
	v_mfma_f32_16x16x32_bf16 v[22:25], v[158:161], v[196:199], v[22:25]
	v_mfma_f32_16x16x32_bf16 v[18:21], v[166:169], v[196:199], v[18:21]
	v_mfma_f32_16x16x32_bf16 v[6:9], v[158:161], v[200:203], v[6:9]
	v_mfma_f32_16x16x32_bf16 v[2:5], v[166:169], v[200:203], v[2:5]
	v_mfma_f32_16x16x32_bf16 v[56:59], v[162:165], v[188:191], v[56:59]
	v_mfma_f32_16x16x32_bf16 v[52:55], v[170:173], v[188:191], v[52:55]
	v_mfma_f32_16x16x32_bf16 v[40:43], v[162:165], v[192:195], v[40:43]
	v_mfma_f32_16x16x32_bf16 v[36:39], v[170:173], v[192:195], v[36:39]
	v_mfma_f32_16x16x32_bf16 v[22:25], v[162:165], v[204:207], v[22:25]
	v_mfma_f32_16x16x32_bf16 v[18:21], v[170:173], v[204:207], v[18:21]
	v_mfma_f32_16x16x32_bf16 v[6:9], v[162:165], v[208:211], v[6:9]
	v_mfma_f32_16x16x32_bf16 v[2:5], v[170:173], v[208:211], v[2:5]
	s_setprio 0
	s_barrier
	s_add_i32 s25, 0, 0x18000
	s_add_i32 s34, 0, 0x1c000
	ds_read_b128 v[138:141], v1 offset:32768
	ds_read_b128 v[142:145], v150 offset:32768
	ds_read_b128 v[146:149], v1 offset:34816
	ds_read_b128 v[154:157], v150 offset:34816
	ds_read_b128 v[158:161], v1 offset:49152
	ds_read_b128 v[162:165], v150 offset:49152
	ds_read_b128 v[166:169], v1 offset:51200
	ds_read_b128 v[170:173], v150 offset:51200
	s_add_u32 s30, s44, 0x80000
	s_addc_u32 s31, s45, 0
	s_mov_b32 m0, s48
	ds_read_b128 v[174:177], v151 offset:32768
	ds_read_b128 v[184:187], v151 offset:34816
	ds_read_b128 v[188:191], v152 offset:32768
	ds_read_b128 v[192:195], v152 offset:34816
	ds_read_b128 v[196:199], v151 offset:36864
	ds_read_b128 v[200:203], v151 offset:38912
	ds_read_b128 v[204:207], v152 offset:36864
	ds_read_b128 v[208:211], v152 offset:38912
	global_load_lds_dwordx4 v136, s[30:31]
	s_mov_b32 m0, s49
	s_nop 0
	global_load_lds_dwordx4 v134, s[30:31]
	s_waitcnt vmcnt(8) lgkmcnt(0)
	s_barrier
	s_setprio 1
	v_mfma_f32_16x16x32_bf16 v[128:131], v[138:141], v[174:177], v[128:131]
	v_mfma_f32_16x16x32_bf16 v[124:127], v[146:149], v[174:177], v[124:127]
	v_mfma_f32_16x16x32_bf16 v[112:115], v[138:141], v[184:187], v[112:115]
	v_mfma_f32_16x16x32_bf16 v[108:111], v[146:149], v[184:187], v[108:111]
	v_mfma_f32_16x16x32_bf16 v[96:99], v[138:141], v[196:199], v[96:99]
	v_mfma_f32_16x16x32_bf16 v[92:95], v[146:149], v[196:199], v[92:95]
	v_mfma_f32_16x16x32_bf16 v[80:83], v[138:141], v[200:203], v[80:83]
	v_mfma_f32_16x16x32_bf16 v[76:79], v[146:149], v[200:203], v[76:79]
	v_mfma_f32_16x16x32_bf16 v[128:131], v[142:145], v[188:191], v[128:131]
	v_mfma_f32_16x16x32_bf16 v[124:127], v[154:157], v[188:191], v[124:127]
	v_mfma_f32_16x16x32_bf16 v[112:115], v[142:145], v[192:195], v[112:115]
	v_mfma_f32_16x16x32_bf16 v[108:111], v[154:157], v[192:195], v[108:111]
	v_mfma_f32_16x16x32_bf16 v[96:99], v[142:145], v[204:207], v[96:99]
	v_mfma_f32_16x16x32_bf16 v[92:95], v[154:157], v[204:207], v[92:95]
	v_mfma_f32_16x16x32_bf16 v[80:83], v[142:145], v[208:211], v[80:83]
	v_mfma_f32_16x16x32_bf16 v[76:79], v[154:157], v[208:211], v[76:79]
	s_setprio 0
	s_setprio 1
	v_mfma_f32_16x16x32_bf16 v[120:123], v[158:161], v[174:177], v[120:123]
	v_mfma_f32_16x16x32_bf16 v[116:119], v[166:169], v[174:177], v[116:119]
	v_mfma_f32_16x16x32_bf16 v[104:107], v[158:161], v[184:187], v[104:107]
	v_mfma_f32_16x16x32_bf16 v[100:103], v[166:169], v[184:187], v[100:103]
	v_mfma_f32_16x16x32_bf16 v[88:91], v[158:161], v[196:199], v[88:91]
	v_mfma_f32_16x16x32_bf16 v[84:87], v[166:169], v[196:199], v[84:87]
	v_mfma_f32_16x16x32_bf16 v[72:75], v[158:161], v[200:203], v[72:75]
	v_mfma_f32_16x16x32_bf16 v[68:71], v[166:169], v[200:203], v[68:71]
	v_mfma_f32_16x16x32_bf16 v[120:123], v[162:165], v[188:191], v[120:123]
	v_mfma_f32_16x16x32_bf16 v[116:119], v[170:173], v[188:191], v[116:119]
	v_mfma_f32_16x16x32_bf16 v[104:107], v[162:165], v[192:195], v[104:107]
	v_mfma_f32_16x16x32_bf16 v[100:103], v[170:173], v[192:195], v[100:103]
	v_mfma_f32_16x16x32_bf16 v[88:91], v[162:165], v[204:207], v[88:91]
	v_mfma_f32_16x16x32_bf16 v[84:87], v[170:173], v[204:207], v[84:87]
	v_mfma_f32_16x16x32_bf16 v[72:75], v[162:165], v[208:211], v[72:75]
	v_mfma_f32_16x16x32_bf16 v[68:71], v[170:173], v[208:211], v[68:71]
	s_setprio 0
	s_barrier
	s_add_i32 s25, s25, s33
	s_add_i32 m0, s25, 0xffffff80
	ds_read_b128 v[174:177], v151 offset:49152
	ds_read_b128 v[184:187], v151 offset:51200
	ds_read_b128 v[188:191], v152 offset:49152
	ds_read_b128 v[192:195], v152 offset:51200
	ds_read_b128 v[196:199], v151 offset:53248
	ds_read_b128 v[200:203], v151 offset:55296
	ds_read_b128 v[204:207], v152 offset:53248
	ds_read_b128 v[208:211], v152 offset:55296
	global_load_lds_dwordx4 v34, s[28:29] offset:128
	s_add_i32 m0, s25, 0x1f80
	s_mov_b64 s[98:99], s[28:29]
	s_add_u32 s28, s28, 0x80080
	s_addc_u32 s29, s29, 0
	s_add_i32 s25, s34, s33
	global_load_lds_dwordx4 v132, s[98:99] offset:128
	s_mov_b32 m0, s25
	s_nop 0
	global_load_lds_dwordx4 v34, s[28:29]
	s_add_i32 m0, s25, 0x2000
	s_nop 0
	global_load_lds_dwordx4 v132, s[28:29]
	s_add_i32 m0, s52, 0xffffff80
	s_nop 0
	global_load_lds_dwordx4 v136, s[44:45] offset:128
	s_add_i32 m0, s53, 0xffffff80
	s_nop 0
	global_load_lds_dwordx4 v134, s[44:45] offset:128
	s_waitcnt vmcnt(8) lgkmcnt(0)
	s_barrier
	s_setprio 1
	v_mfma_f32_16x16x32_bf16 v[64:67], v[138:141], v[174:177], v[64:67]
	v_mfma_f32_16x16x32_bf16 v[60:63], v[146:149], v[174:177], v[60:63]
	v_mfma_f32_16x16x32_bf16 v[48:51], v[138:141], v[184:187], v[48:51]
	v_mfma_f32_16x16x32_bf16 v[44:47], v[146:149], v[184:187], v[44:47]
	v_mfma_f32_16x16x32_bf16 v[30:33], v[138:141], v[196:199], v[30:33]
	v_mfma_f32_16x16x32_bf16 v[26:29], v[146:149], v[196:199], v[26:29]
	v_mfma_f32_16x16x32_bf16 v[14:17], v[138:141], v[200:203], v[14:17]
	v_mfma_f32_16x16x32_bf16 v[10:13], v[146:149], v[200:203], v[10:13]
	v_mfma_f32_16x16x32_bf16 v[64:67], v[142:145], v[188:191], v[64:67]
	v_mfma_f32_16x16x32_bf16 v[60:63], v[154:157], v[188:191], v[60:63]
	v_mfma_f32_16x16x32_bf16 v[48:51], v[142:145], v[192:195], v[48:51]
	v_mfma_f32_16x16x32_bf16 v[44:47], v[154:157], v[192:195], v[44:47]
	v_mfma_f32_16x16x32_bf16 v[30:33], v[142:145], v[204:207], v[30:33]
	v_mfma_f32_16x16x32_bf16 v[26:29], v[154:157], v[204:207], v[26:29]
	v_mfma_f32_16x16x32_bf16 v[14:17], v[142:145], v[208:211], v[14:17]
	v_mfma_f32_16x16x32_bf16 v[10:13], v[154:157], v[208:211], v[10:13]
	s_setprio 0
	s_setprio 1
	v_mfma_f32_16x16x32_bf16 v[56:59], v[158:161], v[174:177], v[56:59]
	v_mfma_f32_16x16x32_bf16 v[52:55], v[166:169], v[174:177], v[52:55]
	v_mfma_f32_16x16x32_bf16 v[40:43], v[158:161], v[184:187], v[40:43]
	v_mfma_f32_16x16x32_bf16 v[36:39], v[166:169], v[184:187], v[36:39]
	v_mfma_f32_16x16x32_bf16 v[22:25], v[158:161], v[196:199], v[22:25]
	v_mfma_f32_16x16x32_bf16 v[18:21], v[166:169], v[196:199], v[18:21]
	v_mfma_f32_16x16x32_bf16 v[6:9], v[158:161], v[200:203], v[6:9]
	v_mfma_f32_16x16x32_bf16 v[2:5], v[166:169], v[200:203], v[2:5]
	v_mfma_f32_16x16x32_bf16 v[56:59], v[162:165], v[188:191], v[56:59]
	v_mfma_f32_16x16x32_bf16 v[52:55], v[170:173], v[188:191], v[52:55]
	v_mfma_f32_16x16x32_bf16 v[40:43], v[162:165], v[192:195], v[40:43]
	v_mfma_f32_16x16x32_bf16 v[36:39], v[170:173], v[192:195], v[36:39]
	v_mfma_f32_16x16x32_bf16 v[22:25], v[162:165], v[204:207], v[22:25]
	v_mfma_f32_16x16x32_bf16 v[18:21], v[170:173], v[204:207], v[18:21]
	v_mfma_f32_16x16x32_bf16 v[6:9], v[162:165], v[208:211], v[6:9]
	v_mfma_f32_16x16x32_bf16 v[2:5], v[170:173], v[208:211], v[2:5]
	s_setprio 0
	s_barrier
	s_add_i32 s24, s24, 2
	s_add_u32 s8, s8, 0x100
	s_addc_u32 s9, s9, 0
	s_add_u32 s21, s21, 0x100
	s_addc_u32 s23, s23, 0
	s_cmp_gt_u32 s24, 29
	s_cbranch_scc0 .LBB0_1023

.LBB0_1113:
	s_ashr_i32 s19, s18, 31
	s_lshl_b64 s[20:21], s[18:19], 20
	v_readlane_b32 s22, v254, 38
	v_readlane_b32 s23, v254, 39
	s_add_u32 s22, s22, s20
	s_addc_u32 s23, s23, s21
	s_and_b64 s[20:21], s[38:39], exec
	s_cselect_b32 s13, s23, s9
	s_cselect_b32 s19, s22, s8
	s_ashr_i32 s11, s10, 31
	s_lshl_b64 s[20:21], s[10:11], 20
	v_readlane_b32 s30, v254, 8
	v_readlane_b32 s31, v254, 9
	s_add_u32 s40, s30, s20
	s_addc_u32 s41, s31, s21
	v_mov_b32_e32 v2, v0
	s_and_b64 s[20:21], s[38:39], exec
	s_cselect_b32 s20, s41, s29
	s_cselect_b32 s21, s40, s28
	s_lshl_b32 s11, s24, 8
	v_and_or_b32 v2, v2, 63, s50
	v_or_b32_e32 v2, s11, v2
	v_ashrrev_i32_e32 v3, 31, v2
	v_readlane_b32 s24, v252, 61
	v_lshlrev_b64 v[2:3], 5, v[2:3]
	v_readlane_b32 s25, v252, 62
	s_add_u32 s8, s8, 0x80080
	s_addc_u32 s9, s9, 0
	v_lshl_add_u64 v[2:3], s[24:25], 0, v[2:3]
	global_load_dwordx4 v[116:119], v[2:3], off offset:16
	global_load_dwordx4 v[120:123], v[2:3], off
	s_add_u32 s24, s28, 0x100
	s_addc_u32 s25, s29, 0
	s_mov_b32 s30, -2
	v_readlane_b32 s57, v255, 20
	v_readlane_b32 s58, v255, 21
	v_readlane_b32 s59, v255, 22
	v_readlane_b32 s60, v255, 23
	s_mov_b64 s[62:63], 0x80
	s_add_u32 s28, s8, 0xfff80080
	s_addc_u32 s29, s9, -1
	s_add_i32 s31, 0, 0x10000
	s_cmp_eq_u32 s30, 28
	s_cselect_b32 s43, s13, s29
	s_cselect_b32 s42, s19, s28
	ds_read_b128 v[150:153], v1
	ds_read_b128 v[154:157], v146
	s_cselect_b32 s29, s20, s25
	s_cselect_b32 s28, s21, s24
	s_add_i32 s56, 0, 0x14000
	ds_read_b128 v[158:161], v1 offset:2048
	ds_read_b128 v[162:165], v146 offset:2048
	ds_read_b128 v[166:169], v1 offset:16384
	ds_read_b128 v[170:173], v146 offset:16384
	ds_read_b128 v[174:177], v1 offset:18432
	ds_read_b128 v[184:187], v146 offset:18432
	s_add_i32 m0, s34, 0xc000
	ds_read_b128 v[188:191], v147
	ds_read_b128 v[192:195], v147 offset:2048
	ds_read_b128 v[196:199], v148
	ds_read_b128 v[200:203], v148 offset:2048
	ds_read_b128 v[204:207], v147 offset:4096
	ds_read_b128 v[208:211], v147 offset:6144
	ds_read_b128 v[224:227], v148 offset:4096
	ds_read_b128 v[228:231], v148 offset:6144
	global_load_lds_dwordx4 v144, s[8:9]
	s_add_i32 m0, s34, 0xe000
	s_nop 0
	global_load_lds_dwordx4 v142, s[8:9]
	s_waitcnt vmcnt(8) lgkmcnt(0)
	s_barrier
	s_setprio 1
	v_mfma_f32_16x16x32_bf16 v[132:135], v[150:153], v[188:191], 0
	v_mfma_f32_16x16x32_bf16 v[124:127], v[158:161], v[188:191], 0
	v_mfma_f32_16x16x32_bf16 v[108:111], v[150:153], v[192:195], 0
	v_mfma_f32_16x16x32_bf16 v[100:103], v[158:161], v[192:195], 0
	v_mfma_f32_16x16x32_bf16 v[92:95], v[150:153], v[204:207], 0
	v_mfma_f32_16x16x32_bf16 v[84:87], v[158:161], v[204:207], 0
	v_mfma_f32_16x16x32_bf16 v[76:79], v[150:153], v[208:211], 0
	v_mfma_f32_16x16x32_bf16 v[68:71], v[158:161], v[208:211], 0
	v_mfma_f32_16x16x32_bf16 v[132:135], v[154:157], v[196:199], v[132:135]
	v_mfma_f32_16x16x32_bf16 v[124:127], v[162:165], v[196:199], v[124:127]
	v_mfma_f32_16x16x32_bf16 v[108:111], v[154:157], v[200:203], v[108:111]
	v_mfma_f32_16x16x32_bf16 v[100:103], v[162:165], v[200:203], v[100:103]
	v_mfma_f32_16x16x32_bf16 v[92:95], v[154:157], v[224:227], v[92:95]
	v_mfma_f32_16x16x32_bf16 v[84:87], v[162:165], v[224:227], v[84:87]
	v_mfma_f32_16x16x32_bf16 v[76:79], v[154:157], v[228:231], v[76:79]
	v_mfma_f32_16x16x32_bf16 v[68:71], v[162:165], v[228:231], v[68:71]
	s_setprio 0
	s_setprio 1
	v_mfma_f32_16x16x32_bf16 v[136:139], v[166:169], v[188:191], 0
	v_mfma_f32_16x16x32_bf16 v[128:131], v[174:177], v[188:191], 0
	v_mfma_f32_16x16x32_bf16 v[112:115], v[166:169], v[192:195], 0
	v_mfma_f32_16x16x32_bf16 v[104:107], v[174:177], v[192:195], 0
	v_mfma_f32_16x16x32_bf16 v[96:99], v[166:169], v[204:207], 0
	v_mfma_f32_16x16x32_bf16 v[88:91], v[174:177], v[204:207], 0
	v_mfma_f32_16x16x32_bf16 v[80:83], v[166:169], v[208:211], 0
	v_mfma_f32_16x16x32_bf16 v[72:75], v[174:177], v[208:211], 0
	v_mfma_f32_16x16x32_bf16 v[136:139], v[170:173], v[196:199], v[136:139]
	v_mfma_f32_16x16x32_bf16 v[128:131], v[184:187], v[196:199], v[128:131]
	v_mfma_f32_16x16x32_bf16 v[112:115], v[170:173], v[200:203], v[112:115]
	v_mfma_f32_16x16x32_bf16 v[104:107], v[184:187], v[200:203], v[104:107]
	v_mfma_f32_16x16x32_bf16 v[96:99], v[170:173], v[224:227], v[96:99]
	v_mfma_f32_16x16x32_bf16 v[88:91], v[184:187], v[224:227], v[88:91]
	v_mfma_f32_16x16x32_bf16 v[80:83], v[170:173], v[228:231], v[80:83]
	v_mfma_f32_16x16x32_bf16 v[72:75], v[184:187], v[228:231], v[72:75]
	s_setprio 0
	s_barrier
	s_add_i32 s31, s31, s33
	s_mov_b32 m0, s31
	ds_read_b128 v[188:191], v147 offset:16384
	ds_read_b128 v[192:195], v147 offset:18432
	ds_read_b128 v[196:199], v148 offset:16384
	ds_read_b128 v[200:203], v148 offset:18432
	ds_read_b128 v[204:207], v147 offset:20480
	ds_read_b128 v[208:211], v147 offset:22528
	ds_read_b128 v[224:227], v148 offset:20480
	ds_read_b128 v[228:231], v148 offset:22528
	global_load_lds_dwordx4 v34, s[28:29]
	s_add_i32 m0, s31, 0x2000
	s_add_u32 s54, s28, 0x80000
	s_addc_u32 s55, s29, 0
	s_add_i32 s31, s56, s33
	global_load_lds_dwordx4 v140, s[28:29]
	s_mov_b32 m0, s31
	s_nop 0
	global_load_lds_dwordx4 v34, s[54:55]
	s_add_i32 m0, s31, 0x2000
	s_nop 0
	global_load_lds_dwordx4 v140, s[54:55]
	s_mov_b32 m0, s34
	s_nop 0
	global_load_lds_dwordx4 v144, s[42:43]
	s_mov_b32 m0, s35
	s_nop 0
	global_load_lds_dwordx4 v142, s[42:43]
	s_waitcnt vmcnt(8) lgkmcnt(0)
	s_barrier
	s_setprio 1
	v_mfma_f32_16x16x32_bf16 v[60:63], v[150:153], v[188:191], 0
	v_mfma_f32_16x16x32_bf16 v[52:55], v[158:161], v[188:191], 0
	v_mfma_f32_16x16x32_bf16 v[44:47], v[150:153], v[192:195], 0
	v_mfma_f32_16x16x32_bf16 v[36:39], v[158:161], v[192:195], 0
	v_mfma_f32_16x16x32_bf16 v[26:29], v[150:153], v[204:207], 0
	v_mfma_f32_16x16x32_bf16 v[18:21], v[158:161], v[204:207], 0
	v_mfma_f32_16x16x32_bf16 v[10:13], v[150:153], v[208:211], 0
	v_mfma_f32_16x16x32_bf16 v[6:9], v[158:161], v[208:211], 0
	v_mfma_f32_16x16x32_bf16 v[60:63], v[154:157], v[196:199], v[60:63]
	v_mfma_f32_16x16x32_bf16 v[52:55], v[162:165], v[196:199], v[52:55]
	v_mfma_f32_16x16x32_bf16 v[44:47], v[154:157], v[200:203], v[44:47]
	v_mfma_f32_16x16x32_bf16 v[36:39], v[162:165], v[200:203], v[36:39]
	v_mfma_f32_16x16x32_bf16 v[26:29], v[154:157], v[224:227], v[26:29]
	v_mfma_f32_16x16x32_bf16 v[18:21], v[162:165], v[224:227], v[18:21]
	v_mfma_f32_16x16x32_bf16 v[10:13], v[154:157], v[228:231], v[10:13]
	v_mfma_f32_16x16x32_bf16 v[6:9], v[162:165], v[228:231], v[6:9]
	s_setprio 0
	s_setprio 1
	v_mfma_f32_16x16x32_bf16 v[64:67], v[166:169], v[188:191], 0
	v_mfma_f32_16x16x32_bf16 v[56:59], v[174:177], v[188:191], 0
	v_mfma_f32_16x16x32_bf16 v[48:51], v[166:169], v[192:195], 0
	v_mfma_f32_16x16x32_bf16 v[40:43], v[174:177], v[192:195], 0
	v_mfma_f32_16x16x32_bf16 v[30:33], v[166:169], v[204:207], 0
	v_mfma_f32_16x16x32_bf16 v[22:25], v[174:177], v[204:207], 0
	v_mfma_f32_16x16x32_bf16 v[14:17], v[166:169], v[208:211], 0
	v_mfma_f32_16x16x32_bf16 v[2:5], v[174:177], v[208:211], 0
	v_mfma_f32_16x16x32_bf16 v[64:67], v[170:173], v[196:199], v[64:67]
	v_mfma_f32_16x16x32_bf16 v[56:59], v[184:187], v[196:199], v[56:59]
	v_mfma_f32_16x16x32_bf16 v[48:51], v[170:173], v[200:203], v[48:51]
	v_mfma_f32_16x16x32_bf16 v[40:43], v[184:187], v[200:203], v[40:43]
	v_mfma_f32_16x16x32_bf16 v[30:33], v[170:173], v[224:227], v[30:33]
	v_mfma_f32_16x16x32_bf16 v[22:25], v[184:187], v[224:227], v[22:25]
	v_mfma_f32_16x16x32_bf16 v[14:17], v[170:173], v[228:231], v[14:17]
	v_mfma_f32_16x16x32_bf16 v[2:5], v[184:187], v[228:231], v[2:5]
	s_setprio 0
	s_barrier
	s_add_i32 s31, 0, 0x18000
	ds_read_b128 v[150:153], v1 offset:32768
	ds_read_b128 v[154:157], v146 offset:32768
	s_add_i32 s54, 0, 0x1c000
	ds_read_b128 v[158:161], v1 offset:34816
	ds_read_b128 v[162:165], v146 offset:34816
	ds_read_b128 v[166:169], v1 offset:49152
	ds_read_b128 v[170:173], v146 offset:49152
	ds_read_b128 v[174:177], v1 offset:51200
	ds_read_b128 v[184:187], v146 offset:51200
	s_mov_b64 s[100:101], s[42:43]
	s_add_u32 s42, s42, 0x80000
	s_addc_u32 s43, s43, 0
	s_mov_b32 m0, s44
	ds_read_b128 v[188:191], v147 offset:32768
	ds_read_b128 v[192:195], v147 offset:34816
	ds_read_b128 v[196:199], v148 offset:32768
	ds_read_b128 v[200:203], v148 offset:34816
	ds_read_b128 v[204:207], v147 offset:36864
	ds_read_b128 v[208:211], v147 offset:38912
	ds_read_b128 v[224:227], v148 offset:36864
	ds_read_b128 v[228:231], v148 offset:38912
	global_load_lds_dwordx4 v144, s[42:43]
	s_mov_b32 m0, s45
	s_nop 0
	global_load_lds_dwordx4 v142, s[42:43]
	s_waitcnt vmcnt(8) lgkmcnt(0)
	s_barrier
	s_setprio 1
	v_mfma_f32_16x16x32_bf16 v[132:135], v[150:153], v[188:191], v[132:135]
	v_mfma_f32_16x16x32_bf16 v[124:127], v[158:161], v[188:191], v[124:127]
	v_mfma_f32_16x16x32_bf16 v[108:111], v[150:153], v[192:195], v[108:111]
	v_mfma_f32_16x16x32_bf16 v[100:103], v[158:161], v[192:195], v[100:103]
	v_mfma_f32_16x16x32_bf16 v[92:95], v[150:153], v[204:207], v[92:95]
	v_mfma_f32_16x16x32_bf16 v[84:87], v[158:161], v[204:207], v[84:87]
	v_mfma_f32_16x16x32_bf16 v[76:79], v[150:153], v[208:211], v[76:79]
	v_mfma_f32_16x16x32_bf16 v[68:71], v[158:161], v[208:211], v[68:71]
	v_mfma_f32_16x16x32_bf16 v[132:135], v[154:157], v[196:199], v[132:135]
	v_mfma_f32_16x16x32_bf16 v[124:127], v[162:165], v[196:199], v[124:127]
	v_mfma_f32_16x16x32_bf16 v[108:111], v[154:157], v[200:203], v[108:111]
	v_mfma_f32_16x16x32_bf16 v[100:103], v[162:165], v[200:203], v[100:103]
	v_mfma_f32_16x16x32_bf16 v[92:95], v[154:157], v[224:227], v[92:95]
	v_mfma_f32_16x16x32_bf16 v[84:87], v[162:165], v[224:227], v[84:87]
	v_mfma_f32_16x16x32_bf16 v[76:79], v[154:157], v[228:231], v[76:79]
	v_mfma_f32_16x16x32_bf16 v[68:71], v[162:165], v[228:231], v[68:71]
	s_setprio 0
	s_setprio 1
	v_mfma_f32_16x16x32_bf16 v[136:139], v[166:169], v[188:191], v[136:139]
	v_mfma_f32_16x16x32_bf16 v[128:131], v[174:177], v[188:191], v[128:131]
	v_mfma_f32_16x16x32_bf16 v[112:115], v[166:169], v[192:195], v[112:115]
	v_mfma_f32_16x16x32_bf16 v[104:107], v[174:177], v[192:195], v[104:107]
	v_mfma_f32_16x16x32_bf16 v[96:99], v[166:169], v[204:207], v[96:99]
	v_mfma_f32_16x16x32_bf16 v[88:91], v[174:177], v[204:207], v[88:91]
	v_mfma_f32_16x16x32_bf16 v[80:83], v[166:169], v[208:211], v[80:83]
	v_mfma_f32_16x16x32_bf16 v[72:75], v[174:177], v[208:211], v[72:75]
	v_mfma_f32_16x16x32_bf16 v[136:139], v[170:173], v[196:199], v[136:139]
	v_mfma_f32_16x16x32_bf16 v[128:131], v[184:187], v[196:199], v[128:131]
	v_mfma_f32_16x16x32_bf16 v[112:115], v[170:173], v[200:203], v[112:115]
	v_mfma_f32_16x16x32_bf16 v[104:107], v[184:187], v[200:203], v[104:107]
	v_mfma_f32_16x16x32_bf16 v[96:99], v[170:173], v[224:227], v[96:99]
	v_mfma_f32_16x16x32_bf16 v[88:91], v[184:187], v[224:227], v[88:91]
	v_mfma_f32_16x16x32_bf16 v[80:83], v[170:173], v[228:231], v[80:83]
	v_mfma_f32_16x16x32_bf16 v[72:75], v[184:187], v[228:231], v[72:75]
	s_setprio 0
	s_barrier
	s_add_i32 s31, s31, s33
	s_add_i32 m0, s31, 0xffffff80
	ds_read_b128 v[188:191], v147 offset:49152
	ds_read_b128 v[192:195], v147 offset:51200
	ds_read_b128 v[196:199], v148 offset:49152
	ds_read_b128 v[200:203], v148 offset:51200
	ds_read_b128 v[204:207], v147 offset:53248
	ds_read_b128 v[208:211], v147 offset:55296
	ds_read_b128 v[224:227], v148 offset:53248
	ds_read_b128 v[228:231], v148 offset:55296
	global_load_lds_dwordx4 v34, s[28:29] offset:128
	s_add_i32 m0, s31, 0x1f80
	s_mov_b64 s[98:99], s[28:29]
	s_add_u32 s28, s28, 0x80080
	s_addc_u32 s29, s29, 0
	s_add_i32 s31, s54, s33
	global_load_lds_dwordx4 v140, s[98:99] offset:128
	s_mov_b32 m0, s31
	s_nop 0
	global_load_lds_dwordx4 v34, s[28:29]
	s_add_i32 m0, s31, 0x2000
	s_nop 0
	global_load_lds_dwordx4 v140, s[28:29]
	s_add_i32 m0, s48, 0xffffff80
	s_nop 0
	global_load_lds_dwordx4 v144, s[100:101] offset:128
	s_add_i32 m0, s49, 0xffffff80
	s_nop 0
	global_load_lds_dwordx4 v142, s[100:101] offset:128
	s_waitcnt vmcnt(8) lgkmcnt(0)
	s_barrier
	s_setprio 1
	v_mfma_f32_16x16x32_bf16 v[60:63], v[150:153], v[188:191], v[60:63]
	v_mfma_f32_16x16x32_bf16 v[52:55], v[158:161], v[188:191], v[52:55]
	v_mfma_f32_16x16x32_bf16 v[44:47], v[150:153], v[192:195], v[44:47]
	v_mfma_f32_16x16x32_bf16 v[36:39], v[158:161], v[192:195], v[36:39]
	v_mfma_f32_16x16x32_bf16 v[26:29], v[150:153], v[204:207], v[26:29]
	v_mfma_f32_16x16x32_bf16 v[18:21], v[158:161], v[204:207], v[18:21]
	v_mfma_f32_16x16x32_bf16 v[10:13], v[150:153], v[208:211], v[10:13]
	v_mfma_f32_16x16x32_bf16 v[6:9], v[158:161], v[208:211], v[6:9]
	v_mfma_f32_16x16x32_bf16 v[60:63], v[154:157], v[196:199], v[60:63]
	v_mfma_f32_16x16x32_bf16 v[52:55], v[162:165], v[196:199], v[52:55]
	v_mfma_f32_16x16x32_bf16 v[44:47], v[154:157], v[200:203], v[44:47]
	v_mfma_f32_16x16x32_bf16 v[36:39], v[162:165], v[200:203], v[36:39]
	v_mfma_f32_16x16x32_bf16 v[26:29], v[154:157], v[224:227], v[26:29]
	v_mfma_f32_16x16x32_bf16 v[18:21], v[162:165], v[224:227], v[18:21]
	v_mfma_f32_16x16x32_bf16 v[10:13], v[154:157], v[228:231], v[10:13]
	v_mfma_f32_16x16x32_bf16 v[6:9], v[162:165], v[228:231], v[6:9]
	s_setprio 0
	s_setprio 1
	v_mfma_f32_16x16x32_bf16 v[64:67], v[166:169], v[188:191], v[64:67]
	v_mfma_f32_16x16x32_bf16 v[56:59], v[174:177], v[188:191], v[56:59]
	v_mfma_f32_16x16x32_bf16 v[48:51], v[166:169], v[192:195], v[48:51]
	v_mfma_f32_16x16x32_bf16 v[40:43], v[174:177], v[192:195], v[40:43]
	v_mfma_f32_16x16x32_bf16 v[30:33], v[166:169], v[204:207], v[30:33]
	v_mfma_f32_16x16x32_bf16 v[22:25], v[174:177], v[204:207], v[22:25]
	v_mfma_f32_16x16x32_bf16 v[14:17], v[166:169], v[208:211], v[14:17]
	v_mfma_f32_16x16x32_bf16 v[2:5], v[174:177], v[208:211], v[2:5]
	v_mfma_f32_16x16x32_bf16 v[64:67], v[170:173], v[196:199], v[64:67]
	v_mfma_f32_16x16x32_bf16 v[56:59], v[184:187], v[196:199], v[56:59]
	v_mfma_f32_16x16x32_bf16 v[48:51], v[170:173], v[200:203], v[48:51]
	v_mfma_f32_16x16x32_bf16 v[40:43], v[184:187], v[200:203], v[40:43]
	v_mfma_f32_16x16x32_bf16 v[30:33], v[170:173], v[224:227], v[30:33]
	v_mfma_f32_16x16x32_bf16 v[22:25], v[184:187], v[224:227], v[22:25]
	v_mfma_f32_16x16x32_bf16 v[14:17], v[170:173], v[228:231], v[14:17]
	v_mfma_f32_16x16x32_bf16 v[2:5], v[184:187], v[228:231], v[2:5]
	s_setprio 0
	s_barrier
	s_add_i32 s30, s30, 2
	s_add_u32 s8, s8, 0x100
	s_addc_u32 s9, s9, 0
	s_add_u32 s24, s24, 0x100
	s_addc_u32 s25, s25, 0
	s_cmp_gt_u32 s30, 29
	s_cbranch_scc1 .Lpeel_done_P6
.LBB0_1114:
	s_add_u32 s28, s8, 0xfff80080
	s_addc_u32 s29, s9, -1
	s_add_i32 s31, 0, 0x10000
	s_cmp_eq_u32 s30, 28
	s_cselect_b32 s43, s13, s29
	s_cselect_b32 s42, s19, s28
	ds_read_b128 v[150:153], v1
	ds_read_b128 v[154:157], v146
	s_cselect_b32 s29, s20, s25
	s_cselect_b32 s28, s21, s24
	s_add_i32 s56, 0, 0x14000
	ds_read_b128 v[158:161], v1 offset:2048
	ds_read_b128 v[162:165], v146 offset:2048
	ds_read_b128 v[166:169], v1 offset:16384
	ds_read_b128 v[170:173], v146 offset:16384
	ds_read_b128 v[174:177], v1 offset:18432
	ds_read_b128 v[184:187], v146 offset:18432
	s_add_i32 m0, s34, 0xc000
	ds_read_b128 v[188:191], v147
	ds_read_b128 v[192:195], v147 offset:2048
	ds_read_b128 v[196:199], v148
	ds_read_b128 v[200:203], v148 offset:2048
	ds_read_b128 v[204:207], v147 offset:4096
	ds_read_b128 v[208:211], v147 offset:6144
	ds_read_b128 v[224:227], v148 offset:4096
	ds_read_b128 v[228:231], v148 offset:6144
	global_load_lds_dwordx4 v144, s[8:9]
	s_add_i32 m0, s34, 0xe000
	s_nop 0
	global_load_lds_dwordx4 v142, s[8:9]
	s_waitcnt vmcnt(8) lgkmcnt(0)
	s_barrier
	s_setprio 1
	v_mfma_f32_16x16x32_bf16 v[132:135], v[150:153], v[188:191], v[132:135]
	v_mfma_f32_16x16x32_bf16 v[124:127], v[158:161], v[188:191], v[124:127]
	v_mfma_f32_16x16x32_bf16 v[108:111], v[150:153], v[192:195], v[108:111]
	v_mfma_f32_16x16x32_bf16 v[100:103], v[158:161], v[192:195], v[100:103]
	v_mfma_f32_16x16x32_bf16 v[92:95], v[150:153], v[204:207], v[92:95]
	v_mfma_f32_16x16x32_bf16 v[84:87], v[158:161], v[204:207], v[84:87]
	v_mfma_f32_16x16x32_bf16 v[76:79], v[150:153], v[208:211], v[76:79]
	v_mfma_f32_16x16x32_bf16 v[68:71], v[158:161], v[208:211], v[68:71]
	v_mfma_f32_16x16x32_bf16 v[132:135], v[154:157], v[196:199], v[132:135]
	v_mfma_f32_16x16x32_bf16 v[124:127], v[162:165], v[196:199], v[124:127]
	v_mfma_f32_16x16x32_bf16 v[108:111], v[154:157], v[200:203], v[108:111]
	v_mfma_f32_16x16x32_bf16 v[100:103], v[162:165], v[200:203], v[100:103]
	v_mfma_f32_16x16x32_bf16 v[92:95], v[154:157], v[224:227], v[92:95]
	v_mfma_f32_16x16x32_bf16 v[84:87], v[162:165], v[224:227], v[84:87]
	v_mfma_f32_16x16x32_bf16 v[76:79], v[154:157], v[228:231], v[76:79]
	v_mfma_f32_16x16x32_bf16 v[68:71], v[162:165], v[228:231], v[68:71]
	s_setprio 0
	s_setprio 1
	v_mfma_f32_16x16x32_bf16 v[136:139], v[166:169], v[188:191], v[136:139]
	v_mfma_f32_16x16x32_bf16 v[128:131], v[174:177], v[188:191], v[128:131]
	v_mfma_f32_16x16x32_bf16 v[112:115], v[166:169], v[192:195], v[112:115]
	v_mfma_f32_16x16x32_bf16 v[104:107], v[174:177], v[192:195], v[104:107]
	v_mfma_f32_16x16x32_bf16 v[96:99], v[166:169], v[204:207], v[96:99]
	v_mfma_f32_16x16x32_bf16 v[88:91], v[174:177], v[204:207], v[88:91]
	v_mfma_f32_16x16x32_bf16 v[80:83], v[166:169], v[208:211], v[80:83]
	v_mfma_f32_16x16x32_bf16 v[72:75], v[174:177], v[208:211], v[72:75]
	v_mfma_f32_16x16x32_bf16 v[136:139], v[170:173], v[196:199], v[136:139]
	v_mfma_f32_16x16x32_bf16 v[128:131], v[184:187], v[196:199], v[128:131]
	v_mfma_f32_16x16x32_bf16 v[112:115], v[170:173], v[200:203], v[112:115]
	v_mfma_f32_16x16x32_bf16 v[104:107], v[184:187], v[200:203], v[104:107]
	v_mfma_f32_16x16x32_bf16 v[96:99], v[170:173], v[224:227], v[96:99]
	v_mfma_f32_16x16x32_bf16 v[88:91], v[184:187], v[224:227], v[88:91]
	v_mfma_f32_16x16x32_bf16 v[80:83], v[170:173], v[228:231], v[80:83]
	v_mfma_f32_16x16x32_bf16 v[72:75], v[184:187], v[228:231], v[72:75]
	s_setprio 0
	s_barrier
	s_add_i32 s31, s31, s33
	s_mov_b32 m0, s31
	ds_read_b128 v[188:191], v147 offset:16384
	ds_read_b128 v[192:195], v147 offset:18432
	ds_read_b128 v[196:199], v148 offset:16384
	ds_read_b128 v[200:203], v148 offset:18432
	ds_read_b128 v[204:207], v147 offset:20480
	ds_read_b128 v[208:211], v147 offset:22528
	ds_read_b128 v[224:227], v148 offset:20480
	ds_read_b128 v[228:231], v148 offset:22528
	global_load_lds_dwordx4 v34, s[28:29]
	s_add_i32 m0, s31, 0x2000
	s_add_u32 s54, s28, 0x80000
	s_addc_u32 s55, s29, 0
	s_add_i32 s31, s56, s33
	global_load_lds_dwordx4 v140, s[28:29]
	s_mov_b32 m0, s31
	s_nop 0
	global_load_lds_dwordx4 v34, s[54:55]
	s_add_i32 m0, s31, 0x2000
	s_nop 0
	global_load_lds_dwordx4 v140, s[54:55]
	s_mov_b32 m0, s34
	s_nop 0
	global_load_lds_dwordx4 v144, s[42:43]
	s_mov_b32 m0, s35
	s_nop 0
	global_load_lds_dwordx4 v142, s[42:43]
	s_waitcnt vmcnt(8) lgkmcnt(0)
	s_barrier
	s_setprio 1
	v_mfma_f32_16x16x32_bf16 v[60:63], v[150:153], v[188:191], v[60:63]
	v_mfma_f32_16x16x32_bf16 v[52:55], v[158:161], v[188:191], v[52:55]
	v_mfma_f32_16x16x32_bf16 v[44:47], v[150:153], v[192:195], v[44:47]
	v_mfma_f32_16x16x32_bf16 v[36:39], v[158:161], v[192:195], v[36:39]
	v_mfma_f32_16x16x32_bf16 v[26:29], v[150:153], v[204:207], v[26:29]
	v_mfma_f32_16x16x32_bf16 v[18:21], v[158:161], v[204:207], v[18:21]
	v_mfma_f32_16x16x32_bf16 v[10:13], v[150:153], v[208:211], v[10:13]
	v_mfma_f32_16x16x32_bf16 v[6:9], v[158:161], v[208:211], v[6:9]
	v_mfma_f32_16x16x32_bf16 v[60:63], v[154:157], v[196:199], v[60:63]
	v_mfma_f32_16x16x32_bf16 v[52:55], v[162:165], v[196:199], v[52:55]
	v_mfma_f32_16x16x32_bf16 v[44:47], v[154:157], v[200:203], v[44:47]
	v_mfma_f32_16x16x32_bf16 v[36:39], v[162:165], v[200:203], v[36:39]
	v_mfma_f32_16x16x32_bf16 v[26:29], v[154:157], v[224:227], v[26:29]
	v_mfma_f32_16x16x32_bf16 v[18:21], v[162:165], v[224:227], v[18:21]
	v_mfma_f32_16x16x32_bf16 v[10:13], v[154:157], v[228:231], v[10:13]
	v_mfma_f32_16x16x32_bf16 v[6:9], v[162:165], v[228:231], v[6:9]
	s_setprio 0
	s_setprio 1
	v_mfma_f32_16x16x32_bf16 v[64:67], v[166:169], v[188:191], v[64:67]
	v_mfma_f32_16x16x32_bf16 v[56:59], v[174:177], v[188:191], v[56:59]
	v_mfma_f32_16x16x32_bf16 v[48:51], v[166:169], v[192:195], v[48:51]
	v_mfma_f32_16x16x32_bf16 v[40:43], v[174:177], v[192:195], v[40:43]
	v_mfma_f32_16x16x32_bf16 v[30:33], v[166:169], v[204:207], v[30:33]
	v_mfma_f32_16x16x32_bf16 v[22:25], v[174:177], v[204:207], v[22:25]
	v_mfma_f32_16x16x32_bf16 v[14:17], v[166:169], v[208:211], v[14:17]
	v_mfma_f32_16x16x32_bf16 v[2:5], v[174:177], v[208:211], v[2:5]
	v_mfma_f32_16x16x32_bf16 v[64:67], v[170:173], v[196:199], v[64:67]
	v_mfma_f32_16x16x32_bf16 v[56:59], v[184:187], v[196:199], v[56:59]
	v_mfma_f32_16x16x32_bf16 v[48:51], v[170:173], v[200:203], v[48:51]
	v_mfma_f32_16x16x32_bf16 v[40:43], v[184:187], v[200:203], v[40:43]
	v_mfma_f32_16x16x32_bf16 v[30:33], v[170:173], v[224:227], v[30:33]
	v_mfma_f32_16x16x32_bf16 v[22:25], v[184:187], v[224:227], v[22:25]
	v_mfma_f32_16x16x32_bf16 v[14:17], v[170:173], v[228:231], v[14:17]
	v_mfma_f32_16x16x32_bf16 v[2:5], v[184:187], v[228:231], v[2:5]
	s_setprio 0
	s_barrier
	s_add_i32 s31, 0, 0x18000
	ds_read_b128 v[150:153], v1 offset:32768
	ds_read_b128 v[154:157], v146 offset:32768
	s_add_i32 s54, 0, 0x1c000
	ds_read_b128 v[158:161], v1 offset:34816
	ds_read_b128 v[162:165], v146 offset:34816
	ds_read_b128 v[166:169], v1 offset:49152
	ds_read_b128 v[170:173], v146 offset:49152
	ds_read_b128 v[174:177], v1 offset:51200
	ds_read_b128 v[184:187], v146 offset:51200
	s_mov_b64 s[100:101], s[42:43]
	s_add_u32 s42, s42, 0x80000
	s_addc_u32 s43, s43, 0
	s_mov_b32 m0, s44
	ds_read_b128 v[188:191], v147 offset:32768
	ds_read_b128 v[192:195], v147 offset:34816
	ds_read_b128 v[196:199], v148 offset:32768
	ds_read_b128 v[200:203], v148 offset:34816
	ds_read_b128 v[204:207], v147 offset:36864
	ds_read_b128 v[208:211], v147 offset:38912
	ds_read_b128 v[224:227], v148 offset:36864
	ds_read_b128 v[228:231], v148 offset:38912
	global_load_lds_dwordx4 v144, s[42:43]
	s_mov_b32 m0, s45
	s_nop 0
	global_load_lds_dwordx4 v142, s[42:43]
	s_waitcnt vmcnt(8) lgkmcnt(0)
	s_barrier
	s_setprio 1
	v_mfma_f32_16x16x32_bf16 v[132:135], v[150:153], v[188:191], v[132:135]
	v_mfma_f32_16x16x32_bf16 v[124:127], v[158:161], v[188:191], v[124:127]
	v_mfma_f32_16x16x32_bf16 v[108:111], v[150:153], v[192:195], v[108:111]
	v_mfma_f32_16x16x32_bf16 v[100:103], v[158:161], v[192:195], v[100:103]
	v_mfma_f32_16x16x32_bf16 v[92:95], v[150:153], v[204:207], v[92:95]
	v_mfma_f32_16x16x32_bf16 v[84:87], v[158:161], v[204:207], v[84:87]
	v_mfma_f32_16x16x32_bf16 v[76:79], v[150:153], v[208:211], v[76:79]
	v_mfma_f32_16x16x32_bf16 v[68:71], v[158:161], v[208:211], v[68:71]
	v_mfma_f32_16x16x32_bf16 v[132:135], v[154:157], v[196:199], v[132:135]
	v_mfma_f32_16x16x32_bf16 v[124:127], v[162:165], v[196:199], v[124:127]
	v_mfma_f32_16x16x32_bf16 v[108:111], v[154:157], v[200:203], v[108:111]
	v_mfma_f32_16x16x32_bf16 v[100:103], v[162:165], v[200:203], v[100:103]
	v_mfma_f32_16x16x32_bf16 v[92:95], v[154:157], v[224:227], v[92:95]
	v_mfma_f32_16x16x32_bf16 v[84:87], v[162:165], v[224:227], v[84:87]
	v_mfma_f32_16x16x32_bf16 v[76:79], v[154:157], v[228:231], v[76:79]
	v_mfma_f32_16x16x32_bf16 v[68:71], v[162:165], v[228:231], v[68:71]
	s_setprio 0
	s_setprio 1
	v_mfma_f32_16x16x32_bf16 v[136:139], v[166:169], v[188:191], v[136:139]
	v_mfma_f32_16x16x32_bf16 v[128:131], v[174:177], v[188:191], v[128:131]
	v_mfma_f32_16x16x32_bf16 v[112:115], v[166:169], v[192:195], v[112:115]
	v_mfma_f32_16x16x32_bf16 v[104:107], v[174:177], v[192:195], v[104:107]
	v_mfma_f32_16x16x32_bf16 v[96:99], v[166:169], v[204:207], v[96:99]
	v_mfma_f32_16x16x32_bf16 v[88:91], v[174:177], v[204:207], v[88:91]
	v_mfma_f32_16x16x32_bf16 v[80:83], v[166:169], v[208:211], v[80:83]
	v_mfma_f32_16x16x32_bf16 v[72:75], v[174:177], v[208:211], v[72:75]
	v_mfma_f32_16x16x32_bf16 v[136:139], v[170:173], v[196:199], v[136:139]
	v_mfma_f32_16x16x32_bf16 v[128:131], v[184:187], v[196:199], v[128:131]
	v_mfma_f32_16x16x32_bf16 v[112:115], v[170:173], v[200:203], v[112:115]
	v_mfma_f32_16x16x32_bf16 v[104:107], v[184:187], v[200:203], v[104:107]
	v_mfma_f32_16x16x32_bf16 v[96:99], v[170:173], v[224:227], v[96:99]
	v_mfma_f32_16x16x32_bf16 v[88:91], v[184:187], v[224:227], v[88:91]
	v_mfma_f32_16x16x32_bf16 v[80:83], v[170:173], v[228:231], v[80:83]
	v_mfma_f32_16x16x32_bf16 v[72:75], v[184:187], v[228:231], v[72:75]
	s_setprio 0
	s_barrier
	s_add_i32 s31, s31, s33
	s_add_i32 m0, s31, 0xffffff80
	ds_read_b128 v[188:191], v147 offset:49152
	ds_read_b128 v[192:195], v147 offset:51200
	ds_read_b128 v[196:199], v148 offset:49152
	ds_read_b128 v[200:203], v148 offset:51200
	ds_read_b128 v[204:207], v147 offset:53248
	ds_read_b128 v[208:211], v147 offset:55296
	ds_read_b128 v[224:227], v148 offset:53248
	ds_read_b128 v[228:231], v148 offset:55296
	global_load_lds_dwordx4 v34, s[28:29] offset:128
	s_add_i32 m0, s31, 0x1f80
	s_mov_b64 s[98:99], s[28:29]
	s_add_u32 s28, s28, 0x80080
	s_addc_u32 s29, s29, 0
	s_add_i32 s31, s54, s33
	global_load_lds_dwordx4 v140, s[98:99] offset:128
	s_mov_b32 m0, s31
	s_nop 0
	global_load_lds_dwordx4 v34, s[28:29]
	s_add_i32 m0, s31, 0x2000
	s_nop 0
	global_load_lds_dwordx4 v140, s[28:29]
	s_add_i32 m0, s48, 0xffffff80
	s_nop 0
	global_load_lds_dwordx4 v144, s[100:101] offset:128
	s_add_i32 m0, s49, 0xffffff80
	s_nop 0
	global_load_lds_dwordx4 v142, s[100:101] offset:128
	s_waitcnt vmcnt(8) lgkmcnt(0)
	s_barrier
	s_setprio 1
	v_mfma_f32_16x16x32_bf16 v[60:63], v[150:153], v[188:191], v[60:63]
	v_mfma_f32_16x16x32_bf16 v[52:55], v[158:161], v[188:191], v[52:55]
	v_mfma_f32_16x16x32_bf16 v[44:47], v[150:153], v[192:195], v[44:47]
	v_mfma_f32_16x16x32_bf16 v[36:39], v[158:161], v[192:195], v[36:39]
	v_mfma_f32_16x16x32_bf16 v[26:29], v[150:153], v[204:207], v[26:29]
	v_mfma_f32_16x16x32_bf16 v[18:21], v[158:161], v[204:207], v[18:21]
	v_mfma_f32_16x16x32_bf16 v[10:13], v[150:153], v[208:211], v[10:13]
	v_mfma_f32_16x16x32_bf16 v[6:9], v[158:161], v[208:211], v[6:9]
	v_mfma_f32_16x16x32_bf16 v[60:63], v[154:157], v[196:199], v[60:63]
	v_mfma_f32_16x16x32_bf16 v[52:55], v[162:165], v[196:199], v[52:55]
	v_mfma_f32_16x16x32_bf16 v[44:47], v[154:157], v[200:203], v[44:47]
	v_mfma_f32_16x16x32_bf16 v[36:39], v[162:165], v[200:203], v[36:39]
	v_mfma_f32_16x16x32_bf16 v[26:29], v[154:157], v[224:227], v[26:29]
	v_mfma_f32_16x16x32_bf16 v[18:21], v[162:165], v[224:227], v[18:21]
	v_mfma_f32_16x16x32_bf16 v[10:13], v[154:157], v[228:231], v[10:13]
	v_mfma_f32_16x16x32_bf16 v[6:9], v[162:165], v[228:231], v[6:9]
	s_setprio 0
	s_setprio 1
	v_mfma_f32_16x16x32_bf16 v[64:67], v[166:169], v[188:191], v[64:67]
	v_mfma_f32_16x16x32_bf16 v[56:59], v[174:177], v[188:191], v[56:59]
	v_mfma_f32_16x16x32_bf16 v[48:51], v[166:169], v[192:195], v[48:51]
	v_mfma_f32_16x16x32_bf16 v[40:43], v[174:177], v[192:195], v[40:43]
	v_mfma_f32_16x16x32_bf16 v[30:33], v[166:169], v[204:207], v[30:33]
	v_mfma_f32_16x16x32_bf16 v[22:25], v[174:177], v[204:207], v[22:25]
	v_mfma_f32_16x16x32_bf16 v[14:17], v[166:169], v[208:211], v[14:17]
	v_mfma_f32_16x16x32_bf16 v[2:5], v[174:177], v[208:211], v[2:5]
	v_mfma_f32_16x16x32_bf16 v[64:67], v[170:173], v[196:199], v[64:67]
	v_mfma_f32_16x16x32_bf16 v[56:59], v[184:187], v[196:199], v[56:59]
	v_mfma_f32_16x16x32_bf16 v[48:51], v[170:173], v[200:203], v[48:51]
	v_mfma_f32_16x16x32_bf16 v[40:43], v[184:187], v[200:203], v[40:43]
	v_mfma_f32_16x16x32_bf16 v[30:33], v[170:173], v[224:227], v[30:33]
	v_mfma_f32_16x16x32_bf16 v[22:25], v[184:187], v[224:227], v[22:25]
	v_mfma_f32_16x16x32_bf16 v[14:17], v[170:173], v[228:231], v[14:17]
	v_mfma_f32_16x16x32_bf16 v[2:5], v[184:187], v[228:231], v[2:5]
	s_setprio 0
	s_barrier
	s_add_i32 s30, s30, 2
	s_add_u32 s8, s8, 0x100
	s_addc_u32 s9, s9, 0
	s_add_u32 s24, s24, 0x100
	s_addc_u32 s25, s25, 0
	s_cmp_gt_u32 s30, 29
	s_cbranch_scc0 .LBB0_1114

.LBB0_1194:
	s_add_u32 s8, s8, 0x160080
	s_addc_u32 s9, s9, 0
	s_add_u32 s20, s18, 0x100
	s_addc_u32 s21, s19, 0
	s_mov_b32 s24, -2
	v_readlane_b32 s35, v255, 20
	v_readlane_b32 s40, v255, 21
	v_readlane_b32 s41, v255, 22
	v_readlane_b32 s57, v255, 23
	s_mov_b64 s[58:59], 0x80
	s_add_u32 s18, s8, 0xffea0080
	s_addc_u32 s19, s9, -1
	s_add_i32 s25, 0, 0x10000
	s_cmpk_eq_i32 s24, 0x54
	s_cselect_b32 s23, s45, s19
	s_cselect_b32 s22, s44, s18
	s_cselect_b32 s19, s47, s21
	s_cselect_b32 s18, s46, s20
	s_add_i32 s34, 0, 0x14000
	ds_read_b128 v[138:141], v1
	ds_read_b128 v[142:145], v160
	ds_read_b128 v[146:149], v1 offset:2048
	ds_read_b128 v[150:153], v160 offset:2048
	ds_read_b128 v[154:157], v1 offset:16384
	ds_read_b128 v[164:167], v160 offset:16384
	ds_read_b128 v[168:171], v1 offset:18432
	ds_read_b128 v[172:175], v160 offset:18432
	s_add_i32 m0, s29, 0xc000
	ds_read_b128 v[176:179], v161
	ds_read_b128 v[184:187], v161 offset:2048
	ds_read_b128 v[188:191], v162
	ds_read_b128 v[192:195], v162 offset:2048
	ds_read_b128 v[196:199], v161 offset:4096
	ds_read_b128 v[200:203], v161 offset:6144
	ds_read_b128 v[204:207], v162 offset:4096
	ds_read_b128 v[208:211], v162 offset:6144
	global_load_lds_dwordx4 v136, s[8:9]
	s_add_i32 m0, s29, 0xe000
	s_nop 0
	global_load_lds_dwordx4 v134, s[8:9]
	s_waitcnt vmcnt(8) lgkmcnt(0)
	s_barrier
	s_setprio 1
	v_mfma_f32_16x16x32_bf16 v[128:131], v[138:141], v[176:179], 0
	v_mfma_f32_16x16x32_bf16 v[124:127], v[146:149], v[176:179], 0
	v_mfma_f32_16x16x32_bf16 v[112:115], v[138:141], v[184:187], 0
	v_mfma_f32_16x16x32_bf16 v[108:111], v[146:149], v[184:187], 0
	v_mfma_f32_16x16x32_bf16 v[96:99], v[138:141], v[196:199], 0
	v_mfma_f32_16x16x32_bf16 v[92:95], v[146:149], v[196:199], 0
	v_mfma_f32_16x16x32_bf16 v[80:83], v[138:141], v[200:203], 0
	v_mfma_f32_16x16x32_bf16 v[76:79], v[146:149], v[200:203], 0
	v_mfma_f32_16x16x32_bf16 v[128:131], v[142:145], v[188:191], v[128:131]
	v_mfma_f32_16x16x32_bf16 v[124:127], v[150:153], v[188:191], v[124:127]
	v_mfma_f32_16x16x32_bf16 v[112:115], v[142:145], v[192:195], v[112:115]
	v_mfma_f32_16x16x32_bf16 v[108:111], v[150:153], v[192:195], v[108:111]
	v_mfma_f32_16x16x32_bf16 v[96:99], v[142:145], v[204:207], v[96:99]
	v_mfma_f32_16x16x32_bf16 v[92:95], v[150:153], v[204:207], v[92:95]
	v_mfma_f32_16x16x32_bf16 v[80:83], v[142:145], v[208:211], v[80:83]
	v_mfma_f32_16x16x32_bf16 v[76:79], v[150:153], v[208:211], v[76:79]
	s_setprio 0
	s_setprio 1
	v_mfma_f32_16x16x32_bf16 v[120:123], v[154:157], v[176:179], 0
	v_mfma_f32_16x16x32_bf16 v[116:119], v[168:171], v[176:179], 0
	v_mfma_f32_16x16x32_bf16 v[104:107], v[154:157], v[184:187], 0
	v_mfma_f32_16x16x32_bf16 v[100:103], v[168:171], v[184:187], 0
	v_mfma_f32_16x16x32_bf16 v[88:91], v[154:157], v[196:199], 0
	v_mfma_f32_16x16x32_bf16 v[84:87], v[168:171], v[196:199], 0
	v_mfma_f32_16x16x32_bf16 v[72:75], v[154:157], v[200:203], 0
	v_mfma_f32_16x16x32_bf16 v[68:71], v[168:171], v[200:203], 0
	v_mfma_f32_16x16x32_bf16 v[120:123], v[164:167], v[188:191], v[120:123]
	v_mfma_f32_16x16x32_bf16 v[116:119], v[172:175], v[188:191], v[116:119]
	v_mfma_f32_16x16x32_bf16 v[104:107], v[164:167], v[192:195], v[104:107]
	v_mfma_f32_16x16x32_bf16 v[100:103], v[172:175], v[192:195], v[100:103]
	v_mfma_f32_16x16x32_bf16 v[88:91], v[164:167], v[204:207], v[88:91]
	v_mfma_f32_16x16x32_bf16 v[84:87], v[172:175], v[204:207], v[84:87]
	v_mfma_f32_16x16x32_bf16 v[72:75], v[164:167], v[208:211], v[72:75]
	v_mfma_f32_16x16x32_bf16 v[68:71], v[172:175], v[208:211], v[68:71]
	s_setprio 0
	s_barrier
	s_add_i32 s25, s25, s28
	s_mov_b32 m0, s25
	ds_read_b128 v[176:179], v161 offset:16384
	ds_read_b128 v[184:187], v161 offset:18432
	ds_read_b128 v[188:191], v162 offset:16384
	ds_read_b128 v[192:195], v162 offset:18432
	ds_read_b128 v[196:199], v161 offset:20480
	ds_read_b128 v[200:203], v161 offset:22528
	ds_read_b128 v[204:207], v162 offset:20480
	ds_read_b128 v[208:211], v162 offset:22528
	global_load_lds_dwordx4 v34, s[18:19]
	s_add_i32 m0, s25, 0x2000
	s_add_u32 s30, s18, 0x160000
	s_addc_u32 s31, s19, 0
	s_add_i32 s25, s34, s28
	global_load_lds_dwordx4 v132, s[18:19]
	s_mov_b32 m0, s25
	s_nop 0
	global_load_lds_dwordx4 v34, s[30:31]
	s_add_i32 m0, s25, 0x2000
	s_nop 0
	global_load_lds_dwordx4 v132, s[30:31]
	s_mov_b32 m0, s29
	s_nop 0
	global_load_lds_dwordx4 v136, s[22:23]
	s_mov_b32 m0, s33
	s_nop 0
	global_load_lds_dwordx4 v134, s[22:23]
	s_waitcnt vmcnt(8) lgkmcnt(0)
	s_barrier
	s_setprio 1
	v_mfma_f32_16x16x32_bf16 v[64:67], v[138:141], v[176:179], 0
	v_mfma_f32_16x16x32_bf16 v[60:63], v[146:149], v[176:179], 0
	v_mfma_f32_16x16x32_bf16 v[48:51], v[138:141], v[184:187], 0
	v_mfma_f32_16x16x32_bf16 v[44:47], v[146:149], v[184:187], 0
	v_mfma_f32_16x16x32_bf16 v[30:33], v[138:141], v[196:199], 0
	v_mfma_f32_16x16x32_bf16 v[26:29], v[146:149], v[196:199], 0
	v_mfma_f32_16x16x32_bf16 v[14:17], v[138:141], v[200:203], 0
	v_mfma_f32_16x16x32_bf16 v[10:13], v[146:149], v[200:203], 0
	v_mfma_f32_16x16x32_bf16 v[64:67], v[142:145], v[188:191], v[64:67]
	v_mfma_f32_16x16x32_bf16 v[60:63], v[150:153], v[188:191], v[60:63]
	v_mfma_f32_16x16x32_bf16 v[48:51], v[142:145], v[192:195], v[48:51]
	v_mfma_f32_16x16x32_bf16 v[44:47], v[150:153], v[192:195], v[44:47]
	v_mfma_f32_16x16x32_bf16 v[30:33], v[142:145], v[204:207], v[30:33]
	v_mfma_f32_16x16x32_bf16 v[26:29], v[150:153], v[204:207], v[26:29]
	v_mfma_f32_16x16x32_bf16 v[14:17], v[142:145], v[208:211], v[14:17]
	v_mfma_f32_16x16x32_bf16 v[10:13], v[150:153], v[208:211], v[10:13]
	s_setprio 0
	s_setprio 1
	v_mfma_f32_16x16x32_bf16 v[56:59], v[154:157], v[176:179], 0
	v_mfma_f32_16x16x32_bf16 v[52:55], v[168:171], v[176:179], 0
	v_mfma_f32_16x16x32_bf16 v[40:43], v[154:157], v[184:187], 0
	v_mfma_f32_16x16x32_bf16 v[36:39], v[168:171], v[184:187], 0
	v_mfma_f32_16x16x32_bf16 v[22:25], v[154:157], v[196:199], 0
	v_mfma_f32_16x16x32_bf16 v[18:21], v[168:171], v[196:199], 0
	v_mfma_f32_16x16x32_bf16 v[6:9], v[154:157], v[200:203], 0
	v_mfma_f32_16x16x32_bf16 v[2:5], v[168:171], v[200:203], 0
	v_mfma_f32_16x16x32_bf16 v[56:59], v[164:167], v[188:191], v[56:59]
	v_mfma_f32_16x16x32_bf16 v[52:55], v[172:175], v[188:191], v[52:55]
	v_mfma_f32_16x16x32_bf16 v[40:43], v[164:167], v[192:195], v[40:43]
	v_mfma_f32_16x16x32_bf16 v[36:39], v[172:175], v[192:195], v[36:39]
	v_mfma_f32_16x16x32_bf16 v[22:25], v[164:167], v[204:207], v[22:25]
	v_mfma_f32_16x16x32_bf16 v[18:21], v[172:175], v[204:207], v[18:21]
	v_mfma_f32_16x16x32_bf16 v[6:9], v[164:167], v[208:211], v[6:9]
	v_mfma_f32_16x16x32_bf16 v[2:5], v[172:175], v[208:211], v[2:5]
	s_setprio 0
	s_barrier
	s_add_i32 s25, 0, 0x18000
	s_add_i32 s30, 0, 0x1c000
	ds_read_b128 v[138:141], v1 offset:32768
	ds_read_b128 v[142:145], v160 offset:32768
	ds_read_b128 v[146:149], v1 offset:34816
	ds_read_b128 v[150:153], v160 offset:34816
	ds_read_b128 v[154:157], v1 offset:49152
	ds_read_b128 v[164:167], v160 offset:49152
	ds_read_b128 v[168:171], v1 offset:51200
	ds_read_b128 v[172:175], v160 offset:51200
	s_mov_b64 s[100:101], s[22:23]
	s_add_u32 s22, s22, 0x160000
	s_addc_u32 s23, s23, 0
	s_mov_b32 m0, s48
	ds_read_b128 v[176:179], v161 offset:32768
	ds_read_b128 v[184:187], v161 offset:34816
	ds_read_b128 v[188:191], v162 offset:32768
	ds_read_b128 v[192:195], v162 offset:34816
	ds_read_b128 v[196:199], v161 offset:36864
	ds_read_b128 v[200:203], v161 offset:38912
	ds_read_b128 v[204:207], v162 offset:36864
	ds_read_b128 v[208:211], v162 offset:38912
	global_load_lds_dwordx4 v136, s[22:23]
	s_mov_b32 m0, s49
	s_nop 0
	global_load_lds_dwordx4 v134, s[22:23]
	s_waitcnt vmcnt(8) lgkmcnt(0)
	s_barrier
	s_setprio 1
	v_mfma_f32_16x16x32_bf16 v[128:131], v[138:141], v[176:179], v[128:131]
	v_mfma_f32_16x16x32_bf16 v[124:127], v[146:149], v[176:179], v[124:127]
	v_mfma_f32_16x16x32_bf16 v[112:115], v[138:141], v[184:187], v[112:115]
	v_mfma_f32_16x16x32_bf16 v[108:111], v[146:149], v[184:187], v[108:111]
	v_mfma_f32_16x16x32_bf16 v[96:99], v[138:141], v[196:199], v[96:99]
	v_mfma_f32_16x16x32_bf16 v[92:95], v[146:149], v[196:199], v[92:95]
	v_mfma_f32_16x16x32_bf16 v[80:83], v[138:141], v[200:203], v[80:83]
	v_mfma_f32_16x16x32_bf16 v[76:79], v[146:149], v[200:203], v[76:79]
	v_mfma_f32_16x16x32_bf16 v[128:131], v[142:145], v[188:191], v[128:131]
	v_mfma_f32_16x16x32_bf16 v[124:127], v[150:153], v[188:191], v[124:127]
	v_mfma_f32_16x16x32_bf16 v[112:115], v[142:145], v[192:195], v[112:115]
	v_mfma_f32_16x16x32_bf16 v[108:111], v[150:153], v[192:195], v[108:111]
	v_mfma_f32_16x16x32_bf16 v[96:99], v[142:145], v[204:207], v[96:99]
	v_mfma_f32_16x16x32_bf16 v[92:95], v[150:153], v[204:207], v[92:95]
	v_mfma_f32_16x16x32_bf16 v[80:83], v[142:145], v[208:211], v[80:83]
	v_mfma_f32_16x16x32_bf16 v[76:79], v[150:153], v[208:211], v[76:79]
	s_setprio 0
	s_setprio 1
	v_mfma_f32_16x16x32_bf16 v[120:123], v[154:157], v[176:179], v[120:123]
	v_mfma_f32_16x16x32_bf16 v[116:119], v[168:171], v[176:179], v[116:119]
	v_mfma_f32_16x16x32_bf16 v[104:107], v[154:157], v[184:187], v[104:107]
	v_mfma_f32_16x16x32_bf16 v[100:103], v[168:171], v[184:187], v[100:103]
	v_mfma_f32_16x16x32_bf16 v[88:91], v[154:157], v[196:199], v[88:91]
	v_mfma_f32_16x16x32_bf16 v[84:87], v[168:171], v[196:199], v[84:87]
	v_mfma_f32_16x16x32_bf16 v[72:75], v[154:157], v[200:203], v[72:75]
	v_mfma_f32_16x16x32_bf16 v[68:71], v[168:171], v[200:203], v[68:71]
	v_mfma_f32_16x16x32_bf16 v[120:123], v[164:167], v[188:191], v[120:123]
	v_mfma_f32_16x16x32_bf16 v[116:119], v[172:175], v[188:191], v[116:119]
	v_mfma_f32_16x16x32_bf16 v[104:107], v[164:167], v[192:195], v[104:107]
	v_mfma_f32_16x16x32_bf16 v[100:103], v[172:175], v[192:195], v[100:103]
	v_mfma_f32_16x16x32_bf16 v[88:91], v[164:167], v[204:207], v[88:91]
	v_mfma_f32_16x16x32_bf16 v[84:87], v[172:175], v[204:207], v[84:87]
	v_mfma_f32_16x16x32_bf16 v[72:75], v[164:167], v[208:211], v[72:75]
	v_mfma_f32_16x16x32_bf16 v[68:71], v[172:175], v[208:211], v[68:71]
	s_setprio 0
	s_barrier
	s_add_i32 s22, s25, s28
	s_add_i32 m0, s22, 0xffffff80
	ds_read_b128 v[176:179], v161 offset:49152
	ds_read_b128 v[184:187], v161 offset:51200
	ds_read_b128 v[188:191], v162 offset:49152
	ds_read_b128 v[192:195], v162 offset:51200
	ds_read_b128 v[196:199], v161 offset:53248
	ds_read_b128 v[200:203], v161 offset:55296
	ds_read_b128 v[204:207], v162 offset:53248
	ds_read_b128 v[208:211], v162 offset:55296
	global_load_lds_dwordx4 v34, s[18:19] offset:128
	s_add_i32 m0, s22, 0x1f80
	s_mov_b64 s[98:99], s[18:19]
	s_add_u32 s18, s18, 0x160080
	s_addc_u32 s19, s19, 0
	s_add_i32 s22, s30, s28
	global_load_lds_dwordx4 v132, s[98:99] offset:128
	s_mov_b32 m0, s22
	s_nop 0
	global_load_lds_dwordx4 v34, s[18:19]
	s_add_i32 m0, s22, 0x2000
	s_nop 0
	global_load_lds_dwordx4 v132, s[18:19]
	s_add_i32 m0, s53, 0xffffff80
	s_nop 0
	global_load_lds_dwordx4 v136, s[100:101] offset:128
	s_add_i32 m0, s54, 0xffffff80
	s_nop 0
	global_load_lds_dwordx4 v134, s[100:101] offset:128
	s_waitcnt vmcnt(8) lgkmcnt(0)
	s_barrier
	s_setprio 1
	v_mfma_f32_16x16x32_bf16 v[64:67], v[138:141], v[176:179], v[64:67]
	v_mfma_f32_16x16x32_bf16 v[60:63], v[146:149], v[176:179], v[60:63]
	v_mfma_f32_16x16x32_bf16 v[48:51], v[138:141], v[184:187], v[48:51]
	v_mfma_f32_16x16x32_bf16 v[44:47], v[146:149], v[184:187], v[44:47]
	v_mfma_f32_16x16x32_bf16 v[30:33], v[138:141], v[196:199], v[30:33]
	v_mfma_f32_16x16x32_bf16 v[26:29], v[146:149], v[196:199], v[26:29]
	v_mfma_f32_16x16x32_bf16 v[14:17], v[138:141], v[200:203], v[14:17]
	v_mfma_f32_16x16x32_bf16 v[10:13], v[146:149], v[200:203], v[10:13]
	v_mfma_f32_16x16x32_bf16 v[64:67], v[142:145], v[188:191], v[64:67]
	v_mfma_f32_16x16x32_bf16 v[60:63], v[150:153], v[188:191], v[60:63]
	v_mfma_f32_16x16x32_bf16 v[48:51], v[142:145], v[192:195], v[48:51]
	v_mfma_f32_16x16x32_bf16 v[44:47], v[150:153], v[192:195], v[44:47]
	v_mfma_f32_16x16x32_bf16 v[30:33], v[142:145], v[204:207], v[30:33]
	v_mfma_f32_16x16x32_bf16 v[26:29], v[150:153], v[204:207], v[26:29]
	v_mfma_f32_16x16x32_bf16 v[14:17], v[142:145], v[208:211], v[14:17]
	v_mfma_f32_16x16x32_bf16 v[10:13], v[150:153], v[208:211], v[10:13]
	s_setprio 0
	s_setprio 1
	v_mfma_f32_16x16x32_bf16 v[56:59], v[154:157], v[176:179], v[56:59]
	v_mfma_f32_16x16x32_bf16 v[52:55], v[168:171], v[176:179], v[52:55]
	v_mfma_f32_16x16x32_bf16 v[40:43], v[154:157], v[184:187], v[40:43]
	v_mfma_f32_16x16x32_bf16 v[36:39], v[168:171], v[184:187], v[36:39]
	v_mfma_f32_16x16x32_bf16 v[22:25], v[154:157], v[196:199], v[22:25]
	v_mfma_f32_16x16x32_bf16 v[18:21], v[168:171], v[196:199], v[18:21]
	v_mfma_f32_16x16x32_bf16 v[6:9], v[154:157], v[200:203], v[6:9]
	v_mfma_f32_16x16x32_bf16 v[2:5], v[168:171], v[200:203], v[2:5]
	v_mfma_f32_16x16x32_bf16 v[56:59], v[164:167], v[188:191], v[56:59]
	v_mfma_f32_16x16x32_bf16 v[52:55], v[172:175], v[188:191], v[52:55]
	v_mfma_f32_16x16x32_bf16 v[40:43], v[164:167], v[192:195], v[40:43]
	v_mfma_f32_16x16x32_bf16 v[36:39], v[172:175], v[192:195], v[36:39]
	v_mfma_f32_16x16x32_bf16 v[22:25], v[164:167], v[204:207], v[22:25]
	v_mfma_f32_16x16x32_bf16 v[18:21], v[172:175], v[204:207], v[18:21]
	v_mfma_f32_16x16x32_bf16 v[6:9], v[164:167], v[208:211], v[6:9]
	v_mfma_f32_16x16x32_bf16 v[2:5], v[172:175], v[208:211], v[2:5]
	s_setprio 0
	s_barrier
	s_add_i32 s24, s24, 2
	s_add_u32 s8, s8, 0x100
	s_addc_u32 s9, s9, 0
	s_add_u32 s20, s20, 0x100
	s_addc_u32 s21, s21, 0
	s_cmpk_gt_u32 s24, 0x55
	s_cbranch_scc1 .Lpeel_done_P7
.LBB0_1195:
	s_add_u32 s18, s8, 0xffea0080
	s_addc_u32 s19, s9, -1
	s_add_i32 s25, 0, 0x10000
	s_cmpk_eq_i32 s24, 0x54
	s_cselect_b32 s23, s45, s19
	s_cselect_b32 s22, s44, s18
	s_cselect_b32 s19, s47, s21
	s_cselect_b32 s18, s46, s20
	s_add_i32 s34, 0, 0x14000
	ds_read_b128 v[138:141], v1
	ds_read_b128 v[142:145], v160
	ds_read_b128 v[146:149], v1 offset:2048
	ds_read_b128 v[150:153], v160 offset:2048
	ds_read_b128 v[154:157], v1 offset:16384
	ds_read_b128 v[164:167], v160 offset:16384
	ds_read_b128 v[168:171], v1 offset:18432
	ds_read_b128 v[172:175], v160 offset:18432
	s_add_i32 m0, s29, 0xc000
	ds_read_b128 v[176:179], v161
	ds_read_b128 v[184:187], v161 offset:2048
	ds_read_b128 v[188:191], v162
	ds_read_b128 v[192:195], v162 offset:2048
	ds_read_b128 v[196:199], v161 offset:4096
	ds_read_b128 v[200:203], v161 offset:6144
	ds_read_b128 v[204:207], v162 offset:4096
	ds_read_b128 v[208:211], v162 offset:6144
	global_load_lds_dwordx4 v136, s[8:9]
	s_add_i32 m0, s29, 0xe000
	s_nop 0
	global_load_lds_dwordx4 v134, s[8:9]
	s_waitcnt vmcnt(8) lgkmcnt(0)
	s_barrier
	s_setprio 1
	v_mfma_f32_16x16x32_bf16 v[128:131], v[138:141], v[176:179], v[128:131]
	v_mfma_f32_16x16x32_bf16 v[124:127], v[146:149], v[176:179], v[124:127]
	v_mfma_f32_16x16x32_bf16 v[112:115], v[138:141], v[184:187], v[112:115]
	v_mfma_f32_16x16x32_bf16 v[108:111], v[146:149], v[184:187], v[108:111]
	v_mfma_f32_16x16x32_bf16 v[96:99], v[138:141], v[196:199], v[96:99]
	v_mfma_f32_16x16x32_bf16 v[92:95], v[146:149], v[196:199], v[92:95]
	v_mfma_f32_16x16x32_bf16 v[80:83], v[138:141], v[200:203], v[80:83]
	v_mfma_f32_16x16x32_bf16 v[76:79], v[146:149], v[200:203], v[76:79]
	v_mfma_f32_16x16x32_bf16 v[128:131], v[142:145], v[188:191], v[128:131]
	v_mfma_f32_16x16x32_bf16 v[124:127], v[150:153], v[188:191], v[124:127]
	v_mfma_f32_16x16x32_bf16 v[112:115], v[142:145], v[192:195], v[112:115]
	v_mfma_f32_16x16x32_bf16 v[108:111], v[150:153], v[192:195], v[108:111]
	v_mfma_f32_16x16x32_bf16 v[96:99], v[142:145], v[204:207], v[96:99]
	v_mfma_f32_16x16x32_bf16 v[92:95], v[150:153], v[204:207], v[92:95]
	v_mfma_f32_16x16x32_bf16 v[80:83], v[142:145], v[208:211], v[80:83]
	v_mfma_f32_16x16x32_bf16 v[76:79], v[150:153], v[208:211], v[76:79]
	s_setprio 0
	s_setprio 1
	v_mfma_f32_16x16x32_bf16 v[120:123], v[154:157], v[176:179], v[120:123]
	v_mfma_f32_16x16x32_bf16 v[116:119], v[168:171], v[176:179], v[116:119]
	v_mfma_f32_16x16x32_bf16 v[104:107], v[154:157], v[184:187], v[104:107]
	v_mfma_f32_16x16x32_bf16 v[100:103], v[168:171], v[184:187], v[100:103]
	v_mfma_f32_16x16x32_bf16 v[88:91], v[154:157], v[196:199], v[88:91]
	v_mfma_f32_16x16x32_bf16 v[84:87], v[168:171], v[196:199], v[84:87]
	v_mfma_f32_16x16x32_bf16 v[72:75], v[154:157], v[200:203], v[72:75]
	v_mfma_f32_16x16x32_bf16 v[68:71], v[168:171], v[200:203], v[68:71]
	v_mfma_f32_16x16x32_bf16 v[120:123], v[164:167], v[188:191], v[120:123]
	v_mfma_f32_16x16x32_bf16 v[116:119], v[172:175], v[188:191], v[116:119]
	v_mfma_f32_16x16x32_bf16 v[104:107], v[164:167], v[192:195], v[104:107]
	v_mfma_f32_16x16x32_bf16 v[100:103], v[172:175], v[192:195], v[100:103]
	v_mfma_f32_16x16x32_bf16 v[88:91], v[164:167], v[204:207], v[88:91]
	v_mfma_f32_16x16x32_bf16 v[84:87], v[172:175], v[204:207], v[84:87]
	v_mfma_f32_16x16x32_bf16 v[72:75], v[164:167], v[208:211], v[72:75]
	v_mfma_f32_16x16x32_bf16 v[68:71], v[172:175], v[208:211], v[68:71]
	s_setprio 0
	s_barrier
	s_add_i32 s25, s25, s28
	s_mov_b32 m0, s25
	ds_read_b128 v[176:179], v161 offset:16384
	ds_read_b128 v[184:187], v161 offset:18432
	ds_read_b128 v[188:191], v162 offset:16384
	ds_read_b128 v[192:195], v162 offset:18432
	ds_read_b128 v[196:199], v161 offset:20480
	ds_read_b128 v[200:203], v161 offset:22528
	ds_read_b128 v[204:207], v162 offset:20480
	ds_read_b128 v[208:211], v162 offset:22528
	global_load_lds_dwordx4 v34, s[18:19]
	s_add_i32 m0, s25, 0x2000
	s_add_u32 s30, s18, 0x160000
	s_addc_u32 s31, s19, 0
	s_add_i32 s25, s34, s28
	global_load_lds_dwordx4 v132, s[18:19]
	s_mov_b32 m0, s25
	s_nop 0
	global_load_lds_dwordx4 v34, s[30:31]
	s_add_i32 m0, s25, 0x2000
	s_nop 0
	global_load_lds_dwordx4 v132, s[30:31]
	s_mov_b32 m0, s29
	s_nop 0
	global_load_lds_dwordx4 v136, s[22:23]
	s_mov_b32 m0, s33
	s_nop 0
	global_load_lds_dwordx4 v134, s[22:23]
	s_waitcnt vmcnt(8) lgkmcnt(0)
	s_barrier
	s_setprio 1
	v_mfma_f32_16x16x32_bf16 v[64:67], v[138:141], v[176:179], v[64:67]
	v_mfma_f32_16x16x32_bf16 v[60:63], v[146:149], v[176:179], v[60:63]
	v_mfma_f32_16x16x32_bf16 v[48:51], v[138:141], v[184:187], v[48:51]
	v_mfma_f32_16x16x32_bf16 v[44:47], v[146:149], v[184:187], v[44:47]
	v_mfma_f32_16x16x32_bf16 v[30:33], v[138:141], v[196:199], v[30:33]
	v_mfma_f32_16x16x32_bf16 v[26:29], v[146:149], v[196:199], v[26:29]
	v_mfma_f32_16x16x32_bf16 v[14:17], v[138:141], v[200:203], v[14:17]
	v_mfma_f32_16x16x32_bf16 v[10:13], v[146:149], v[200:203], v[10:13]
	v_mfma_f32_16x16x32_bf16 v[64:67], v[142:145], v[188:191], v[64:67]
	v_mfma_f32_16x16x32_bf16 v[60:63], v[150:153], v[188:191], v[60:63]
	v_mfma_f32_16x16x32_bf16 v[48:51], v[142:145], v[192:195], v[48:51]
	v_mfma_f32_16x16x32_bf16 v[44:47], v[150:153], v[192:195], v[44:47]
	v_mfma_f32_16x16x32_bf16 v[30:33], v[142:145], v[204:207], v[30:33]
	v_mfma_f32_16x16x32_bf16 v[26:29], v[150:153], v[204:207], v[26:29]
	v_mfma_f32_16x16x32_bf16 v[14:17], v[142:145], v[208:211], v[14:17]
	v_mfma_f32_16x16x32_bf16 v[10:13], v[150:153], v[208:211], v[10:13]
	s_setprio 0
	s_setprio 1
	v_mfma_f32_16x16x32_bf16 v[56:59], v[154:157], v[176:179], v[56:59]
	v_mfma_f32_16x16x32_bf16 v[52:55], v[168:171], v[176:179], v[52:55]
	v_mfma_f32_16x16x32_bf16 v[40:43], v[154:157], v[184:187], v[40:43]
	v_mfma_f32_16x16x32_bf16 v[36:39], v[168:171], v[184:187], v[36:39]
	v_mfma_f32_16x16x32_bf16 v[22:25], v[154:157], v[196:199], v[22:25]
	v_mfma_f32_16x16x32_bf16 v[18:21], v[168:171], v[196:199], v[18:21]
	v_mfma_f32_16x16x32_bf16 v[6:9], v[154:157], v[200:203], v[6:9]
	v_mfma_f32_16x16x32_bf16 v[2:5], v[168:171], v[200:203], v[2:5]
	v_mfma_f32_16x16x32_bf16 v[56:59], v[164:167], v[188:191], v[56:59]
	v_mfma_f32_16x16x32_bf16 v[52:55], v[172:175], v[188:191], v[52:55]
	v_mfma_f32_16x16x32_bf16 v[40:43], v[164:167], v[192:195], v[40:43]
	v_mfma_f32_16x16x32_bf16 v[36:39], v[172:175], v[192:195], v[36:39]
	v_mfma_f32_16x16x32_bf16 v[22:25], v[164:167], v[204:207], v[22:25]
	v_mfma_f32_16x16x32_bf16 v[18:21], v[172:175], v[204:207], v[18:21]
	v_mfma_f32_16x16x32_bf16 v[6:9], v[164:167], v[208:211], v[6:9]
	v_mfma_f32_16x16x32_bf16 v[2:5], v[172:175], v[208:211], v[2:5]
	s_setprio 0
	s_barrier
	s_add_i32 s25, 0, 0x18000
	s_add_i32 s30, 0, 0x1c000
	ds_read_b128 v[138:141], v1 offset:32768
	ds_read_b128 v[142:145], v160 offset:32768
	ds_read_b128 v[146:149], v1 offset:34816
	ds_read_b128 v[150:153], v160 offset:34816
	ds_read_b128 v[154:157], v1 offset:49152
	ds_read_b128 v[164:167], v160 offset:49152
	ds_read_b128 v[168:171], v1 offset:51200
	ds_read_b128 v[172:175], v160 offset:51200
	s_mov_b64 s[100:101], s[22:23]
	s_add_u32 s22, s22, 0x160000
	s_addc_u32 s23, s23, 0
	s_mov_b32 m0, s48
	ds_read_b128 v[176:179], v161 offset:32768
	ds_read_b128 v[184:187], v161 offset:34816
	ds_read_b128 v[188:191], v162 offset:32768
	ds_read_b128 v[192:195], v162 offset:34816
	ds_read_b128 v[196:199], v161 offset:36864
	ds_read_b128 v[200:203], v161 offset:38912
	ds_read_b128 v[204:207], v162 offset:36864
	ds_read_b128 v[208:211], v162 offset:38912
	global_load_lds_dwordx4 v136, s[22:23]
	s_mov_b32 m0, s49
	s_nop 0
	global_load_lds_dwordx4 v134, s[22:23]
	s_waitcnt vmcnt(8) lgkmcnt(0)
	s_barrier
	s_setprio 1
	v_mfma_f32_16x16x32_bf16 v[128:131], v[138:141], v[176:179], v[128:131]
	v_mfma_f32_16x16x32_bf16 v[124:127], v[146:149], v[176:179], v[124:127]
	v_mfma_f32_16x16x32_bf16 v[112:115], v[138:141], v[184:187], v[112:115]
	v_mfma_f32_16x16x32_bf16 v[108:111], v[146:149], v[184:187], v[108:111]
	v_mfma_f32_16x16x32_bf16 v[96:99], v[138:141], v[196:199], v[96:99]
	v_mfma_f32_16x16x32_bf16 v[92:95], v[146:149], v[196:199], v[92:95]
	v_mfma_f32_16x16x32_bf16 v[80:83], v[138:141], v[200:203], v[80:83]
	v_mfma_f32_16x16x32_bf16 v[76:79], v[146:149], v[200:203], v[76:79]
	v_mfma_f32_16x16x32_bf16 v[128:131], v[142:145], v[188:191], v[128:131]
	v_mfma_f32_16x16x32_bf16 v[124:127], v[150:153], v[188:191], v[124:127]
	v_mfma_f32_16x16x32_bf16 v[112:115], v[142:145], v[192:195], v[112:115]
	v_mfma_f32_16x16x32_bf16 v[108:111], v[150:153], v[192:195], v[108:111]
	v_mfma_f32_16x16x32_bf16 v[96:99], v[142:145], v[204:207], v[96:99]
	v_mfma_f32_16x16x32_bf16 v[92:95], v[150:153], v[204:207], v[92:95]
	v_mfma_f32_16x16x32_bf16 v[80:83], v[142:145], v[208:211], v[80:83]
	v_mfma_f32_16x16x32_bf16 v[76:79], v[150:153], v[208:211], v[76:79]
	s_setprio 0
	s_setprio 1
	v_mfma_f32_16x16x32_bf16 v[120:123], v[154:157], v[176:179], v[120:123]
	v_mfma_f32_16x16x32_bf16 v[116:119], v[168:171], v[176:179], v[116:119]
	v_mfma_f32_16x16x32_bf16 v[104:107], v[154:157], v[184:187], v[104:107]
	v_mfma_f32_16x16x32_bf16 v[100:103], v[168:171], v[184:187], v[100:103]
	v_mfma_f32_16x16x32_bf16 v[88:91], v[154:157], v[196:199], v[88:91]
	v_mfma_f32_16x16x32_bf16 v[84:87], v[168:171], v[196:199], v[84:87]
	v_mfma_f32_16x16x32_bf16 v[72:75], v[154:157], v[200:203], v[72:75]
	v_mfma_f32_16x16x32_bf16 v[68:71], v[168:171], v[200:203], v[68:71]
	v_mfma_f32_16x16x32_bf16 v[120:123], v[164:167], v[188:191], v[120:123]
	v_mfma_f32_16x16x32_bf16 v[116:119], v[172:175], v[188:191], v[116:119]
	v_mfma_f32_16x16x32_bf16 v[104:107], v[164:167], v[192:195], v[104:107]
	v_mfma_f32_16x16x32_bf16 v[100:103], v[172:175], v[192:195], v[100:103]
	v_mfma_f32_16x16x32_bf16 v[88:91], v[164:167], v[204:207], v[88:91]
	v_mfma_f32_16x16x32_bf16 v[84:87], v[172:175], v[204:207], v[84:87]
	v_mfma_f32_16x16x32_bf16 v[72:75], v[164:167], v[208:211], v[72:75]
	v_mfma_f32_16x16x32_bf16 v[68:71], v[172:175], v[208:211], v[68:71]
	s_setprio 0
	s_barrier
	s_add_i32 s22, s25, s28
	s_add_i32 m0, s22, 0xffffff80
	ds_read_b128 v[176:179], v161 offset:49152
	ds_read_b128 v[184:187], v161 offset:51200
	ds_read_b128 v[188:191], v162 offset:49152
	ds_read_b128 v[192:195], v162 offset:51200
	ds_read_b128 v[196:199], v161 offset:53248
	ds_read_b128 v[200:203], v161 offset:55296
	ds_read_b128 v[204:207], v162 offset:53248
	ds_read_b128 v[208:211], v162 offset:55296
	global_load_lds_dwordx4 v34, s[18:19] offset:128
	s_add_i32 m0, s22, 0x1f80
	s_mov_b64 s[98:99], s[18:19]
	s_add_u32 s18, s18, 0x160080
	s_addc_u32 s19, s19, 0
	s_add_i32 s22, s30, s28
	global_load_lds_dwordx4 v132, s[98:99] offset:128
	s_mov_b32 m0, s22
	s_nop 0
	global_load_lds_dwordx4 v34, s[18:19]
	s_add_i32 m0, s22, 0x2000
	s_nop 0
	global_load_lds_dwordx4 v132, s[18:19]
	s_add_i32 m0, s53, 0xffffff80
	s_nop 0
	global_load_lds_dwordx4 v136, s[100:101] offset:128
	s_add_i32 m0, s54, 0xffffff80
	s_nop 0
	global_load_lds_dwordx4 v134, s[100:101] offset:128
	s_waitcnt vmcnt(8) lgkmcnt(0)
	s_barrier
	s_setprio 1
	v_mfma_f32_16x16x32_bf16 v[64:67], v[138:141], v[176:179], v[64:67]
	v_mfma_f32_16x16x32_bf16 v[60:63], v[146:149], v[176:179], v[60:63]
	v_mfma_f32_16x16x32_bf16 v[48:51], v[138:141], v[184:187], v[48:51]
	v_mfma_f32_16x16x32_bf16 v[44:47], v[146:149], v[184:187], v[44:47]
	v_mfma_f32_16x16x32_bf16 v[30:33], v[138:141], v[196:199], v[30:33]
	v_mfma_f32_16x16x32_bf16 v[26:29], v[146:149], v[196:199], v[26:29]
	v_mfma_f32_16x16x32_bf16 v[14:17], v[138:141], v[200:203], v[14:17]
	v_mfma_f32_16x16x32_bf16 v[10:13], v[146:149], v[200:203], v[10:13]
	v_mfma_f32_16x16x32_bf16 v[64:67], v[142:145], v[188:191], v[64:67]
	v_mfma_f32_16x16x32_bf16 v[60:63], v[150:153], v[188:191], v[60:63]
	v_mfma_f32_16x16x32_bf16 v[48:51], v[142:145], v[192:195], v[48:51]
	v_mfma_f32_16x16x32_bf16 v[44:47], v[150:153], v[192:195], v[44:47]
	v_mfma_f32_16x16x32_bf16 v[30:33], v[142:145], v[204:207], v[30:33]
	v_mfma_f32_16x16x32_bf16 v[26:29], v[150:153], v[204:207], v[26:29]
	v_mfma_f32_16x16x32_bf16 v[14:17], v[142:145], v[208:211], v[14:17]
	v_mfma_f32_16x16x32_bf16 v[10:13], v[150:153], v[208:211], v[10:13]
	s_setprio 0
	s_setprio 1
	v_mfma_f32_16x16x32_bf16 v[56:59], v[154:157], v[176:179], v[56:59]
	v_mfma_f32_16x16x32_bf16 v[52:55], v[168:171], v[176:179], v[52:55]
	v_mfma_f32_16x16x32_bf16 v[40:43], v[154:157], v[184:187], v[40:43]
	v_mfma_f32_16x16x32_bf16 v[36:39], v[168:171], v[184:187], v[36:39]
	v_mfma_f32_16x16x32_bf16 v[22:25], v[154:157], v[196:199], v[22:25]
	v_mfma_f32_16x16x32_bf16 v[18:21], v[168:171], v[196:199], v[18:21]
	v_mfma_f32_16x16x32_bf16 v[6:9], v[154:157], v[200:203], v[6:9]
	v_mfma_f32_16x16x32_bf16 v[2:5], v[168:171], v[200:203], v[2:5]
	v_mfma_f32_16x16x32_bf16 v[56:59], v[164:167], v[188:191], v[56:59]
	v_mfma_f32_16x16x32_bf16 v[52:55], v[172:175], v[188:191], v[52:55]
	v_mfma_f32_16x16x32_bf16 v[40:43], v[164:167], v[192:195], v[40:43]
	v_mfma_f32_16x16x32_bf16 v[36:39], v[172:175], v[192:195], v[36:39]
	v_mfma_f32_16x16x32_bf16 v[22:25], v[164:167], v[204:207], v[22:25]
	v_mfma_f32_16x16x32_bf16 v[18:21], v[172:175], v[204:207], v[18:21]
	v_mfma_f32_16x16x32_bf16 v[6:9], v[164:167], v[208:211], v[6:9]
	v_mfma_f32_16x16x32_bf16 v[2:5], v[172:175], v[208:211], v[2:5]
	s_setprio 0
	s_barrier
	s_add_i32 s24, s24, 2
	s_add_u32 s8, s8, 0x100
	s_addc_u32 s9, s9, 0
	s_add_u32 s20, s20, 0x100
	s_addc_u32 s21, s21, 0
	s_cmpk_gt_u32 s24, 0x55
	s_cbranch_scc0 .LBB0_1195
